# removed the already-satisfied s_waitcnt lgkmcnt(0) that follows the barrier at each MMA segment head (36 sites in the GEMM K-loops)
# baseline (speedup 1.0000x reference)
; #define PG8_STAGE(bufoff, gbase, voff) do { _Pragma("unroll") for (int _i = 0; _i < 2; ++_i) \
;         __builtin_amdgcn_global_load_lds((const unsigned*)((const char*)(gbase) + (voff)[_i]), (PG8_LAS unsigned*)(lds + (bufoff) + ldsw + _i * 8192), 16, 0, 0); } while (0)
; #define PG8_LDA(dst, b, h) do { _Pragma("unroll") for (int m = 0; m < 4; ++m) _Pragma("unroll") for (int k = 0; k < 2; ++k) dst[m][k] = *(const PG8_LAS bf16x8*)(lds + PG8_SA(b, h) + aoff + m * 2048 + k * 1024); } while (0)
; #define PG8_LDB(dst, b, h) do { _Pragma("unroll") for (int n = 0; n < 2; ++n) _Pragma("unroll") for (int k = 0; k < 2; ++k) dst[n][k] = *(const PG8_LAS bf16x8*)(lds + PG8_SB(b, h) + boff + n * 2048 + k * 1024); } while (0)
; #define PG8_MMA(ai, bj, At, Bt) do { __builtin_amdgcn_s_setprio(1); _Pragma("unroll") for (int m = 0; m < 4; ++m) _Pragma("unroll") for (int n = 0; n < 2; ++n) _Pragma("unroll") for (int k = 0; k < 2; ++k) \
;         acc[ai][bj][m][n] = __builtin_amdgcn_mfma_f32_16x16x32_bf16(Bt[n][k], At[m][k], acc[ai][bj][m][n], 0, 0, 0); __builtin_amdgcn_s_setprio(0); } while (0)
; #define PG8_WAIT_V(n) asm volatile("s_waitcnt vmcnt(" #n ")" ::: "memory")
; #define PG8_WAIT_L(n) asm volatile("s_waitcnt lgkmcnt(" #n ")" ::: "memory")
; #define PG8_BAR __builtin_amdgcn_s_barrier()
; #define PG8_SCHED __builtin_amdgcn_sched_barrier(0)
; template <class Epi, class Sched, bool ALIGN_EPI = false, bool SP2 = false>
; __device__ __forceinline__ void gemm_phase(PG8_LAS unsigned char* lds, const Gemm g, const Sched& S, const Epi& E) {
;     ...
;         for (int t = 0; t < nt; t += 2) {
;             const bool last = (t == nt - 2);
;             const char* a1 = cA + (size_t)(t + 1) * kstep;
;             const char* a2 = last ? nA : cA + (size_t)(t + 2) * kstep; const char* b2 = last ? nB : cB + (size_t)(t + 2) * kstep;
;             const char* a3 = a2 + kstep; const char* b3 = b2 + kstep;
;             if (last && has_next) S.a_ready(nxt);
;             if constexpr (SP2) {
;             PG8_LDB(B0, 0, 0); PG8_LDB(B1, 0, 1); PG8_SCHED; PG8_LDA(At, 0, 0); PG8_STAGE(PG8_SA(1, 1), a1 + hstep, voffA);
;             PG8_WAIT_V(8); PG8_WAIT_L(0); PG8_BAR; PG8_MMA(0, 0, At, B0); PG8_MMA(0, 1, At, B1); PG8_BAR; PG8_SCHED;
;             PG8_LDA(At, 0, 1); PG8_STAGE(PG8_SB(0, 0), b2, voffB); PG8_STAGE(PG8_SB(0, 1), b2 + hstep, voffB); PG8_STAGE(PG8_SA(0, 0), a2, voffA);
.LBB0_95:
	ds_read_b128 v[144:147], v155
	ds_read_b128 v[148:151], v155 offset:1024
	ds_read_b128 v[158:161], v155 offset:2048
	ds_read_b128 v[162:165], v155 offset:3072
	ds_read_b128 v[166:169], v156
	ds_read_b128 v[170:173], v156 offset:1024
	ds_read_b128 v[174:177], v156 offset:2048
	ds_read_b128 v[178:181], v156 offset:3072
	s_add_u32 s0, s80, 0xfff80080
	s_addc_u32 s1, s81, -1
	s_cmp_eq_u32 s56, 28
	s_cselect_b32 s83, s23, s1
	s_cselect_b32 s82, s52, s0
	s_cselect_b32 s1, s21, s55
	s_cselect_b32 s0, s53, s54
	v_lshl_add_u64 v[214:215], s[80:81], 0, v[136:137]
	s_add_i32 m0, s36, 0xc000
	ds_read_b128 v[182:185], v157
	ds_read_b128 v[186:189], v157 offset:1024
	ds_read_b128 v[190:193], v157 offset:2048
	ds_read_b128 v[194:197], v157 offset:3072
	ds_read_b128 v[198:201], v157 offset:4096
	ds_read_b128 v[202:205], v157 offset:5120
	ds_read_b128 v[206:209], v157 offset:6144
	ds_read_b128 v[210:213], v157 offset:7168
	global_load_lds_dwordx4 v[214:215], off
	v_lshl_add_u64 v[214:215], s[80:81], 0, v[138:139]
	s_add_i32 m0, s36, 0xe000
	s_nop 0
	global_load_lds_dwordx4 v[214:215], off
	s_waitcnt vmcnt(8)
	s_waitcnt lgkmcnt(0)
	s_barrier
	s_setprio 1
	v_mfma_f32_16x16x32_bf16 v[124:127], v[144:147], v[182:185], v[124:127]
	v_mfma_f32_16x16x32_bf16 v[120:123], v[158:161], v[182:185], v[120:123]
	v_mfma_f32_16x16x32_bf16 v[108:111], v[144:147], v[190:193], v[108:111]
	v_mfma_f32_16x16x32_bf16 v[104:107], v[158:161], v[190:193], v[104:107]
	v_mfma_f32_16x16x32_bf16 v[92:95], v[144:147], v[198:201], v[92:95]
	v_mfma_f32_16x16x32_bf16 v[88:91], v[158:161], v[198:201], v[88:91]
	v_mfma_f32_16x16x32_bf16 v[76:79], v[144:147], v[206:209], v[76:79]
	v_mfma_f32_16x16x32_bf16 v[72:75], v[158:161], v[206:209], v[72:75]
	v_mfma_f32_16x16x32_bf16 v[124:127], v[148:151], v[186:189], v[124:127]
	v_mfma_f32_16x16x32_bf16 v[120:123], v[162:165], v[186:189], v[120:123]
	v_mfma_f32_16x16x32_bf16 v[108:111], v[148:151], v[194:197], v[108:111]
	v_mfma_f32_16x16x32_bf16 v[104:107], v[162:165], v[194:197], v[104:107]
	v_mfma_f32_16x16x32_bf16 v[92:95], v[148:151], v[202:205], v[92:95]
	v_mfma_f32_16x16x32_bf16 v[88:91], v[162:165], v[202:205], v[88:91]
	v_mfma_f32_16x16x32_bf16 v[76:79], v[148:151], v[210:213], v[76:79]
	v_mfma_f32_16x16x32_bf16 v[72:75], v[162:165], v[210:213], v[72:75]
	s_setprio 0
	s_setprio 1
	v_mfma_f32_16x16x32_bf16 v[116:119], v[166:169], v[182:185], v[116:119]
	v_mfma_f32_16x16x32_bf16 v[112:115], v[174:177], v[182:185], v[112:115]
	v_mfma_f32_16x16x32_bf16 v[100:103], v[166:169], v[190:193], v[100:103]
	v_mfma_f32_16x16x32_bf16 v[96:99], v[174:177], v[190:193], v[96:99]
	v_mfma_f32_16x16x32_bf16 v[84:87], v[166:169], v[198:201], v[84:87]
	v_mfma_f32_16x16x32_bf16 v[80:83], v[174:177], v[198:201], v[80:83]
	v_mfma_f32_16x16x32_bf16 v[68:71], v[166:169], v[206:209], v[68:71]
	v_mfma_f32_16x16x32_bf16 v[64:67], v[174:177], v[206:209], v[64:67]
	v_mfma_f32_16x16x32_bf16 v[116:119], v[170:173], v[186:189], v[116:119]
	v_mfma_f32_16x16x32_bf16 v[112:115], v[178:181], v[186:189], v[112:115]
	v_mfma_f32_16x16x32_bf16 v[100:103], v[170:173], v[194:197], v[100:103]
	v_mfma_f32_16x16x32_bf16 v[96:99], v[178:181], v[194:197], v[96:99]
	v_mfma_f32_16x16x32_bf16 v[84:87], v[170:173], v[202:205], v[84:87]
	v_mfma_f32_16x16x32_bf16 v[80:83], v[178:181], v[202:205], v[80:83]
	v_mfma_f32_16x16x32_bf16 v[68:71], v[170:173], v[210:213], v[68:71]
	v_mfma_f32_16x16x32_bf16 v[64:67], v[178:181], v[210:213], v[64:67]
	s_setprio 0
	s_barrier
	s_add_i32 s57, s45, s3
	v_lshl_add_u64 v[214:215], s[0:1], 0, v[132:133]
	s_mov_b32 m0, s57
	ds_read_b128 v[182:185], v157 offset:16384
	ds_read_b128 v[186:189], v157 offset:17408
	ds_read_b128 v[190:193], v157 offset:18432
	ds_read_b128 v[194:197], v157 offset:19456
	ds_read_b128 v[198:201], v157 offset:20480
	ds_read_b128 v[202:205], v157 offset:21504
	ds_read_b128 v[206:209], v157 offset:22528
	ds_read_b128 v[210:213], v157 offset:23552
	global_load_lds_dwordx4 v[214:215], off
	s_add_i32 m0, s57, 0x2000
	s_add_u32 s58, s0, 0x80000
	v_lshl_add_u64 v[216:217], s[0:1], 0, v[128:129]
	s_addc_u32 s59, s1, 0
	s_add_i32 s57, s46, s3
	global_load_lds_dwordx4 v[216:217], off
	v_lshl_add_u64 v[218:219], s[58:59], 0, v[132:133]
	s_mov_b32 m0, s57
	v_lshl_add_u64 v[220:221], s[82:83], 0, v[130:131]
	global_load_lds_dwordx4 v[218:219], off
	v_lshl_add_u64 v[218:219], s[58:59], 0, v[128:129]
	s_add_i32 m0, s57, 0x2000
	s_nop 0
	global_load_lds_dwordx4 v[218:219], off
	v_lshl_add_u64 v[218:219], s[82:83], 0, v[134:135]
	s_mov_b32 m0, s36
	s_nop 0
	global_load_lds_dwordx4 v[218:219], off
	s_mov_b32 m0, s37
	s_nop 0
	global_load_lds_dwordx4 v[220:221], off
	s_waitcnt vmcnt(8)
	s_waitcnt lgkmcnt(0)
	s_barrier
; #define PG8_STAGE(bufoff, gbase, voff) do { _Pragma("unroll") for (int _i = 0; _i < 2; ++_i) \
;         __builtin_amdgcn_global_load_lds((const unsigned*)((const char*)(gbase) + (voff)[_i]), (PG8_LAS unsigned*)(lds + (bufoff) + ldsw + _i * 8192), 16, 0, 0); } while (0)
; #define PG8_LDA(dst, b, h) do { _Pragma("unroll") for (int m = 0; m < 4; ++m) _Pragma("unroll") for (int k = 0; k < 2; ++k) dst[m][k] = *(const PG8_LAS bf16x8*)(lds + PG8_SA(b, h) + aoff + m * 2048 + k * 1024); } while (0)
; #define PG8_LDB(dst, b, h) do { _Pragma("unroll") for (int n = 0; n < 2; ++n) _Pragma("unroll") for (int k = 0; k < 2; ++k) dst[n][k] = *(const PG8_LAS bf16x8*)(lds + PG8_SB(b, h) + boff + n * 2048 + k * 1024); } while (0)
; #define PG8_MMA(ai, bj, At, Bt) do { __builtin_amdgcn_s_setprio(1); _Pragma("unroll") for (int m = 0; m < 4; ++m) _Pragma("unroll") for (int n = 0; n < 2; ++n) _Pragma("unroll") for (int k = 0; k < 2; ++k) \
;         acc[ai][bj][m][n] = __builtin_amdgcn_mfma_f32_16x16x32_bf16(Bt[n][k], At[m][k], acc[ai][bj][m][n], 0, 0, 0); __builtin_amdgcn_s_setprio(0); } while (0)
; #define PG8_WAIT_V(n) asm volatile("s_waitcnt vmcnt(" #n ")" ::: "memory")
; #define PG8_WAIT_L(n) asm volatile("s_waitcnt lgkmcnt(" #n ")" ::: "memory")
; #define PG8_BAR __builtin_amdgcn_s_barrier()
; #define PG8_SCHED __builtin_amdgcn_sched_barrier(0)
; template <class Epi, class Sched, bool ALIGN_EPI = false, bool SP2 = false>
; __device__ __forceinline__ void gemm_phase(PG8_LAS unsigned char* lds, const Gemm g, const Sched& S, const Epi& E) {
;     ...
;             PG8_WAIT_V(8); PG8_WAIT_L(0); PG8_BAR; PG8_MMA(1, 0, At, B0); PG8_MMA(1, 1, At, B1); PG8_BAR; PG8_SCHED;
;             PG8_LDB(B0, 1, 0); PG8_LDB(B1, 1, 1); PG8_SCHED; PG8_LDA(At, 1, 0); PG8_STAGE(PG8_SA(0, 1), a2 + hstep, voffA);
;             PG8_WAIT_V(8); PG8_WAIT_L(0); PG8_BAR; PG8_MMA(0, 0, At, B0); PG8_MMA(0, 1, At, B1); PG8_BAR; PG8_SCHED;
	s_setprio 1
	v_mfma_f32_16x16x32_bf16 v[60:63], v[144:147], v[182:185], v[60:63]
	v_mfma_f32_16x16x32_bf16 v[56:59], v[158:161], v[182:185], v[56:59]
	v_mfma_f32_16x16x32_bf16 v[44:47], v[144:147], v[190:193], v[44:47]
	v_mfma_f32_16x16x32_bf16 v[40:43], v[158:161], v[190:193], v[40:43]
	v_mfma_f32_16x16x32_bf16 v[28:31], v[144:147], v[198:201], v[28:31]
	v_mfma_f32_16x16x32_bf16 v[24:27], v[158:161], v[198:201], v[24:27]
	v_mfma_f32_16x16x32_bf16 v[12:15], v[144:147], v[206:209], v[12:15]
	v_mfma_f32_16x16x32_bf16 v[8:11], v[158:161], v[206:209], v[8:11]
	v_mfma_f32_16x16x32_bf16 v[60:63], v[148:151], v[186:189], v[60:63]
	v_mfma_f32_16x16x32_bf16 v[56:59], v[162:165], v[186:189], v[56:59]
	v_mfma_f32_16x16x32_bf16 v[44:47], v[148:151], v[194:197], v[44:47]
	v_mfma_f32_16x16x32_bf16 v[40:43], v[162:165], v[194:197], v[40:43]
	v_mfma_f32_16x16x32_bf16 v[28:31], v[148:151], v[202:205], v[28:31]
	v_mfma_f32_16x16x32_bf16 v[24:27], v[162:165], v[202:205], v[24:27]
	v_mfma_f32_16x16x32_bf16 v[12:15], v[148:151], v[210:213], v[12:15]
	v_mfma_f32_16x16x32_bf16 v[8:11], v[162:165], v[210:213], v[8:11]
	s_setprio 0
	s_setprio 1
	v_mfma_f32_16x16x32_bf16 v[52:55], v[166:169], v[182:185], v[52:55]
	v_mfma_f32_16x16x32_bf16 v[48:51], v[174:177], v[182:185], v[48:51]
	v_mfma_f32_16x16x32_bf16 v[36:39], v[166:169], v[190:193], v[36:39]
	v_mfma_f32_16x16x32_bf16 v[32:35], v[174:177], v[190:193], v[32:35]
	v_mfma_f32_16x16x32_bf16 v[20:23], v[166:169], v[198:201], v[20:23]
	v_mfma_f32_16x16x32_bf16 v[16:19], v[174:177], v[198:201], v[16:19]
	v_mfma_f32_16x16x32_bf16 v[4:7], v[166:169], v[206:209], v[4:7]
	v_mfma_f32_16x16x32_bf16 v[0:3], v[174:177], v[206:209], v[0:3]
	v_mfma_f32_16x16x32_bf16 v[52:55], v[170:173], v[186:189], v[52:55]
	v_mfma_f32_16x16x32_bf16 v[48:51], v[178:181], v[186:189], v[48:51]
	v_mfma_f32_16x16x32_bf16 v[36:39], v[170:173], v[194:197], v[36:39]
	v_mfma_f32_16x16x32_bf16 v[32:35], v[178:181], v[194:197], v[32:35]
	v_mfma_f32_16x16x32_bf16 v[20:23], v[170:173], v[202:205], v[20:23]
	v_mfma_f32_16x16x32_bf16 v[16:19], v[178:181], v[202:205], v[16:19]
	v_mfma_f32_16x16x32_bf16 v[4:7], v[170:173], v[210:213], v[4:7]
	v_mfma_f32_16x16x32_bf16 v[0:3], v[178:181], v[210:213], v[0:3]
	s_setprio 0
	s_barrier
	s_add_i32 s57, 0, 0x18000
	s_add_i32 s65, 0, 0x1c000
	v_add_u32_e32 v162, s57, v153
	v_add_u32_e32 v178, s65, v153
	ds_read_b128 v[144:147], v162
	ds_read_b128 v[148:151], v162 offset:1024
	ds_read_b128 v[158:161], v162 offset:2048
	ds_read_b128 v[162:165], v162 offset:3072
	ds_read_b128 v[166:169], v178
	ds_read_b128 v[170:173], v178 offset:1024
	ds_read_b128 v[174:177], v178 offset:2048
	ds_read_b128 v[178:181], v178 offset:3072
	s_add_u32 s58, s82, 0x80000
	s_addc_u32 s59, s83, 0
	s_mov_b32 m0, s38
	v_lshl_add_u64 v[228:229], s[58:59], 0, v[134:135]
	ds_read_b128 v[182:185], v157 offset:32768
	ds_read_b128 v[186:189], v157 offset:33792
	ds_read_b128 v[190:193], v157 offset:34816
	ds_read_b128 v[194:197], v157 offset:35840
	ds_read_b128 v[198:201], v157 offset:36864
	ds_read_b128 v[202:205], v157 offset:37888
	ds_read_b128 v[206:209], v157 offset:38912
	ds_read_b128 v[210:213], v157 offset:39936
	global_load_lds_dwordx4 v[228:229], off
	v_lshl_add_u64 v[228:229], s[58:59], 0, v[130:131]
	s_mov_b32 m0, s39
	s_nop 0
	global_load_lds_dwordx4 v[228:229], off
	s_waitcnt vmcnt(8)
	s_waitcnt lgkmcnt(0)
	s_barrier
	s_setprio 1
	v_mfma_f32_16x16x32_bf16 v[124:127], v[144:147], v[182:185], v[124:127]
	v_mfma_f32_16x16x32_bf16 v[120:123], v[158:161], v[182:185], v[120:123]
	v_mfma_f32_16x16x32_bf16 v[108:111], v[144:147], v[190:193], v[108:111]
	v_mfma_f32_16x16x32_bf16 v[104:107], v[158:161], v[190:193], v[104:107]
	v_mfma_f32_16x16x32_bf16 v[92:95], v[144:147], v[198:201], v[92:95]
	v_mfma_f32_16x16x32_bf16 v[88:91], v[158:161], v[198:201], v[88:91]
	v_mfma_f32_16x16x32_bf16 v[76:79], v[144:147], v[206:209], v[76:79]
	v_mfma_f32_16x16x32_bf16 v[72:75], v[158:161], v[206:209], v[72:75]
	v_mfma_f32_16x16x32_bf16 v[124:127], v[148:151], v[186:189], v[124:127]
	v_mfma_f32_16x16x32_bf16 v[120:123], v[162:165], v[186:189], v[120:123]
	v_mfma_f32_16x16x32_bf16 v[108:111], v[148:151], v[194:197], v[108:111]
	v_mfma_f32_16x16x32_bf16 v[104:107], v[162:165], v[194:197], v[104:107]
	v_mfma_f32_16x16x32_bf16 v[92:95], v[148:151], v[202:205], v[92:95]
	v_mfma_f32_16x16x32_bf16 v[88:91], v[162:165], v[202:205], v[88:91]
	v_mfma_f32_16x16x32_bf16 v[76:79], v[148:151], v[210:213], v[76:79]
	v_mfma_f32_16x16x32_bf16 v[72:75], v[162:165], v[210:213], v[72:75]
	s_setprio 0
	s_setprio 1
	v_mfma_f32_16x16x32_bf16 v[116:119], v[166:169], v[182:185], v[116:119]
	v_mfma_f32_16x16x32_bf16 v[112:115], v[174:177], v[182:185], v[112:115]
	v_mfma_f32_16x16x32_bf16 v[100:103], v[166:169], v[190:193], v[100:103]
	v_mfma_f32_16x16x32_bf16 v[96:99], v[174:177], v[190:193], v[96:99]
	v_mfma_f32_16x16x32_bf16 v[84:87], v[166:169], v[198:201], v[84:87]
	v_mfma_f32_16x16x32_bf16 v[80:83], v[174:177], v[198:201], v[80:83]
	v_mfma_f32_16x16x32_bf16 v[68:71], v[166:169], v[206:209], v[68:71]
	v_mfma_f32_16x16x32_bf16 v[64:67], v[174:177], v[206:209], v[64:67]
	v_mfma_f32_16x16x32_bf16 v[116:119], v[170:173], v[186:189], v[116:119]
	v_mfma_f32_16x16x32_bf16 v[112:115], v[178:181], v[186:189], v[112:115]
	v_mfma_f32_16x16x32_bf16 v[100:103], v[170:173], v[194:197], v[100:103]
	v_mfma_f32_16x16x32_bf16 v[96:99], v[178:181], v[194:197], v[96:99]
	v_mfma_f32_16x16x32_bf16 v[84:87], v[170:173], v[202:205], v[84:87]
	v_mfma_f32_16x16x32_bf16 v[80:83], v[178:181], v[202:205], v[80:83]
	v_mfma_f32_16x16x32_bf16 v[68:71], v[170:173], v[210:213], v[68:71]
	v_mfma_f32_16x16x32_bf16 v[64:67], v[178:181], v[210:213], v[64:67]
	s_setprio 0
	s_barrier
; #define PG8_STAGE(bufoff, gbase, voff) do { _Pragma("unroll") for (int _i = 0; _i < 2; ++_i) \
;         __builtin_amdgcn_global_load_lds((const unsigned*)((const char*)(gbase) + (voff)[_i]), (PG8_LAS unsigned*)(lds + (bufoff) + ldsw + _i * 8192), 16, 0, 0); } while (0)
; #define PG8_LDA(dst, b, h) do { _Pragma("unroll") for (int m = 0; m < 4; ++m) _Pragma("unroll") for (int k = 0; k < 2; ++k) dst[m][k] = *(const PG8_LAS bf16x8*)(lds + PG8_SA(b, h) + aoff + m * 2048 + k * 1024); } while (0)
; #define PG8_MMA(ai, bj, At, Bt) do { __builtin_amdgcn_s_setprio(1); _Pragma("unroll") for (int m = 0; m < 4; ++m) _Pragma("unroll") for (int n = 0; n < 2; ++n) _Pragma("unroll") for (int k = 0; k < 2; ++k) \
;         acc[ai][bj][m][n] = __builtin_amdgcn_mfma_f32_16x16x32_bf16(Bt[n][k], At[m][k], acc[ai][bj][m][n], 0, 0, 0); __builtin_amdgcn_s_setprio(0); } while (0)
; #define PG8_WAIT_V(n) asm volatile("s_waitcnt vmcnt(" #n ")" ::: "memory")
; #define PG8_WAIT_L(n) asm volatile("s_waitcnt lgkmcnt(" #n ")" ::: "memory")
; #define PG8_BAR __builtin_amdgcn_s_barrier()
; #define PG8_SCHED __builtin_amdgcn_sched_barrier(0)
; template <class Epi, class Sched, bool ALIGN_EPI = false, bool SP2 = false>
; __device__ __forceinline__ void gemm_phase(PG8_LAS unsigned char* lds, const Gemm g, const Sched& S, const Epi& E) {
;     ...
;             PG8_LDA(At, 1, 1); PG8_STAGE(PG8_SB(1, 0), b3, voffB); PG8_STAGE(PG8_SB(1, 1), b3 + hstep, voffB); PG8_STAGE(PG8_SA(1, 0), a3, voffA);
;             PG8_WAIT_V(8); PG8_WAIT_L(0); PG8_BAR; PG8_MMA(1, 0, At, B0); PG8_MMA(1, 1, At, B1); PG8_BAR; PG8_SCHED;
;     ...
;         if constexpr (ALIGN_EPI) { if (wr == 0) PG8_BAR; }
	s_add_i32 s57, s57, s3
	v_lshl_add_u64 v[214:215], v[214:215], 0, s[12:13]
	s_mov_b32 m0, s57
	ds_read_b128 v[182:185], v157 offset:49152
	ds_read_b128 v[186:189], v157 offset:50176
	ds_read_b128 v[190:193], v157 offset:51200
	ds_read_b128 v[194:197], v157 offset:52224
	ds_read_b128 v[198:201], v157 offset:53248
	ds_read_b128 v[202:205], v157 offset:54272
	ds_read_b128 v[206:209], v157 offset:55296
	ds_read_b128 v[210:213], v157 offset:56320
	global_load_lds_dwordx4 v[214:215], off
	s_add_i32 m0, s57, 0x2000
	s_add_u32 s0, s0, 0x80080
	v_lshl_add_u64 v[214:215], v[216:217], 0, s[12:13]
	s_addc_u32 s1, s1, 0
	s_add_i32 s57, s65, s3
	global_load_lds_dwordx4 v[214:215], off
	v_lshl_add_u64 v[214:215], s[0:1], 0, v[132:133]
	s_mov_b32 m0, s57
	s_nop 0
	global_load_lds_dwordx4 v[214:215], off
	v_lshl_add_u64 v[214:215], s[0:1], 0, v[128:129]
	s_add_i32 m0, s57, 0x2000
	s_nop 0
	global_load_lds_dwordx4 v[214:215], off
	v_lshl_add_u64 v[214:215], v[218:219], 0, s[12:13]
	s_mov_b32 m0, s41
	s_nop 0
	global_load_lds_dwordx4 v[214:215], off
	v_lshl_add_u64 v[214:215], v[220:221], 0, s[12:13]
	s_mov_b32 m0, s42
	s_nop 0
	global_load_lds_dwordx4 v[214:215], off
	s_waitcnt vmcnt(8)
	s_waitcnt lgkmcnt(0)
	s_barrier
	s_setprio 1
	v_mfma_f32_16x16x32_bf16 v[60:63], v[144:147], v[182:185], v[60:63]
	v_mfma_f32_16x16x32_bf16 v[56:59], v[158:161], v[182:185], v[56:59]
	v_mfma_f32_16x16x32_bf16 v[44:47], v[144:147], v[190:193], v[44:47]
	v_mfma_f32_16x16x32_bf16 v[40:43], v[158:161], v[190:193], v[40:43]
	v_mfma_f32_16x16x32_bf16 v[28:31], v[144:147], v[198:201], v[28:31]
	v_mfma_f32_16x16x32_bf16 v[24:27], v[158:161], v[198:201], v[24:27]
	v_mfma_f32_16x16x32_bf16 v[12:15], v[144:147], v[206:209], v[12:15]
	v_mfma_f32_16x16x32_bf16 v[8:11], v[158:161], v[206:209], v[8:11]
	v_mfma_f32_16x16x32_bf16 v[60:63], v[148:151], v[186:189], v[60:63]
	v_mfma_f32_16x16x32_bf16 v[56:59], v[162:165], v[186:189], v[56:59]
	v_mfma_f32_16x16x32_bf16 v[44:47], v[148:151], v[194:197], v[44:47]
	v_mfma_f32_16x16x32_bf16 v[40:43], v[162:165], v[194:197], v[40:43]
	v_mfma_f32_16x16x32_bf16 v[28:31], v[148:151], v[202:205], v[28:31]
	v_mfma_f32_16x16x32_bf16 v[24:27], v[162:165], v[202:205], v[24:27]
	v_mfma_f32_16x16x32_bf16 v[12:15], v[148:151], v[210:213], v[12:15]
	v_mfma_f32_16x16x32_bf16 v[8:11], v[162:165], v[210:213], v[8:11]
	s_setprio 0
	s_setprio 1
	v_mfma_f32_16x16x32_bf16 v[52:55], v[166:169], v[182:185], v[52:55]
	v_mfma_f32_16x16x32_bf16 v[48:51], v[174:177], v[182:185], v[48:51]
	v_mfma_f32_16x16x32_bf16 v[36:39], v[166:169], v[190:193], v[36:39]
	v_mfma_f32_16x16x32_bf16 v[32:35], v[174:177], v[190:193], v[32:35]
	v_mfma_f32_16x16x32_bf16 v[20:23], v[166:169], v[198:201], v[20:23]
	v_mfma_f32_16x16x32_bf16 v[16:19], v[174:177], v[198:201], v[16:19]
	v_mfma_f32_16x16x32_bf16 v[4:7], v[166:169], v[206:209], v[4:7]
	v_mfma_f32_16x16x32_bf16 v[0:3], v[174:177], v[206:209], v[0:3]
	v_mfma_f32_16x16x32_bf16 v[52:55], v[170:173], v[186:189], v[52:55]
	v_mfma_f32_16x16x32_bf16 v[48:51], v[178:181], v[186:189], v[48:51]
	v_mfma_f32_16x16x32_bf16 v[36:39], v[170:173], v[194:197], v[36:39]
	v_mfma_f32_16x16x32_bf16 v[32:35], v[178:181], v[194:197], v[32:35]
	v_mfma_f32_16x16x32_bf16 v[20:23], v[170:173], v[202:205], v[20:23]
	v_mfma_f32_16x16x32_bf16 v[16:19], v[178:181], v[202:205], v[16:19]
	v_mfma_f32_16x16x32_bf16 v[4:7], v[170:173], v[210:213], v[4:7]
	v_mfma_f32_16x16x32_bf16 v[0:3], v[178:181], v[210:213], v[0:3]
	s_setprio 0
	s_barrier
	s_add_i32 s56, s56, 2
	s_add_u32 s80, s80, 0x100
	s_addc_u32 s81, s81, 0
	s_add_u32 s54, s54, 0x100
	s_addc_u32 s55, s55, 0
	s_cmp_gt_u32 s56, 29
	s_cbranch_scc0 .LBB0_95
	s_and_b64 vcc, exec, s[14:15]
	s_cbranch_vccz .LBB0_98
	s_barrier

; #define PG8_STAGE(bufoff, gbase, voff) do { _Pragma("unroll") for (int _i = 0; _i < 2; ++_i) \
;         __builtin_amdgcn_global_load_lds((const unsigned*)((const char*)(gbase) + (voff)[_i]), (PG8_LAS unsigned*)(lds + (bufoff) + ldsw + _i * 8192), 16, 0, 0); } while (0)
; #define PG8_LDA(dst, b, h) do { _Pragma("unroll") for (int m = 0; m < 4; ++m) _Pragma("unroll") for (int k = 0; k < 2; ++k) dst[m][k] = *(const PG8_LAS bf16x8*)(lds + PG8_SA(b, h) + aoff + m * 2048 + k * 1024); } while (0)
; #define PG8_LDB(dst, b, h) do { _Pragma("unroll") for (int n = 0; n < 2; ++n) _Pragma("unroll") for (int k = 0; k < 2; ++k) dst[n][k] = *(const PG8_LAS bf16x8*)(lds + PG8_SB(b, h) + boff + n * 2048 + k * 1024); } while (0)
; #define PG8_MMA(ai, bj, At, Bt) do { __builtin_amdgcn_s_setprio(1); _Pragma("unroll") for (int m = 0; m < 4; ++m) _Pragma("unroll") for (int n = 0; n < 2; ++n) _Pragma("unroll") for (int k = 0; k < 2; ++k) \
;         acc[ai][bj][m][n] = __builtin_amdgcn_mfma_f32_16x16x32_bf16(Bt[n][k], At[m][k], acc[ai][bj][m][n], 0, 0, 0); __builtin_amdgcn_s_setprio(0); } while (0)
; #define PG8_WAIT_V(n) asm volatile("s_waitcnt vmcnt(" #n ")" ::: "memory")
; #define PG8_WAIT_L(n) asm volatile("s_waitcnt lgkmcnt(" #n ")" ::: "memory")
; #define PG8_BAR __builtin_amdgcn_s_barrier()
; #define PG8_SCHED __builtin_amdgcn_sched_barrier(0)
; template <class Epi, class Sched, bool ALIGN_EPI = false, bool SP2 = false>
; __device__ __forceinline__ void gemm_phase(PG8_LAS unsigned char* lds, const Gemm g, const Sched& S, const Epi& E) {
;     ...
;         for (int t = 0; t < nt; t += 2) {
;             const bool last = (t == nt - 2);
;             const char* a1 = cA + (size_t)(t + 1) * kstep;
;             const char* a2 = last ? nA : cA + (size_t)(t + 2) * kstep; const char* b2 = last ? nB : cB + (size_t)(t + 2) * kstep;
;             const char* a3 = a2 + kstep; const char* b3 = b2 + kstep;
;             if (last && has_next) S.a_ready(nxt);
;             if constexpr (SP2) {
;             PG8_LDB(B0, 0, 0); PG8_LDB(B1, 0, 1); PG8_SCHED; PG8_LDA(At, 0, 0); PG8_STAGE(PG8_SA(1, 1), a1 + hstep, voffA);
;             PG8_WAIT_V(8); PG8_WAIT_L(0); PG8_BAR; PG8_MMA(0, 0, At, B0); PG8_MMA(0, 1, At, B1); PG8_BAR; PG8_SCHED;
;             PG8_LDA(At, 0, 1); PG8_STAGE(PG8_SB(0, 0), b2, voffB); PG8_STAGE(PG8_SB(0, 1), b2 + hstep, voffB); PG8_STAGE(PG8_SA(0, 0), a2, voffA);
.LBB0_177:
	ds_read_b128 v[128:131], v203
	ds_read_b128 v[132:135], v203 offset:1024
	ds_read_b128 v[136:139], v203 offset:2048
	ds_read_b128 v[140:143], v203 offset:3072
	ds_read_b128 v[144:147], v204
	ds_read_b128 v[148:151], v204 offset:1024
	ds_read_b128 v[152:155], v204 offset:2048
	ds_read_b128 v[156:159], v204 offset:3072
	s_add_u32 s0, s50, 0x100
	s_addc_u32 s1, s51, 0
	s_cmpk_eq_i32 s56, 0x54
	s_cselect_b32 s81, s11, s1
	s_cselect_b32 s80, s10, s0
	s_cselect_b32 s25, s75, s55
	s_cselect_b32 s24, s74, s54
	v_lshl_add_u64 v[212:213], s[50:51], 0, v[180:181]
	s_add_i32 m0, s33, 0xc000
	ds_read_b128 v[160:163], v205
	ds_read_b128 v[164:167], v205 offset:1024
	ds_read_b128 v[168:171], v205 offset:2048
	ds_read_b128 v[172:175], v205 offset:3072
	ds_read_b128 v[188:191], v205 offset:4096
	ds_read_b128 v[192:195], v205 offset:5120
	ds_read_b128 v[196:199], v205 offset:6144
	ds_read_b128 v[208:211], v205 offset:7168
	global_load_lds_dwordx4 v[212:213], off
	v_lshl_add_u64 v[212:213], s[50:51], 0, v[182:183]
	s_add_i32 m0, s33, 0xe000
	s_nop 0
	global_load_lds_dwordx4 v[212:213], off
	s_waitcnt vmcnt(8)
	s_waitcnt lgkmcnt(0)
	s_barrier
	s_setprio 1
	v_mfma_f32_16x16x32_bf16 v[124:127], v[128:131], v[160:163], v[124:127]
	v_mfma_f32_16x16x32_bf16 v[120:123], v[136:139], v[160:163], v[120:123]
	v_mfma_f32_16x16x32_bf16 v[108:111], v[128:131], v[168:171], v[108:111]
	v_mfma_f32_16x16x32_bf16 v[104:107], v[136:139], v[168:171], v[104:107]
	v_mfma_f32_16x16x32_bf16 v[92:95], v[128:131], v[188:191], v[92:95]
	v_mfma_f32_16x16x32_bf16 v[88:91], v[136:139], v[188:191], v[88:91]
	v_mfma_f32_16x16x32_bf16 v[76:79], v[128:131], v[196:199], v[76:79]
	v_mfma_f32_16x16x32_bf16 v[72:75], v[136:139], v[196:199], v[72:75]
	v_mfma_f32_16x16x32_bf16 v[124:127], v[132:135], v[164:167], v[124:127]
	v_mfma_f32_16x16x32_bf16 v[120:123], v[140:143], v[164:167], v[120:123]
	v_mfma_f32_16x16x32_bf16 v[108:111], v[132:135], v[172:175], v[108:111]
	v_mfma_f32_16x16x32_bf16 v[104:107], v[140:143], v[172:175], v[104:107]
	v_mfma_f32_16x16x32_bf16 v[92:95], v[132:135], v[192:195], v[92:95]
	v_mfma_f32_16x16x32_bf16 v[88:91], v[140:143], v[192:195], v[88:91]
	v_mfma_f32_16x16x32_bf16 v[76:79], v[132:135], v[208:211], v[76:79]
	v_mfma_f32_16x16x32_bf16 v[72:75], v[140:143], v[208:211], v[72:75]
	s_setprio 0
	s_setprio 1
	v_mfma_f32_16x16x32_bf16 v[116:119], v[144:147], v[160:163], v[116:119]
	v_mfma_f32_16x16x32_bf16 v[112:115], v[152:155], v[160:163], v[112:115]
	v_mfma_f32_16x16x32_bf16 v[100:103], v[144:147], v[168:171], v[100:103]
	v_mfma_f32_16x16x32_bf16 v[96:99], v[152:155], v[168:171], v[96:99]
	v_mfma_f32_16x16x32_bf16 v[84:87], v[144:147], v[188:191], v[84:87]
	v_mfma_f32_16x16x32_bf16 v[80:83], v[152:155], v[188:191], v[80:83]
	v_mfma_f32_16x16x32_bf16 v[68:71], v[144:147], v[196:199], v[68:71]
	v_mfma_f32_16x16x32_bf16 v[64:67], v[152:155], v[196:199], v[64:67]
	v_mfma_f32_16x16x32_bf16 v[116:119], v[148:151], v[164:167], v[116:119]
	v_mfma_f32_16x16x32_bf16 v[112:115], v[156:159], v[164:167], v[112:115]
	v_mfma_f32_16x16x32_bf16 v[100:103], v[148:151], v[172:175], v[100:103]
	v_mfma_f32_16x16x32_bf16 v[96:99], v[156:159], v[172:175], v[96:99]
	v_mfma_f32_16x16x32_bf16 v[84:87], v[148:151], v[192:195], v[84:87]
	v_mfma_f32_16x16x32_bf16 v[80:83], v[156:159], v[192:195], v[80:83]
	v_mfma_f32_16x16x32_bf16 v[68:71], v[148:151], v[208:211], v[68:71]
	v_mfma_f32_16x16x32_bf16 v[64:67], v[156:159], v[208:211], v[64:67]
	s_setprio 0
	s_barrier
	s_add_i32 s50, s44, s3
	v_lshl_add_u64 v[212:213], s[24:25], 0, v[176:177]
	s_mov_b32 m0, s50
	ds_read_b128 v[160:163], v205 offset:16384
	ds_read_b128 v[164:167], v205 offset:17408
	ds_read_b128 v[168:171], v205 offset:18432
	ds_read_b128 v[172:175], v205 offset:19456
	ds_read_b128 v[188:191], v205 offset:20480
	ds_read_b128 v[192:195], v205 offset:21504
	ds_read_b128 v[196:199], v205 offset:22528
	ds_read_b128 v[208:211], v205 offset:23552
	global_load_lds_dwordx4 v[212:213], off
	s_add_i32 m0, s50, 0x2000
	s_add_u32 s50, s24, 0x160000
	v_lshl_add_u64 v[214:215], s[24:25], 0, v[178:179]
	s_addc_u32 s51, s25, 0
	s_add_i32 s57, s45, s3
	global_load_lds_dwordx4 v[214:215], off
	v_lshl_add_u64 v[216:217], s[50:51], 0, v[176:177]
	s_mov_b32 m0, s57
	v_lshl_add_u64 v[218:219], s[80:81], 0, v[178:179]
	global_load_lds_dwordx4 v[216:217], off
	v_lshl_add_u64 v[216:217], s[50:51], 0, v[178:179]
	s_add_i32 m0, s57, 0x2000
	s_nop 0
	global_load_lds_dwordx4 v[216:217], off
	v_lshl_add_u64 v[216:217], s[80:81], 0, v[176:177]
	s_mov_b32 m0, s33
	s_nop 0
	global_load_lds_dwordx4 v[216:217], off
	s_mov_b32 m0, s35
	s_nop 0
	global_load_lds_dwordx4 v[218:219], off
	s_waitcnt vmcnt(8)
	s_waitcnt lgkmcnt(0)
	s_barrier
; #define PG8_STAGE(bufoff, gbase, voff) do { _Pragma("unroll") for (int _i = 0; _i < 2; ++_i) \
;         __builtin_amdgcn_global_load_lds((const unsigned*)((const char*)(gbase) + (voff)[_i]), (PG8_LAS unsigned*)(lds + (bufoff) + ldsw + _i * 8192), 16, 0, 0); } while (0)
; #define PG8_LDA(dst, b, h) do { _Pragma("unroll") for (int m = 0; m < 4; ++m) _Pragma("unroll") for (int k = 0; k < 2; ++k) dst[m][k] = *(const PG8_LAS bf16x8*)(lds + PG8_SA(b, h) + aoff + m * 2048 + k * 1024); } while (0)
; #define PG8_LDB(dst, b, h) do { _Pragma("unroll") for (int n = 0; n < 2; ++n) _Pragma("unroll") for (int k = 0; k < 2; ++k) dst[n][k] = *(const PG8_LAS bf16x8*)(lds + PG8_SB(b, h) + boff + n * 2048 + k * 1024); } while (0)
; #define PG8_MMA(ai, bj, At, Bt) do { __builtin_amdgcn_s_setprio(1); _Pragma("unroll") for (int m = 0; m < 4; ++m) _Pragma("unroll") for (int n = 0; n < 2; ++n) _Pragma("unroll") for (int k = 0; k < 2; ++k) \
;         acc[ai][bj][m][n] = __builtin_amdgcn_mfma_f32_16x16x32_bf16(Bt[n][k], At[m][k], acc[ai][bj][m][n], 0, 0, 0); __builtin_amdgcn_s_setprio(0); } while (0)
; #define PG8_WAIT_V(n) asm volatile("s_waitcnt vmcnt(" #n ")" ::: "memory")
; #define PG8_WAIT_L(n) asm volatile("s_waitcnt lgkmcnt(" #n ")" ::: "memory")
; #define PG8_BAR __builtin_amdgcn_s_barrier()
; #define PG8_SCHED __builtin_amdgcn_sched_barrier(0)
; template <class Epi, class Sched, bool ALIGN_EPI = false, bool SP2 = false>
; __device__ __forceinline__ void gemm_phase(PG8_LAS unsigned char* lds, const Gemm g, const Sched& S, const Epi& E) {
;     ...
;             PG8_WAIT_V(8); PG8_WAIT_L(0); PG8_BAR; PG8_MMA(1, 0, At, B0); PG8_MMA(1, 1, At, B1); PG8_BAR; PG8_SCHED;
;             PG8_LDB(B0, 1, 0); PG8_LDB(B1, 1, 1); PG8_SCHED; PG8_LDA(At, 1, 0); PG8_STAGE(PG8_SA(0, 1), a2 + hstep, voffA);
;             PG8_WAIT_V(8); PG8_WAIT_L(0); PG8_BAR; PG8_MMA(0, 0, At, B0); PG8_MMA(0, 1, At, B1); PG8_BAR; PG8_SCHED;
	s_setprio 1
	v_mfma_f32_16x16x32_bf16 v[60:63], v[128:131], v[160:163], v[60:63]
	v_mfma_f32_16x16x32_bf16 v[56:59], v[136:139], v[160:163], v[56:59]
	v_mfma_f32_16x16x32_bf16 v[44:47], v[128:131], v[168:171], v[44:47]
	v_mfma_f32_16x16x32_bf16 v[40:43], v[136:139], v[168:171], v[40:43]
	v_mfma_f32_16x16x32_bf16 v[28:31], v[128:131], v[188:191], v[28:31]
	v_mfma_f32_16x16x32_bf16 v[24:27], v[136:139], v[188:191], v[24:27]
	v_mfma_f32_16x16x32_bf16 v[12:15], v[128:131], v[196:199], v[12:15]
	v_mfma_f32_16x16x32_bf16 v[8:11], v[136:139], v[196:199], v[8:11]
	v_mfma_f32_16x16x32_bf16 v[60:63], v[132:135], v[164:167], v[60:63]
	v_mfma_f32_16x16x32_bf16 v[56:59], v[140:143], v[164:167], v[56:59]
	v_mfma_f32_16x16x32_bf16 v[44:47], v[132:135], v[172:175], v[44:47]
	v_mfma_f32_16x16x32_bf16 v[40:43], v[140:143], v[172:175], v[40:43]
	v_mfma_f32_16x16x32_bf16 v[28:31], v[132:135], v[192:195], v[28:31]
	v_mfma_f32_16x16x32_bf16 v[24:27], v[140:143], v[192:195], v[24:27]
	v_mfma_f32_16x16x32_bf16 v[12:15], v[132:135], v[208:211], v[12:15]
	v_mfma_f32_16x16x32_bf16 v[8:11], v[140:143], v[208:211], v[8:11]
	s_setprio 0
	s_setprio 1
	v_mfma_f32_16x16x32_bf16 v[52:55], v[144:147], v[160:163], v[52:55]
	v_mfma_f32_16x16x32_bf16 v[48:51], v[152:155], v[160:163], v[48:51]
	v_mfma_f32_16x16x32_bf16 v[36:39], v[144:147], v[168:171], v[36:39]
	v_mfma_f32_16x16x32_bf16 v[32:35], v[152:155], v[168:171], v[32:35]
	v_mfma_f32_16x16x32_bf16 v[20:23], v[144:147], v[188:191], v[20:23]
	v_mfma_f32_16x16x32_bf16 v[16:19], v[152:155], v[188:191], v[16:19]
	v_mfma_f32_16x16x32_bf16 v[4:7], v[144:147], v[196:199], v[4:7]
	v_mfma_f32_16x16x32_bf16 v[0:3], v[152:155], v[196:199], v[0:3]
	v_mfma_f32_16x16x32_bf16 v[52:55], v[148:151], v[164:167], v[52:55]
	v_mfma_f32_16x16x32_bf16 v[48:51], v[156:159], v[164:167], v[48:51]
	v_mfma_f32_16x16x32_bf16 v[36:39], v[148:151], v[172:175], v[36:39]
	v_mfma_f32_16x16x32_bf16 v[32:35], v[156:159], v[172:175], v[32:35]
	v_mfma_f32_16x16x32_bf16 v[20:23], v[148:151], v[192:195], v[20:23]
	v_mfma_f32_16x16x32_bf16 v[16:19], v[156:159], v[192:195], v[16:19]
	v_mfma_f32_16x16x32_bf16 v[4:7], v[148:151], v[208:211], v[4:7]
	v_mfma_f32_16x16x32_bf16 v[0:3], v[156:159], v[208:211], v[0:3]
	s_setprio 0
	s_barrier
	s_add_i32 s57, 0, 0x18000
	s_add_i32 s58, 0, 0x1c000
	v_add_u32_e32 v140, s57, v201
	v_add_u32_e32 v156, s58, v201
	ds_read_b128 v[128:131], v140
	ds_read_b128 v[132:135], v140 offset:1024
	ds_read_b128 v[136:139], v140 offset:2048
	ds_read_b128 v[140:143], v140 offset:3072
	ds_read_b128 v[144:147], v156
	ds_read_b128 v[148:151], v156 offset:1024
	ds_read_b128 v[152:155], v156 offset:2048
	ds_read_b128 v[156:159], v156 offset:3072
	s_add_u32 s50, s80, 0x160000
	s_addc_u32 s51, s81, 0
	s_mov_b32 m0, s36
	v_lshl_add_u64 v[220:221], s[50:51], 0, v[176:177]
	ds_read_b128 v[160:163], v205 offset:32768
	ds_read_b128 v[164:167], v205 offset:33792
	ds_read_b128 v[168:171], v205 offset:34816
	ds_read_b128 v[172:175], v205 offset:35840
	ds_read_b128 v[188:191], v205 offset:36864
	ds_read_b128 v[192:195], v205 offset:37888
	ds_read_b128 v[196:199], v205 offset:38912
	ds_read_b128 v[208:211], v205 offset:39936
	global_load_lds_dwordx4 v[220:221], off
	v_lshl_add_u64 v[220:221], s[50:51], 0, v[178:179]
	s_mov_b32 m0, s37
	s_nop 0
	global_load_lds_dwordx4 v[220:221], off
	s_waitcnt vmcnt(8)
	s_waitcnt lgkmcnt(0)
	s_barrier
	s_setprio 1
	v_mfma_f32_16x16x32_bf16 v[124:127], v[128:131], v[160:163], v[124:127]
	v_mfma_f32_16x16x32_bf16 v[120:123], v[136:139], v[160:163], v[120:123]
	v_mfma_f32_16x16x32_bf16 v[108:111], v[128:131], v[168:171], v[108:111]
	v_mfma_f32_16x16x32_bf16 v[104:107], v[136:139], v[168:171], v[104:107]
	v_mfma_f32_16x16x32_bf16 v[92:95], v[128:131], v[188:191], v[92:95]
	v_mfma_f32_16x16x32_bf16 v[88:91], v[136:139], v[188:191], v[88:91]
	v_mfma_f32_16x16x32_bf16 v[76:79], v[128:131], v[196:199], v[76:79]
	v_mfma_f32_16x16x32_bf16 v[72:75], v[136:139], v[196:199], v[72:75]
	v_mfma_f32_16x16x32_bf16 v[124:127], v[132:135], v[164:167], v[124:127]
	v_mfma_f32_16x16x32_bf16 v[120:123], v[140:143], v[164:167], v[120:123]
	v_mfma_f32_16x16x32_bf16 v[108:111], v[132:135], v[172:175], v[108:111]
	v_mfma_f32_16x16x32_bf16 v[104:107], v[140:143], v[172:175], v[104:107]
	v_mfma_f32_16x16x32_bf16 v[92:95], v[132:135], v[192:195], v[92:95]
	v_mfma_f32_16x16x32_bf16 v[88:91], v[140:143], v[192:195], v[88:91]
	v_mfma_f32_16x16x32_bf16 v[76:79], v[132:135], v[208:211], v[76:79]
	v_mfma_f32_16x16x32_bf16 v[72:75], v[140:143], v[208:211], v[72:75]
	s_setprio 0
	s_setprio 1
	v_mfma_f32_16x16x32_bf16 v[116:119], v[144:147], v[160:163], v[116:119]
	v_mfma_f32_16x16x32_bf16 v[112:115], v[152:155], v[160:163], v[112:115]
	v_mfma_f32_16x16x32_bf16 v[100:103], v[144:147], v[168:171], v[100:103]
	v_mfma_f32_16x16x32_bf16 v[96:99], v[152:155], v[168:171], v[96:99]
	v_mfma_f32_16x16x32_bf16 v[84:87], v[144:147], v[188:191], v[84:87]
	v_mfma_f32_16x16x32_bf16 v[80:83], v[152:155], v[188:191], v[80:83]
	v_mfma_f32_16x16x32_bf16 v[68:71], v[144:147], v[196:199], v[68:71]
	v_mfma_f32_16x16x32_bf16 v[64:67], v[152:155], v[196:199], v[64:67]
	v_mfma_f32_16x16x32_bf16 v[116:119], v[148:151], v[164:167], v[116:119]
	v_mfma_f32_16x16x32_bf16 v[112:115], v[156:159], v[164:167], v[112:115]
	v_mfma_f32_16x16x32_bf16 v[100:103], v[148:151], v[172:175], v[100:103]
	v_mfma_f32_16x16x32_bf16 v[96:99], v[156:159], v[172:175], v[96:99]
	v_mfma_f32_16x16x32_bf16 v[84:87], v[148:151], v[192:195], v[84:87]
	v_mfma_f32_16x16x32_bf16 v[80:83], v[156:159], v[192:195], v[80:83]
	v_mfma_f32_16x16x32_bf16 v[68:71], v[148:151], v[208:211], v[68:71]
	v_mfma_f32_16x16x32_bf16 v[64:67], v[156:159], v[208:211], v[64:67]
	s_setprio 0
	s_barrier
; #define PG8_STAGE(bufoff, gbase, voff) do { _Pragma("unroll") for (int _i = 0; _i < 2; ++_i) \
;         __builtin_amdgcn_global_load_lds((const unsigned*)((const char*)(gbase) + (voff)[_i]), (PG8_LAS unsigned*)(lds + (bufoff) + ldsw + _i * 8192), 16, 0, 0); } while (0)
; #define PG8_LDA(dst, b, h) do { _Pragma("unroll") for (int m = 0; m < 4; ++m) _Pragma("unroll") for (int k = 0; k < 2; ++k) dst[m][k] = *(const PG8_LAS bf16x8*)(lds + PG8_SA(b, h) + aoff + m * 2048 + k * 1024); } while (0)
; #define PG8_MMA(ai, bj, At, Bt) do { __builtin_amdgcn_s_setprio(1); _Pragma("unroll") for (int m = 0; m < 4; ++m) _Pragma("unroll") for (int n = 0; n < 2; ++n) _Pragma("unroll") for (int k = 0; k < 2; ++k) \
;         acc[ai][bj][m][n] = __builtin_amdgcn_mfma_f32_16x16x32_bf16(Bt[n][k], At[m][k], acc[ai][bj][m][n], 0, 0, 0); __builtin_amdgcn_s_setprio(0); } while (0)
; #define PG8_WAIT_V(n) asm volatile("s_waitcnt vmcnt(" #n ")" ::: "memory")
; #define PG8_WAIT_L(n) asm volatile("s_waitcnt lgkmcnt(" #n ")" ::: "memory")
; #define PG8_BAR __builtin_amdgcn_s_barrier()
; #define PG8_SCHED __builtin_amdgcn_sched_barrier(0)
; template <class Epi, class Sched, bool ALIGN_EPI = false, bool SP2 = false>
; __device__ __forceinline__ void gemm_phase(PG8_LAS unsigned char* lds, const Gemm g, const Sched& S, const Epi& E) {
;     ...
;             PG8_LDA(At, 1, 1); PG8_STAGE(PG8_SB(1, 0), b3, voffB); PG8_STAGE(PG8_SB(1, 1), b3 + hstep, voffB); PG8_STAGE(PG8_SA(1, 0), a3, voffA);
;             PG8_WAIT_V(8); PG8_WAIT_L(0); PG8_BAR; PG8_MMA(1, 0, At, B0); PG8_MMA(1, 1, At, B1); PG8_BAR; PG8_SCHED;
;     ...
;         if constexpr (ALIGN_EPI) { if (wr == 0) PG8_BAR; }
	s_add_i32 s50, s57, s3
	v_lshl_add_u64 v[212:213], v[212:213], 0, s[14:15]
	s_mov_b32 m0, s50
	ds_read_b128 v[160:163], v205 offset:49152
	ds_read_b128 v[164:167], v205 offset:50176
	ds_read_b128 v[168:171], v205 offset:51200
	ds_read_b128 v[172:175], v205 offset:52224
	ds_read_b128 v[188:191], v205 offset:53248
	ds_read_b128 v[192:195], v205 offset:54272
	ds_read_b128 v[196:199], v205 offset:55296
	ds_read_b128 v[208:211], v205 offset:56320
	global_load_lds_dwordx4 v[212:213], off
	s_add_i32 m0, s50, 0x2000
	s_add_u32 s24, s24, 0x160080
	v_lshl_add_u64 v[212:213], v[214:215], 0, s[14:15]
	s_addc_u32 s25, s25, 0
	s_add_i32 s50, s58, s3
	global_load_lds_dwordx4 v[212:213], off
	v_lshl_add_u64 v[212:213], s[24:25], 0, v[176:177]
	s_mov_b32 m0, s50
	s_nop 0
	global_load_lds_dwordx4 v[212:213], off
	v_lshl_add_u64 v[212:213], s[24:25], 0, v[178:179]
	s_add_i32 m0, s50, 0x2000
	s_nop 0
	global_load_lds_dwordx4 v[212:213], off
	v_lshl_add_u64 v[212:213], v[216:217], 0, s[14:15]
	s_mov_b32 m0, s39
	s_nop 0
	global_load_lds_dwordx4 v[212:213], off
	v_lshl_add_u64 v[212:213], v[218:219], 0, s[14:15]
	s_mov_b32 m0, s40
	s_nop 0
	global_load_lds_dwordx4 v[212:213], off
	s_waitcnt vmcnt(8)
	s_waitcnt lgkmcnt(0)
	s_barrier
	s_setprio 1
	v_mfma_f32_16x16x32_bf16 v[60:63], v[128:131], v[160:163], v[60:63]
	v_mfma_f32_16x16x32_bf16 v[56:59], v[136:139], v[160:163], v[56:59]
	v_mfma_f32_16x16x32_bf16 v[44:47], v[128:131], v[168:171], v[44:47]
	v_mfma_f32_16x16x32_bf16 v[40:43], v[136:139], v[168:171], v[40:43]
	v_mfma_f32_16x16x32_bf16 v[28:31], v[128:131], v[188:191], v[28:31]
	v_mfma_f32_16x16x32_bf16 v[24:27], v[136:139], v[188:191], v[24:27]
	v_mfma_f32_16x16x32_bf16 v[12:15], v[128:131], v[196:199], v[12:15]
	v_mfma_f32_16x16x32_bf16 v[8:11], v[136:139], v[196:199], v[8:11]
	v_mfma_f32_16x16x32_bf16 v[60:63], v[132:135], v[164:167], v[60:63]
	v_mfma_f32_16x16x32_bf16 v[56:59], v[140:143], v[164:167], v[56:59]
	v_mfma_f32_16x16x32_bf16 v[44:47], v[132:135], v[172:175], v[44:47]
	v_mfma_f32_16x16x32_bf16 v[40:43], v[140:143], v[172:175], v[40:43]
	v_mfma_f32_16x16x32_bf16 v[28:31], v[132:135], v[192:195], v[28:31]
	v_mfma_f32_16x16x32_bf16 v[24:27], v[140:143], v[192:195], v[24:27]
	v_mfma_f32_16x16x32_bf16 v[12:15], v[132:135], v[208:211], v[12:15]
	v_mfma_f32_16x16x32_bf16 v[8:11], v[140:143], v[208:211], v[8:11]
	s_setprio 0
	s_setprio 1
	v_mfma_f32_16x16x32_bf16 v[52:55], v[144:147], v[160:163], v[52:55]
	v_mfma_f32_16x16x32_bf16 v[48:51], v[152:155], v[160:163], v[48:51]
	v_mfma_f32_16x16x32_bf16 v[36:39], v[144:147], v[168:171], v[36:39]
	v_mfma_f32_16x16x32_bf16 v[32:35], v[152:155], v[168:171], v[32:35]
	v_mfma_f32_16x16x32_bf16 v[20:23], v[144:147], v[188:191], v[20:23]
	v_mfma_f32_16x16x32_bf16 v[16:19], v[152:155], v[188:191], v[16:19]
	v_mfma_f32_16x16x32_bf16 v[4:7], v[144:147], v[196:199], v[4:7]
	v_mfma_f32_16x16x32_bf16 v[0:3], v[152:155], v[196:199], v[0:3]
	v_mfma_f32_16x16x32_bf16 v[52:55], v[148:151], v[164:167], v[52:55]
	v_mfma_f32_16x16x32_bf16 v[48:51], v[156:159], v[164:167], v[48:51]
	v_mfma_f32_16x16x32_bf16 v[36:39], v[148:151], v[172:175], v[36:39]
	v_mfma_f32_16x16x32_bf16 v[32:35], v[156:159], v[172:175], v[32:35]
	v_mfma_f32_16x16x32_bf16 v[20:23], v[148:151], v[192:195], v[20:23]
	v_mfma_f32_16x16x32_bf16 v[16:19], v[156:159], v[192:195], v[16:19]
	v_mfma_f32_16x16x32_bf16 v[4:7], v[148:151], v[208:211], v[4:7]
	v_mfma_f32_16x16x32_bf16 v[0:3], v[156:159], v[208:211], v[0:3]
	s_setprio 0
	s_barrier
	s_add_i32 s56, s56, 2
	s_add_u32 s54, s54, 0x100
	s_addc_u32 s55, s55, 0
	s_cmpk_gt_u32 s56, 0x55
	s_mov_b64 s[50:51], s[0:1]
	s_cbranch_scc0 .LBB0_177
	s_and_b64 vcc, exec, s[20:21]
	s_cbranch_vccz .LBB0_180
	s_barrier

; #define PG8_STAGE(bufoff, gbase, voff) do { _Pragma("unroll") for (int _i = 0; _i < 2; ++_i) \
;         __builtin_amdgcn_global_load_lds((const unsigned*)((const char*)(gbase) + (voff)[_i]), (PG8_LAS unsigned*)(lds + (bufoff) + ldsw + _i * 8192), 16, 0, 0); } while (0)
; #define PG8_LDA(dst, b, h) do { _Pragma("unroll") for (int m = 0; m < 4; ++m) _Pragma("unroll") for (int k = 0; k < 2; ++k) dst[m][k] = *(const PG8_LAS bf16x8*)(lds + PG8_SA(b, h) + aoff + m * 2048 + k * 1024); } while (0)
; #define PG8_LDB(dst, b, h) do { _Pragma("unroll") for (int n = 0; n < 2; ++n) _Pragma("unroll") for (int k = 0; k < 2; ++k) dst[n][k] = *(const PG8_LAS bf16x8*)(lds + PG8_SB(b, h) + boff + n * 2048 + k * 1024); } while (0)
; #define PG8_MMA(ai, bj, At, Bt) do { __builtin_amdgcn_s_setprio(1); _Pragma("unroll") for (int m = 0; m < 4; ++m) _Pragma("unroll") for (int n = 0; n < 2; ++n) _Pragma("unroll") for (int k = 0; k < 2; ++k) \
;         acc[ai][bj][m][n] = __builtin_amdgcn_mfma_f32_16x16x32_bf16(Bt[n][k], At[m][k], acc[ai][bj][m][n], 0, 0, 0); __builtin_amdgcn_s_setprio(0); } while (0)
; #define PG8_WAIT_V(n) asm volatile("s_waitcnt vmcnt(" #n ")" ::: "memory")
; #define PG8_WAIT_L(n) asm volatile("s_waitcnt lgkmcnt(" #n ")" ::: "memory")
; #define PG8_BAR __builtin_amdgcn_s_barrier()
; #define PG8_SCHED __builtin_amdgcn_sched_barrier(0)
; template <class Epi, class Sched, bool ALIGN_EPI = false, bool SP2 = false>
; __device__ __forceinline__ void gemm_phase(PG8_LAS unsigned char* lds, const Gemm g, const Sched& S, const Epi& E) {
;     ...
;         for (int t = 0; t < nt; t += 2) {
;             const bool last = (t == nt - 2);
;             const char* a1 = cA + (size_t)(t + 1) * kstep;
;             const char* a2 = last ? nA : cA + (size_t)(t + 2) * kstep; const char* b2 = last ? nB : cB + (size_t)(t + 2) * kstep;
;             const char* a3 = a2 + kstep; const char* b3 = b2 + kstep;
;             if (last && has_next) S.a_ready(nxt);
;             if constexpr (SP2) {
;             PG8_LDB(B0, 0, 0); PG8_LDB(B1, 0, 1); PG8_SCHED; PG8_LDA(At, 0, 0); PG8_STAGE(PG8_SA(1, 1), a1 + hstep, voffA);
;             PG8_WAIT_V(8); PG8_WAIT_L(0); PG8_BAR; PG8_MMA(0, 0, At, B0); PG8_MMA(0, 1, At, B1); PG8_BAR; PG8_SCHED;
;             PG8_LDA(At, 0, 1); PG8_STAGE(PG8_SB(0, 0), b2, voffB); PG8_STAGE(PG8_SB(0, 1), b2 + hstep, voffB); PG8_STAGE(PG8_SA(0, 0), a2, voffA);
.LBB0_263:
	ds_read_b128 v[4:7], v208
	ds_read_b128 v[12:15], v208 offset:1024
	ds_read_b128 v[16:19], v208 offset:2048
	ds_read_b128 v[20:23], v208 offset:3072
	ds_read_b128 v[164:167], v209
	ds_read_b128 v[168:171], v209 offset:1024
	ds_read_b128 v[172:175], v209 offset:2048
	ds_read_b128 v[176:179], v209 offset:3072
	s_add_u32 s0, s4, 0xfff80080
	s_addc_u32 s1, s5, -1
	s_cmp_eq_u32 s17, 28
	s_cselect_b32 s7, s3, s1
	s_cselect_b32 s6, s11, s0
	s_cselect_b32 s1, s12, s16
	s_cselect_b32 s0, s13, s15
	v_lshl_add_u64 v[220:221], s[4:5], 0, v[156:157]
	s_add_i32 m0, s25, 0xc000
	ds_read_b128 v[180:183], v210
	ds_read_b128 v[184:187], v210 offset:1024
	ds_read_b128 v[188:191], v210 offset:2048
	ds_read_b128 v[192:195], v210 offset:3072
	ds_read_b128 v[196:199], v210 offset:4096
	ds_read_b128 v[200:203], v210 offset:5120
	ds_read_b128 v[216:219], v210 offset:6144
	ds_read_b128 v[228:231], v210 offset:7168
	global_load_lds_dwordx4 v[220:221], off
	v_lshl_add_u64 v[220:221], s[4:5], 0, v[158:159]
	s_add_i32 m0, s25, 0xe000
	s_nop 0
	global_load_lds_dwordx4 v[220:221], off
	s_waitcnt vmcnt(8)
	s_waitcnt lgkmcnt(0)
	s_barrier
	s_setprio 1
	v_mfma_f32_16x16x32_bf16 v[140:143], v[4:7], v[180:183], v[140:143]
	v_mfma_f32_16x16x32_bf16 v[136:139], v[16:19], v[180:183], v[136:139]
	v_mfma_f32_16x16x32_bf16 v[124:127], v[4:7], v[188:191], v[124:127]
	v_mfma_f32_16x16x32_bf16 v[120:123], v[16:19], v[188:191], v[120:123]
	v_mfma_f32_16x16x32_bf16 v[108:111], v[4:7], v[196:199], v[108:111]
	v_mfma_f32_16x16x32_bf16 v[104:107], v[16:19], v[196:199], v[104:107]
	v_mfma_f32_16x16x32_bf16 v[92:95], v[4:7], v[216:219], v[92:95]
	v_mfma_f32_16x16x32_bf16 v[88:91], v[16:19], v[216:219], v[88:91]
	v_mfma_f32_16x16x32_bf16 v[140:143], v[12:15], v[184:187], v[140:143]
	v_mfma_f32_16x16x32_bf16 v[136:139], v[20:23], v[184:187], v[136:139]
	v_mfma_f32_16x16x32_bf16 v[124:127], v[12:15], v[192:195], v[124:127]
	v_mfma_f32_16x16x32_bf16 v[120:123], v[20:23], v[192:195], v[120:123]
	v_mfma_f32_16x16x32_bf16 v[108:111], v[12:15], v[200:203], v[108:111]
	v_mfma_f32_16x16x32_bf16 v[104:107], v[20:23], v[200:203], v[104:107]
	v_mfma_f32_16x16x32_bf16 v[92:95], v[12:15], v[228:231], v[92:95]
	v_mfma_f32_16x16x32_bf16 v[88:91], v[20:23], v[228:231], v[88:91]
	s_setprio 0
	s_setprio 1
	v_mfma_f32_16x16x32_bf16 v[132:135], v[164:167], v[180:183], v[132:135]
	v_mfma_f32_16x16x32_bf16 v[128:131], v[172:175], v[180:183], v[128:131]
	v_mfma_f32_16x16x32_bf16 v[116:119], v[164:167], v[188:191], v[116:119]
	v_mfma_f32_16x16x32_bf16 v[112:115], v[172:175], v[188:191], v[112:115]
	v_mfma_f32_16x16x32_bf16 v[100:103], v[164:167], v[196:199], v[100:103]
	v_mfma_f32_16x16x32_bf16 v[96:99], v[172:175], v[196:199], v[96:99]
	v_mfma_f32_16x16x32_bf16 v[84:87], v[164:167], v[216:219], v[84:87]
	v_mfma_f32_16x16x32_bf16 v[80:83], v[172:175], v[216:219], v[80:83]
	v_mfma_f32_16x16x32_bf16 v[132:135], v[168:171], v[184:187], v[132:135]
	v_mfma_f32_16x16x32_bf16 v[128:131], v[176:179], v[184:187], v[128:131]
	v_mfma_f32_16x16x32_bf16 v[116:119], v[168:171], v[192:195], v[116:119]
	v_mfma_f32_16x16x32_bf16 v[112:115], v[176:179], v[192:195], v[112:115]
	v_mfma_f32_16x16x32_bf16 v[100:103], v[168:171], v[200:203], v[100:103]
	v_mfma_f32_16x16x32_bf16 v[96:99], v[176:179], v[200:203], v[96:99]
	v_mfma_f32_16x16x32_bf16 v[84:87], v[168:171], v[228:231], v[84:87]
	v_mfma_f32_16x16x32_bf16 v[80:83], v[176:179], v[228:231], v[80:83]
	s_setprio 0
	s_barrier
	s_add_i32 s20, s54, s24
	v_lshl_add_u64 v[220:221], s[0:1], 0, v[146:147]
	s_mov_b32 m0, s20
	ds_read_b128 v[180:183], v210 offset:16384
	ds_read_b128 v[184:187], v210 offset:17408
	ds_read_b128 v[188:191], v210 offset:18432
	ds_read_b128 v[192:195], v210 offset:19456
	ds_read_b128 v[196:199], v210 offset:20480
	ds_read_b128 v[200:203], v210 offset:21504
	ds_read_b128 v[216:219], v210 offset:22528
	ds_read_b128 v[228:231], v210 offset:23552
	global_load_lds_dwordx4 v[220:221], off
	s_add_i32 m0, s20, 0x2000
	s_add_u32 s36, s0, 0x80000
	v_lshl_add_u64 v[232:233], s[0:1], 0, v[150:151]
	s_addc_u32 s37, s1, 0
	s_add_i32 s20, s55, s24
	global_load_lds_dwordx4 v[232:233], off
	v_lshl_add_u64 v[234:235], s[36:37], 0, v[146:147]
	s_mov_b32 m0, s20
	v_lshl_add_u64 v[236:237], s[6:7], 0, v[148:149]
	global_load_lds_dwordx4 v[234:235], off
	v_lshl_add_u64 v[234:235], s[36:37], 0, v[150:151]
	s_add_i32 m0, s20, 0x2000
	s_nop 0
	global_load_lds_dwordx4 v[234:235], off
	v_lshl_add_u64 v[234:235], s[6:7], 0, v[144:145]
	s_mov_b32 m0, s25
	s_nop 0
	global_load_lds_dwordx4 v[234:235], off
	s_mov_b32 m0, s35
	s_nop 0
	global_load_lds_dwordx4 v[236:237], off
	s_waitcnt vmcnt(8)
	s_waitcnt lgkmcnt(0)
	s_barrier
; #define PG8_STAGE(bufoff, gbase, voff) do { _Pragma("unroll") for (int _i = 0; _i < 2; ++_i) \
;         __builtin_amdgcn_global_load_lds((const unsigned*)((const char*)(gbase) + (voff)[_i]), (PG8_LAS unsigned*)(lds + (bufoff) + ldsw + _i * 8192), 16, 0, 0); } while (0)
; #define PG8_LDA(dst, b, h) do { _Pragma("unroll") for (int m = 0; m < 4; ++m) _Pragma("unroll") for (int k = 0; k < 2; ++k) dst[m][k] = *(const PG8_LAS bf16x8*)(lds + PG8_SA(b, h) + aoff + m * 2048 + k * 1024); } while (0)
; #define PG8_LDB(dst, b, h) do { _Pragma("unroll") for (int n = 0; n < 2; ++n) _Pragma("unroll") for (int k = 0; k < 2; ++k) dst[n][k] = *(const PG8_LAS bf16x8*)(lds + PG8_SB(b, h) + boff + n * 2048 + k * 1024); } while (0)
; #define PG8_MMA(ai, bj, At, Bt) do { __builtin_amdgcn_s_setprio(1); _Pragma("unroll") for (int m = 0; m < 4; ++m) _Pragma("unroll") for (int n = 0; n < 2; ++n) _Pragma("unroll") for (int k = 0; k < 2; ++k) \
;         acc[ai][bj][m][n] = __builtin_amdgcn_mfma_f32_16x16x32_bf16(Bt[n][k], At[m][k], acc[ai][bj][m][n], 0, 0, 0); __builtin_amdgcn_s_setprio(0); } while (0)
; #define PG8_WAIT_V(n) asm volatile("s_waitcnt vmcnt(" #n ")" ::: "memory")
; #define PG8_WAIT_L(n) asm volatile("s_waitcnt lgkmcnt(" #n ")" ::: "memory")
; #define PG8_BAR __builtin_amdgcn_s_barrier()
; #define PG8_SCHED __builtin_amdgcn_sched_barrier(0)
; template <class Epi, class Sched, bool ALIGN_EPI = false, bool SP2 = false>
; __device__ __forceinline__ void gemm_phase(PG8_LAS unsigned char* lds, const Gemm g, const Sched& S, const Epi& E) {
;     ...
;             PG8_WAIT_V(8); PG8_WAIT_L(0); PG8_BAR; PG8_MMA(1, 0, At, B0); PG8_MMA(1, 1, At, B1); PG8_BAR; PG8_SCHED;
;             PG8_LDB(B0, 1, 0); PG8_LDB(B1, 1, 1); PG8_SCHED; PG8_LDA(At, 1, 0); PG8_STAGE(PG8_SA(0, 1), a2 + hstep, voffA);
;             PG8_WAIT_V(8); PG8_WAIT_L(0); PG8_BAR; PG8_MMA(0, 0, At, B0); PG8_MMA(0, 1, At, B1); PG8_BAR; PG8_SCHED;
	s_setprio 1
	v_mfma_f32_16x16x32_bf16 v[76:79], v[4:7], v[180:183], v[76:79]
	v_mfma_f32_16x16x32_bf16 v[72:75], v[16:19], v[180:183], v[72:75]
	v_mfma_f32_16x16x32_bf16 v[60:63], v[4:7], v[188:191], v[60:63]
	v_mfma_f32_16x16x32_bf16 v[56:59], v[16:19], v[188:191], v[56:59]
	v_mfma_f32_16x16x32_bf16 v[44:47], v[4:7], v[196:199], v[44:47]
	v_mfma_f32_16x16x32_bf16 v[40:43], v[16:19], v[196:199], v[40:43]
	v_mfma_f32_16x16x32_bf16 v[4:7], v[4:7], v[216:219], v[28:31]
	v_mfma_f32_16x16x32_bf16 v[76:79], v[12:15], v[184:187], v[76:79]
	v_mfma_f32_16x16x32_bf16 v[72:75], v[20:23], v[184:187], v[72:75]
	v_mfma_f32_16x16x32_bf16 v[60:63], v[12:15], v[192:195], v[60:63]
	v_mfma_f32_16x16x32_bf16 v[56:59], v[20:23], v[192:195], v[56:59]
	v_mfma_f32_16x16x32_bf16 v[44:47], v[12:15], v[200:203], v[44:47]
	v_mfma_f32_16x16x32_bf16 v[40:43], v[20:23], v[200:203], v[40:43]
	v_mfma_f32_16x16x32_bf16 v[4:7], v[12:15], v[228:231], v[4:7]
	v_mfma_f32_16x16x32_bf16 v[12:15], v[16:19], v[216:219], v[24:27]
	v_mfma_f32_16x16x32_bf16 v[12:15], v[20:23], v[228:231], v[12:15]
	s_setprio 0
	s_setprio 1
	v_mfma_f32_16x16x32_bf16 v[24:27], v[164:167], v[188:191], v[52:55]
	v_mfma_f32_16x16x32_bf16 v[52:55], v[168:171], v[192:195], v[24:27]
	v_mfma_f32_16x16x32_bf16 v[24:27], v[172:175], v[188:191], v[48:51]
	v_mfma_f32_16x16x32_bf16 v[48:51], v[176:179], v[192:195], v[24:27]
	v_mfma_f32_16x16x32_bf16 v[24:27], v[164:167], v[196:199], v[36:39]
	v_mfma_f32_16x16x32_bf16 v[36:39], v[168:171], v[200:203], v[24:27]
	v_mfma_f32_16x16x32_bf16 v[24:27], v[172:175], v[196:199], v[32:35]
	v_mfma_f32_16x16x32_bf16 v[8:11], v[164:167], v[216:219], v[8:11]
	v_mfma_f32_16x16x32_bf16 v[0:3], v[172:175], v[216:219], v[0:3]
	v_mfma_f32_16x16x32_bf16 v[16:19], v[164:167], v[180:183], v[68:71]
	v_mfma_f32_16x16x32_bf16 v[20:23], v[172:175], v[180:183], v[64:67]
	v_mfma_f32_16x16x32_bf16 v[32:35], v[176:179], v[200:203], v[24:27]
	v_mfma_f32_16x16x32_bf16 v[8:11], v[168:171], v[228:231], v[8:11]
	v_mfma_f32_16x16x32_bf16 v[0:3], v[176:179], v[228:231], v[0:3]
	v_mfma_f32_16x16x32_bf16 v[16:19], v[168:171], v[184:187], v[16:19]
	v_mfma_f32_16x16x32_bf16 v[20:23], v[176:179], v[184:187], v[20:23]
	s_setprio 0
	s_barrier
	s_add_i32 s20, 0, 0x18000
	s_add_i32 s33, 0, 0x1c000
	v_add_u32_e32 v68, s20, v206
	v_add_u32_e32 v152, s33, v206
	ds_read_b128 v[24:27], v68
	ds_read_b128 v[28:31], v68 offset:1024
	ds_read_b128 v[64:67], v68 offset:2048
	ds_read_b128 v[68:71], v68 offset:3072
	ds_read_b128 v[164:167], v152
	ds_read_b128 v[168:171], v152 offset:1024
	ds_read_b128 v[172:175], v152 offset:2048
	ds_read_b128 v[176:179], v152 offset:3072
	s_add_u32 s6, s6, 0x80000
	s_addc_u32 s7, s7, 0
	s_mov_b32 m0, s65
	v_lshl_add_u64 v[238:239], s[6:7], 0, v[144:145]
	ds_read_b128 v[180:183], v210 offset:32768
	ds_read_b128 v[184:187], v210 offset:33792
	ds_read_b128 v[188:191], v210 offset:34816
	ds_read_b128 v[192:195], v210 offset:35840
	ds_read_b128 v[196:199], v210 offset:36864
	ds_read_b128 v[200:203], v210 offset:37888
	ds_read_b128 v[216:219], v210 offset:38912
	ds_read_b128 v[228:231], v210 offset:39936
	global_load_lds_dwordx4 v[238:239], off
	v_lshl_add_u64 v[238:239], s[6:7], 0, v[148:149]
	s_mov_b32 m0, s59
	s_nop 0
	global_load_lds_dwordx4 v[238:239], off
	s_waitcnt vmcnt(8)
	s_waitcnt lgkmcnt(0)
	s_barrier
	s_setprio 1
	v_mfma_f32_16x16x32_bf16 v[140:143], v[24:27], v[180:183], v[140:143]
	v_mfma_f32_16x16x32_bf16 v[136:139], v[64:67], v[180:183], v[136:139]
	v_mfma_f32_16x16x32_bf16 v[124:127], v[24:27], v[188:191], v[124:127]
	v_mfma_f32_16x16x32_bf16 v[120:123], v[64:67], v[188:191], v[120:123]
	v_mfma_f32_16x16x32_bf16 v[108:111], v[24:27], v[196:199], v[108:111]
	v_mfma_f32_16x16x32_bf16 v[104:107], v[64:67], v[196:199], v[104:107]
	v_mfma_f32_16x16x32_bf16 v[92:95], v[24:27], v[216:219], v[92:95]
	v_mfma_f32_16x16x32_bf16 v[88:91], v[64:67], v[216:219], v[88:91]
	v_mfma_f32_16x16x32_bf16 v[140:143], v[28:31], v[184:187], v[140:143]
	v_mfma_f32_16x16x32_bf16 v[136:139], v[68:71], v[184:187], v[136:139]
	v_mfma_f32_16x16x32_bf16 v[124:127], v[28:31], v[192:195], v[124:127]
	v_mfma_f32_16x16x32_bf16 v[120:123], v[68:71], v[192:195], v[120:123]
	v_mfma_f32_16x16x32_bf16 v[108:111], v[28:31], v[200:203], v[108:111]
	v_mfma_f32_16x16x32_bf16 v[104:107], v[68:71], v[200:203], v[104:107]
	v_mfma_f32_16x16x32_bf16 v[92:95], v[28:31], v[228:231], v[92:95]
	v_mfma_f32_16x16x32_bf16 v[88:91], v[68:71], v[228:231], v[88:91]
	s_setprio 0
	s_setprio 1
	v_mfma_f32_16x16x32_bf16 v[132:135], v[164:167], v[180:183], v[132:135]
	v_mfma_f32_16x16x32_bf16 v[128:131], v[172:175], v[180:183], v[128:131]
	v_mfma_f32_16x16x32_bf16 v[116:119], v[164:167], v[188:191], v[116:119]
	v_mfma_f32_16x16x32_bf16 v[112:115], v[172:175], v[188:191], v[112:115]
	v_mfma_f32_16x16x32_bf16 v[100:103], v[164:167], v[196:199], v[100:103]
	v_mfma_f32_16x16x32_bf16 v[96:99], v[172:175], v[196:199], v[96:99]
	v_mfma_f32_16x16x32_bf16 v[84:87], v[164:167], v[216:219], v[84:87]
	v_mfma_f32_16x16x32_bf16 v[80:83], v[172:175], v[216:219], v[80:83]
	v_mfma_f32_16x16x32_bf16 v[132:135], v[168:171], v[184:187], v[132:135]
	v_mfma_f32_16x16x32_bf16 v[128:131], v[176:179], v[184:187], v[128:131]
	v_mfma_f32_16x16x32_bf16 v[116:119], v[168:171], v[192:195], v[116:119]
	v_mfma_f32_16x16x32_bf16 v[112:115], v[176:179], v[192:195], v[112:115]
	v_mfma_f32_16x16x32_bf16 v[100:103], v[168:171], v[200:203], v[100:103]
	v_mfma_f32_16x16x32_bf16 v[96:99], v[176:179], v[200:203], v[96:99]
	v_mfma_f32_16x16x32_bf16 v[84:87], v[168:171], v[228:231], v[84:87]
	v_mfma_f32_16x16x32_bf16 v[80:83], v[176:179], v[228:231], v[80:83]
	s_setprio 0
	s_barrier
; #define PG8_STAGE(bufoff, gbase, voff) do { _Pragma("unroll") for (int _i = 0; _i < 2; ++_i) \
;         __builtin_amdgcn_global_load_lds((const unsigned*)((const char*)(gbase) + (voff)[_i]), (PG8_LAS unsigned*)(lds + (bufoff) + ldsw + _i * 8192), 16, 0, 0); } while (0)
; #define PG8_LDA(dst, b, h) do { _Pragma("unroll") for (int m = 0; m < 4; ++m) _Pragma("unroll") for (int k = 0; k < 2; ++k) dst[m][k] = *(const PG8_LAS bf16x8*)(lds + PG8_SA(b, h) + aoff + m * 2048 + k * 1024); } while (0)
; #define PG8_MMA(ai, bj, At, Bt) do { __builtin_amdgcn_s_setprio(1); _Pragma("unroll") for (int m = 0; m < 4; ++m) _Pragma("unroll") for (int n = 0; n < 2; ++n) _Pragma("unroll") for (int k = 0; k < 2; ++k) \
;         acc[ai][bj][m][n] = __builtin_amdgcn_mfma_f32_16x16x32_bf16(Bt[n][k], At[m][k], acc[ai][bj][m][n], 0, 0, 0); __builtin_amdgcn_s_setprio(0); } while (0)
; #define PG8_WAIT_V(n) asm volatile("s_waitcnt vmcnt(" #n ")" ::: "memory")
; #define PG8_WAIT_L(n) asm volatile("s_waitcnt lgkmcnt(" #n ")" ::: "memory")
; #define PG8_BAR __builtin_amdgcn_s_barrier()
; #define PG8_SCHED __builtin_amdgcn_sched_barrier(0)
; template <class Epi, class Sched, bool ALIGN_EPI = false, bool SP2 = false>
; __device__ __forceinline__ void gemm_phase(PG8_LAS unsigned char* lds, const Gemm g, const Sched& S, const Epi& E) {
;     ...
;             PG8_LDA(At, 1, 1); PG8_STAGE(PG8_SB(1, 0), b3, voffB); PG8_STAGE(PG8_SB(1, 1), b3 + hstep, voffB); PG8_STAGE(PG8_SA(1, 0), a3, voffA);
;             PG8_WAIT_V(8); PG8_WAIT_L(0); PG8_BAR; PG8_MMA(1, 0, At, B0); PG8_MMA(1, 1, At, B1); PG8_BAR; PG8_SCHED;
;     ...
;         if constexpr (ALIGN_EPI) { if (wr == 0) PG8_BAR; }
	s_add_i32 s6, s20, s24
	v_lshl_add_u64 v[220:221], v[220:221], 0, s[84:85]
	s_mov_b32 m0, s6
	ds_read_b128 v[180:183], v210 offset:49152
	ds_read_b128 v[184:187], v210 offset:50176
	ds_read_b128 v[188:191], v210 offset:51200
	ds_read_b128 v[192:195], v210 offset:52224
	ds_read_b128 v[196:199], v210 offset:53248
	ds_read_b128 v[200:203], v210 offset:54272
	ds_read_b128 v[216:219], v210 offset:55296
	ds_read_b128 v[228:231], v210 offset:56320
	global_load_lds_dwordx4 v[220:221], off
	s_add_i32 m0, s6, 0x2000
	s_add_u32 s0, s0, 0x80080
	v_lshl_add_u64 v[220:221], v[232:233], 0, s[84:85]
	s_addc_u32 s1, s1, 0
	s_add_i32 s6, s33, s24
	global_load_lds_dwordx4 v[220:221], off
	v_lshl_add_u64 v[220:221], s[0:1], 0, v[146:147]
	s_mov_b32 m0, s6
	s_nop 0
	global_load_lds_dwordx4 v[220:221], off
	v_lshl_add_u64 v[220:221], s[0:1], 0, v[150:151]
	s_add_i32 m0, s6, 0x2000
	s_nop 0
	global_load_lds_dwordx4 v[220:221], off
	v_lshl_add_u64 v[220:221], v[234:235], 0, s[84:85]
	s_mov_b32 m0, s67
	s_nop 0
	global_load_lds_dwordx4 v[220:221], off
	v_lshl_add_u64 v[220:221], v[236:237], 0, s[84:85]
	s_mov_b32 m0, s22
	s_nop 0
	global_load_lds_dwordx4 v[220:221], off
	s_waitcnt vmcnt(8)
	s_waitcnt lgkmcnt(0)
	s_barrier
	s_setprio 1
	v_mfma_f32_16x16x32_bf16 v[76:79], v[24:27], v[180:183], v[76:79]
	v_mfma_f32_16x16x32_bf16 v[60:63], v[24:27], v[188:191], v[60:63]
	v_mfma_f32_16x16x32_bf16 v[44:47], v[24:27], v[196:199], v[44:47]
	v_mfma_f32_16x16x32_bf16 v[4:7], v[24:27], v[216:219], v[4:7]
	v_mfma_f32_16x16x32_bf16 v[76:79], v[28:31], v[184:187], v[76:79]
	v_mfma_f32_16x16x32_bf16 v[72:75], v[64:67], v[180:183], v[72:75]
	v_mfma_f32_16x16x32_bf16 v[60:63], v[28:31], v[192:195], v[60:63]
	v_mfma_f32_16x16x32_bf16 v[56:59], v[64:67], v[188:191], v[56:59]
	v_mfma_f32_16x16x32_bf16 v[44:47], v[28:31], v[200:203], v[44:47]
	v_mfma_f32_16x16x32_bf16 v[40:43], v[64:67], v[196:199], v[40:43]
	v_mfma_f32_16x16x32_bf16 v[28:31], v[28:31], v[228:231], v[4:7]
	v_mfma_f32_16x16x32_bf16 v[4:7], v[64:67], v[216:219], v[12:15]
	v_mfma_f32_16x16x32_bf16 v[72:75], v[68:71], v[184:187], v[72:75]
	v_mfma_f32_16x16x32_bf16 v[56:59], v[68:71], v[192:195], v[56:59]
	v_mfma_f32_16x16x32_bf16 v[40:43], v[68:71], v[200:203], v[40:43]
	v_mfma_f32_16x16x32_bf16 v[24:27], v[68:71], v[228:231], v[4:7]
	s_setprio 0
	s_setprio 1
	v_mfma_f32_16x16x32_bf16 v[4:7], v[164:167], v[180:183], v[16:19]
	v_mfma_f32_16x16x32_bf16 v[68:71], v[168:171], v[184:187], v[4:7]
	v_mfma_f32_16x16x32_bf16 v[4:7], v[172:175], v[180:183], v[20:23]
	v_mfma_f32_16x16x32_bf16 v[64:67], v[176:179], v[184:187], v[4:7]
	v_mfma_f32_16x16x32_bf16 v[4:7], v[164:167], v[188:191], v[52:55]
	v_mfma_f32_16x16x32_bf16 v[52:55], v[168:171], v[192:195], v[4:7]
	v_mfma_f32_16x16x32_bf16 v[4:7], v[172:175], v[188:191], v[48:51]
	v_mfma_f32_16x16x32_bf16 v[48:51], v[176:179], v[192:195], v[4:7]
	v_mfma_f32_16x16x32_bf16 v[4:7], v[164:167], v[196:199], v[36:39]
	v_mfma_f32_16x16x32_bf16 v[36:39], v[168:171], v[200:203], v[4:7]
	v_mfma_f32_16x16x32_bf16 v[4:7], v[172:175], v[196:199], v[32:35]
	v_mfma_f32_16x16x32_bf16 v[32:35], v[176:179], v[200:203], v[4:7]
	v_mfma_f32_16x16x32_bf16 v[4:7], v[164:167], v[216:219], v[8:11]
	v_mfma_f32_16x16x32_bf16 v[0:3], v[172:175], v[216:219], v[0:3]
	v_mfma_f32_16x16x32_bf16 v[8:11], v[168:171], v[228:231], v[4:7]
	v_mfma_f32_16x16x32_bf16 v[0:3], v[176:179], v[228:231], v[0:3]
	s_setprio 0
	s_barrier
	s_add_i32 s17, s17, 2
	s_add_u32 s4, s4, 0x100
	s_addc_u32 s5, s5, 0
	s_add_u32 s15, s15, 0x100
	s_addc_u32 s16, s16, 0
	s_cmp_gt_u32 s17, 29
	s_cbranch_scc0 .LBB0_263
	s_and_b64 vcc, exec, s[86:87]
	s_cbranch_vccz .LBB0_266
	s_barrier

; #define PG8_STAGE(bufoff, gbase, voff) do { _Pragma("unroll") for (int _i = 0; _i < 2; ++_i) \
;         __builtin_amdgcn_global_load_lds((const unsigned*)((const char*)(gbase) + (voff)[_i]), (PG8_LAS unsigned*)(lds + (bufoff) + ldsw + _i * 8192), 16, 0, 0); } while (0)
; #define PG8_LDA(dst, b, h) do { _Pragma("unroll") for (int m = 0; m < 4; ++m) _Pragma("unroll") for (int k = 0; k < 2; ++k) dst[m][k] = *(const PG8_LAS bf16x8*)(lds + PG8_SA(b, h) + aoff + m * 2048 + k * 1024); } while (0)
; #define PG8_LDB(dst, b, h) do { _Pragma("unroll") for (int n = 0; n < 2; ++n) _Pragma("unroll") for (int k = 0; k < 2; ++k) dst[n][k] = *(const PG8_LAS bf16x8*)(lds + PG8_SB(b, h) + boff + n * 2048 + k * 1024); } while (0)
; #define PG8_MMA(ai, bj, At, Bt) do { __builtin_amdgcn_s_setprio(1); _Pragma("unroll") for (int m = 0; m < 4; ++m) _Pragma("unroll") for (int n = 0; n < 2; ++n) _Pragma("unroll") for (int k = 0; k < 2; ++k) \
;         acc[ai][bj][m][n] = __builtin_amdgcn_mfma_f32_16x16x32_bf16(Bt[n][k], At[m][k], acc[ai][bj][m][n], 0, 0, 0); __builtin_amdgcn_s_setprio(0); } while (0)
; #define PG8_WAIT_V(n) asm volatile("s_waitcnt vmcnt(" #n ")" ::: "memory")
; #define PG8_WAIT_L(n) asm volatile("s_waitcnt lgkmcnt(" #n ")" ::: "memory")
; #define PG8_BAR __builtin_amdgcn_s_barrier()
; #define PG8_SCHED __builtin_amdgcn_sched_barrier(0)
; template <class Epi, class Sched, bool ALIGN_EPI = false, bool SP2 = false>
; __device__ __forceinline__ void gemm_phase(PG8_LAS unsigned char* lds, const Gemm g, const Sched& S, const Epi& E) {
;     ...
;         for (int t = 0; t < nt; t += 2) {
;             const bool last = (t == nt - 2);
;             const char* a1 = cA + (size_t)(t + 1) * kstep;
;             const char* a2 = last ? nA : cA + (size_t)(t + 2) * kstep; const char* b2 = last ? nB : cB + (size_t)(t + 2) * kstep;
;             const char* a3 = a2 + kstep; const char* b3 = b2 + kstep;
;             if (last && has_next) S.a_ready(nxt);
;             if constexpr (SP2) {
;             PG8_LDB(B0, 0, 0); PG8_LDB(B1, 0, 1); PG8_SCHED; PG8_LDA(At, 0, 0); PG8_STAGE(PG8_SA(1, 1), a1 + hstep, voffA);
;             PG8_WAIT_V(8); PG8_WAIT_L(0); PG8_BAR; PG8_MMA(0, 0, At, B0); PG8_MMA(0, 1, At, B1); PG8_BAR; PG8_SCHED;
;             PG8_LDA(At, 0, 1); PG8_STAGE(PG8_SB(0, 0), b2, voffB); PG8_STAGE(PG8_SB(0, 1), b2 + hstep, voffB); PG8_STAGE(PG8_SA(0, 0), a2, voffA);
.LBB0_1678:
	ds_read_b128 v[144:147], v157
	ds_read_b128 v[148:151], v157 offset:1024
	ds_read_b128 v[160:163], v157 offset:2048
	ds_read_b128 v[164:167], v157 offset:3072
	ds_read_b128 v[168:171], v158
	ds_read_b128 v[172:175], v158 offset:1024
	ds_read_b128 v[176:179], v158 offset:2048
	ds_read_b128 v[180:183], v158 offset:3072
	s_add_u32 s0, s36, 0xfffc0080
	s_addc_u32 s1, s37, -1
	s_cmp_eq_u32 s55, 12
	s_cselect_b32 s25, s21, s1
	s_cselect_b32 s24, s51, s0
	s_cselect_b32 s1, s19, s54
	s_cselect_b32 s0, s52, s53
	v_lshl_add_u64 v[152:153], s[36:37], 0, v[136:137]
	s_add_i32 m0, s31, 0xc000
	ds_read_b128 v[184:187], v159
	ds_read_b128 v[188:191], v159 offset:1024
	ds_read_b128 v[192:195], v159 offset:2048
	ds_read_b128 v[196:199], v159 offset:3072
	ds_read_b128 v[200:203], v159 offset:4096
	ds_read_b128 v[204:207], v159 offset:5120
	ds_read_b128 v[208:211], v159 offset:6144
	ds_read_b128 v[212:215], v159 offset:7168
	global_load_lds_dwordx4 v[152:153], off
	v_lshl_add_u64 v[152:153], s[36:37], 0, v[138:139]
	s_add_i32 m0, s31, 0xe000
	s_nop 0
	global_load_lds_dwordx4 v[152:153], off
	s_waitcnt vmcnt(8)
	s_waitcnt lgkmcnt(0)
	s_barrier
	s_setprio 1
	v_mfma_f32_16x16x32_bf16 v[124:127], v[144:147], v[184:187], v[124:127]
	v_mfma_f32_16x16x32_bf16 v[120:123], v[160:163], v[184:187], v[120:123]
	v_mfma_f32_16x16x32_bf16 v[116:119], v[144:147], v[192:195], v[116:119]
	v_mfma_f32_16x16x32_bf16 v[108:111], v[160:163], v[192:195], v[108:111]
	v_mfma_f32_16x16x32_bf16 v[96:99], v[144:147], v[200:203], v[96:99]
	v_mfma_f32_16x16x32_bf16 v[88:91], v[160:163], v[200:203], v[88:91]
	v_mfma_f32_16x16x32_bf16 v[80:83], v[144:147], v[208:211], v[80:83]
	v_mfma_f32_16x16x32_bf16 v[72:75], v[160:163], v[208:211], v[72:75]
	v_mfma_f32_16x16x32_bf16 v[124:127], v[148:151], v[188:191], v[124:127]
	v_mfma_f32_16x16x32_bf16 v[120:123], v[164:167], v[188:191], v[120:123]
	v_mfma_f32_16x16x32_bf16 v[116:119], v[148:151], v[196:199], v[116:119]
	v_mfma_f32_16x16x32_bf16 v[108:111], v[164:167], v[196:199], v[108:111]
	v_mfma_f32_16x16x32_bf16 v[96:99], v[148:151], v[204:207], v[96:99]
	v_mfma_f32_16x16x32_bf16 v[88:91], v[164:167], v[204:207], v[88:91]
	v_mfma_f32_16x16x32_bf16 v[80:83], v[148:151], v[212:215], v[80:83]
	v_mfma_f32_16x16x32_bf16 v[72:75], v[164:167], v[212:215], v[72:75]
	s_setprio 0
	s_setprio 1
	v_mfma_f32_16x16x32_bf16 v[112:115], v[168:171], v[184:187], v[112:115]
	v_mfma_f32_16x16x32_bf16 v[104:107], v[176:179], v[184:187], v[104:107]
	v_mfma_f32_16x16x32_bf16 v[100:103], v[168:171], v[192:195], v[100:103]
	v_mfma_f32_16x16x32_bf16 v[92:95], v[176:179], v[192:195], v[92:95]
	v_mfma_f32_16x16x32_bf16 v[84:87], v[168:171], v[200:203], v[84:87]
	v_mfma_f32_16x16x32_bf16 v[76:79], v[176:179], v[200:203], v[76:79]
	v_mfma_f32_16x16x32_bf16 v[68:71], v[168:171], v[208:211], v[68:71]
	v_mfma_f32_16x16x32_bf16 v[64:67], v[176:179], v[208:211], v[64:67]
	v_mfma_f32_16x16x32_bf16 v[112:115], v[172:175], v[188:191], v[112:115]
	v_mfma_f32_16x16x32_bf16 v[104:107], v[180:183], v[188:191], v[104:107]
	v_mfma_f32_16x16x32_bf16 v[100:103], v[172:175], v[196:199], v[100:103]
	v_mfma_f32_16x16x32_bf16 v[92:95], v[180:183], v[196:199], v[92:95]
	v_mfma_f32_16x16x32_bf16 v[84:87], v[172:175], v[204:207], v[84:87]
	v_mfma_f32_16x16x32_bf16 v[76:79], v[180:183], v[204:207], v[76:79]
	v_mfma_f32_16x16x32_bf16 v[68:71], v[172:175], v[212:215], v[68:71]
	v_mfma_f32_16x16x32_bf16 v[64:67], v[180:183], v[212:215], v[64:67]
	s_setprio 0
	s_barrier
	s_add_i32 s56, s44, s17
	v_lshl_add_u64 v[152:153], s[0:1], 0, v[130:131]
	s_mov_b32 m0, s56
	ds_read_b128 v[184:187], v159 offset:16384
	ds_read_b128 v[188:191], v159 offset:17408
	ds_read_b128 v[192:195], v159 offset:18432
	ds_read_b128 v[196:199], v159 offset:19456
	ds_read_b128 v[200:203], v159 offset:20480
	ds_read_b128 v[204:207], v159 offset:21504
	ds_read_b128 v[208:211], v159 offset:22528
	ds_read_b128 v[212:215], v159 offset:23552
	global_load_lds_dwordx4 v[152:153], off
	s_add_i32 m0, s56, 0x2000
	s_add_u32 s56, s0, 0x40000
	v_lshl_add_u64 v[216:217], s[0:1], 0, v[134:135]
	s_addc_u32 s57, s1, 0
	s_add_i32 s58, s45, s17
	global_load_lds_dwordx4 v[216:217], off
	v_lshl_add_u64 v[218:219], s[56:57], 0, v[130:131]
	s_mov_b32 m0, s58
	v_lshl_add_u64 v[220:221], s[24:25], 0, v[132:133]
	global_load_lds_dwordx4 v[218:219], off
	v_lshl_add_u64 v[218:219], s[56:57], 0, v[134:135]
	s_add_i32 m0, s58, 0x2000
	s_nop 0
	global_load_lds_dwordx4 v[218:219], off
	v_lshl_add_u64 v[218:219], s[24:25], 0, v[128:129]
	s_mov_b32 m0, s31
	s_nop 0
	global_load_lds_dwordx4 v[218:219], off
	s_mov_b32 m0, s33
	s_nop 0
	global_load_lds_dwordx4 v[220:221], off
	s_waitcnt vmcnt(8)
	s_waitcnt lgkmcnt(0)
	s_barrier
; #define PG8_STAGE(bufoff, gbase, voff) do { _Pragma("unroll") for (int _i = 0; _i < 2; ++_i) \
;         __builtin_amdgcn_global_load_lds((const unsigned*)((const char*)(gbase) + (voff)[_i]), (PG8_LAS unsigned*)(lds + (bufoff) + ldsw + _i * 8192), 16, 0, 0); } while (0)
; #define PG8_LDA(dst, b, h) do { _Pragma("unroll") for (int m = 0; m < 4; ++m) _Pragma("unroll") for (int k = 0; k < 2; ++k) dst[m][k] = *(const PG8_LAS bf16x8*)(lds + PG8_SA(b, h) + aoff + m * 2048 + k * 1024); } while (0)
; #define PG8_LDB(dst, b, h) do { _Pragma("unroll") for (int n = 0; n < 2; ++n) _Pragma("unroll") for (int k = 0; k < 2; ++k) dst[n][k] = *(const PG8_LAS bf16x8*)(lds + PG8_SB(b, h) + boff + n * 2048 + k * 1024); } while (0)
; #define PG8_MMA(ai, bj, At, Bt) do { __builtin_amdgcn_s_setprio(1); _Pragma("unroll") for (int m = 0; m < 4; ++m) _Pragma("unroll") for (int n = 0; n < 2; ++n) _Pragma("unroll") for (int k = 0; k < 2; ++k) \
;         acc[ai][bj][m][n] = __builtin_amdgcn_mfma_f32_16x16x32_bf16(Bt[n][k], At[m][k], acc[ai][bj][m][n], 0, 0, 0); __builtin_amdgcn_s_setprio(0); } while (0)
; #define PG8_WAIT_V(n) asm volatile("s_waitcnt vmcnt(" #n ")" ::: "memory")
; #define PG8_WAIT_L(n) asm volatile("s_waitcnt lgkmcnt(" #n ")" ::: "memory")
; #define PG8_BAR __builtin_amdgcn_s_barrier()
; #define PG8_SCHED __builtin_amdgcn_sched_barrier(0)
; template <class Epi, class Sched, bool ALIGN_EPI = false, bool SP2 = false>
; __device__ __forceinline__ void gemm_phase(PG8_LAS unsigned char* lds, const Gemm g, const Sched& S, const Epi& E) {
;     ...
;             PG8_WAIT_V(8); PG8_WAIT_L(0); PG8_BAR; PG8_MMA(1, 0, At, B0); PG8_MMA(1, 1, At, B1); PG8_BAR; PG8_SCHED;
;             PG8_LDB(B0, 1, 0); PG8_LDB(B1, 1, 1); PG8_SCHED; PG8_LDA(At, 1, 0); PG8_STAGE(PG8_SA(0, 1), a2 + hstep, voffA);
;             PG8_WAIT_V(8); PG8_WAIT_L(0); PG8_BAR; PG8_MMA(0, 0, At, B0); PG8_MMA(0, 1, At, B1); PG8_BAR; PG8_SCHED;
	s_setprio 1
	v_mfma_f32_16x16x32_bf16 v[60:63], v[144:147], v[184:187], v[60:63]
	v_mfma_f32_16x16x32_bf16 v[56:59], v[160:163], v[184:187], v[56:59]
	v_mfma_f32_16x16x32_bf16 v[48:51], v[144:147], v[192:195], v[48:51]
	v_mfma_f32_16x16x32_bf16 v[40:43], v[160:163], v[192:195], v[40:43]
	v_mfma_f32_16x16x32_bf16 v[32:35], v[144:147], v[200:203], v[32:35]
	v_mfma_f32_16x16x32_bf16 v[24:27], v[160:163], v[200:203], v[24:27]
	v_mfma_f32_16x16x32_bf16 v[16:19], v[144:147], v[208:211], v[16:19]
	v_mfma_f32_16x16x32_bf16 v[8:11], v[160:163], v[208:211], v[8:11]
	v_mfma_f32_16x16x32_bf16 v[60:63], v[148:151], v[188:191], v[60:63]
	v_mfma_f32_16x16x32_bf16 v[56:59], v[164:167], v[188:191], v[56:59]
	v_mfma_f32_16x16x32_bf16 v[48:51], v[148:151], v[196:199], v[48:51]
	v_mfma_f32_16x16x32_bf16 v[40:43], v[164:167], v[196:199], v[40:43]
	v_mfma_f32_16x16x32_bf16 v[32:35], v[148:151], v[204:207], v[32:35]
	v_mfma_f32_16x16x32_bf16 v[24:27], v[164:167], v[204:207], v[24:27]
	v_mfma_f32_16x16x32_bf16 v[16:19], v[148:151], v[212:215], v[16:19]
	v_mfma_f32_16x16x32_bf16 v[8:11], v[164:167], v[212:215], v[8:11]
	s_setprio 0
	s_setprio 1
	v_mfma_f32_16x16x32_bf16 v[52:55], v[168:171], v[184:187], v[52:55]
	v_mfma_f32_16x16x32_bf16 v[44:47], v[176:179], v[184:187], v[44:47]
	v_mfma_f32_16x16x32_bf16 v[36:39], v[168:171], v[192:195], v[36:39]
	v_mfma_f32_16x16x32_bf16 v[28:31], v[176:179], v[192:195], v[28:31]
	v_mfma_f32_16x16x32_bf16 v[20:23], v[168:171], v[200:203], v[20:23]
	v_mfma_f32_16x16x32_bf16 v[12:15], v[176:179], v[200:203], v[12:15]
	v_mfma_f32_16x16x32_bf16 v[4:7], v[168:171], v[208:211], v[4:7]
	v_mfma_f32_16x16x32_bf16 v[0:3], v[176:179], v[208:211], v[0:3]
	v_mfma_f32_16x16x32_bf16 v[52:55], v[172:175], v[188:191], v[52:55]
	v_mfma_f32_16x16x32_bf16 v[44:47], v[180:183], v[188:191], v[44:47]
	v_mfma_f32_16x16x32_bf16 v[36:39], v[172:175], v[196:199], v[36:39]
	v_mfma_f32_16x16x32_bf16 v[28:31], v[180:183], v[196:199], v[28:31]
	v_mfma_f32_16x16x32_bf16 v[20:23], v[172:175], v[204:207], v[20:23]
	v_mfma_f32_16x16x32_bf16 v[12:15], v[180:183], v[204:207], v[12:15]
	v_mfma_f32_16x16x32_bf16 v[4:7], v[172:175], v[212:215], v[4:7]
	v_mfma_f32_16x16x32_bf16 v[0:3], v[180:183], v[212:215], v[0:3]
	s_setprio 0
	s_barrier
	s_add_i32 s56, 0, 0x18000
	s_add_i32 s57, 0, 0x1c000
	v_add_u32_e32 v164, s56, v155
	v_add_u32_e32 v180, s57, v155
	ds_read_b128 v[144:147], v164
	ds_read_b128 v[148:151], v164 offset:1024
	ds_read_b128 v[160:163], v164 offset:2048
	ds_read_b128 v[164:167], v164 offset:3072
	ds_read_b128 v[168:171], v180
	ds_read_b128 v[172:175], v180 offset:1024
	ds_read_b128 v[176:179], v180 offset:2048
	ds_read_b128 v[180:183], v180 offset:3072
	s_add_u32 s24, s24, 0x40000
	s_addc_u32 s25, s25, 0
	s_mov_b32 m0, s35
	v_lshl_add_u64 v[228:229], s[24:25], 0, v[128:129]
	ds_read_b128 v[184:187], v159 offset:32768
	ds_read_b128 v[188:191], v159 offset:33792
	ds_read_b128 v[192:195], v159 offset:34816
	ds_read_b128 v[196:199], v159 offset:35840
	ds_read_b128 v[200:203], v159 offset:36864
	ds_read_b128 v[204:207], v159 offset:37888
	ds_read_b128 v[208:211], v159 offset:38912
	ds_read_b128 v[212:215], v159 offset:39936
	global_load_lds_dwordx4 v[228:229], off
	v_lshl_add_u64 v[228:229], s[24:25], 0, v[132:133]
	s_mov_b32 m0, s38
	s_nop 0
	global_load_lds_dwordx4 v[228:229], off
	s_waitcnt vmcnt(8)
	s_waitcnt lgkmcnt(0)
	s_barrier
	s_setprio 1
	v_mfma_f32_16x16x32_bf16 v[124:127], v[144:147], v[184:187], v[124:127]
	v_mfma_f32_16x16x32_bf16 v[120:123], v[160:163], v[184:187], v[120:123]
	v_mfma_f32_16x16x32_bf16 v[116:119], v[144:147], v[192:195], v[116:119]
	v_mfma_f32_16x16x32_bf16 v[108:111], v[160:163], v[192:195], v[108:111]
	v_mfma_f32_16x16x32_bf16 v[96:99], v[144:147], v[200:203], v[96:99]
	v_mfma_f32_16x16x32_bf16 v[88:91], v[160:163], v[200:203], v[88:91]
	v_mfma_f32_16x16x32_bf16 v[80:83], v[144:147], v[208:211], v[80:83]
	v_mfma_f32_16x16x32_bf16 v[72:75], v[160:163], v[208:211], v[72:75]
	v_mfma_f32_16x16x32_bf16 v[124:127], v[148:151], v[188:191], v[124:127]
	v_mfma_f32_16x16x32_bf16 v[120:123], v[164:167], v[188:191], v[120:123]
	v_mfma_f32_16x16x32_bf16 v[116:119], v[148:151], v[196:199], v[116:119]
	v_mfma_f32_16x16x32_bf16 v[108:111], v[164:167], v[196:199], v[108:111]
	v_mfma_f32_16x16x32_bf16 v[96:99], v[148:151], v[204:207], v[96:99]
	v_mfma_f32_16x16x32_bf16 v[88:91], v[164:167], v[204:207], v[88:91]
	v_mfma_f32_16x16x32_bf16 v[80:83], v[148:151], v[212:215], v[80:83]
	v_mfma_f32_16x16x32_bf16 v[72:75], v[164:167], v[212:215], v[72:75]
	s_setprio 0
	s_setprio 1
	v_mfma_f32_16x16x32_bf16 v[112:115], v[168:171], v[184:187], v[112:115]
	v_mfma_f32_16x16x32_bf16 v[104:107], v[176:179], v[184:187], v[104:107]
	v_mfma_f32_16x16x32_bf16 v[100:103], v[168:171], v[192:195], v[100:103]
	v_mfma_f32_16x16x32_bf16 v[92:95], v[176:179], v[192:195], v[92:95]
	v_mfma_f32_16x16x32_bf16 v[84:87], v[168:171], v[200:203], v[84:87]
	v_mfma_f32_16x16x32_bf16 v[76:79], v[176:179], v[200:203], v[76:79]
	v_mfma_f32_16x16x32_bf16 v[68:71], v[168:171], v[208:211], v[68:71]
	v_mfma_f32_16x16x32_bf16 v[64:67], v[176:179], v[208:211], v[64:67]
	v_mfma_f32_16x16x32_bf16 v[112:115], v[172:175], v[188:191], v[112:115]
	v_mfma_f32_16x16x32_bf16 v[104:107], v[180:183], v[188:191], v[104:107]
	v_mfma_f32_16x16x32_bf16 v[100:103], v[172:175], v[196:199], v[100:103]
	v_mfma_f32_16x16x32_bf16 v[92:95], v[180:183], v[196:199], v[92:95]
	v_mfma_f32_16x16x32_bf16 v[84:87], v[172:175], v[204:207], v[84:87]
	v_mfma_f32_16x16x32_bf16 v[76:79], v[180:183], v[204:207], v[76:79]
	v_mfma_f32_16x16x32_bf16 v[68:71], v[172:175], v[212:215], v[68:71]
	v_mfma_f32_16x16x32_bf16 v[64:67], v[180:183], v[212:215], v[64:67]
	s_setprio 0
	s_barrier
; #define PG8_STAGE(bufoff, gbase, voff) do { _Pragma("unroll") for (int _i = 0; _i < 2; ++_i) \
;         __builtin_amdgcn_global_load_lds((const unsigned*)((const char*)(gbase) + (voff)[_i]), (PG8_LAS unsigned*)(lds + (bufoff) + ldsw + _i * 8192), 16, 0, 0); } while (0)
; #define PG8_LDA(dst, b, h) do { _Pragma("unroll") for (int m = 0; m < 4; ++m) _Pragma("unroll") for (int k = 0; k < 2; ++k) dst[m][k] = *(const PG8_LAS bf16x8*)(lds + PG8_SA(b, h) + aoff + m * 2048 + k * 1024); } while (0)
; #define PG8_MMA(ai, bj, At, Bt) do { __builtin_amdgcn_s_setprio(1); _Pragma("unroll") for (int m = 0; m < 4; ++m) _Pragma("unroll") for (int n = 0; n < 2; ++n) _Pragma("unroll") for (int k = 0; k < 2; ++k) \
;         acc[ai][bj][m][n] = __builtin_amdgcn_mfma_f32_16x16x32_bf16(Bt[n][k], At[m][k], acc[ai][bj][m][n], 0, 0, 0); __builtin_amdgcn_s_setprio(0); } while (0)
; #define PG8_WAIT_V(n) asm volatile("s_waitcnt vmcnt(" #n ")" ::: "memory")
; #define PG8_WAIT_L(n) asm volatile("s_waitcnt lgkmcnt(" #n ")" ::: "memory")
; #define PG8_BAR __builtin_amdgcn_s_barrier()
; #define PG8_SCHED __builtin_amdgcn_sched_barrier(0)
; template <class Epi, class Sched, bool ALIGN_EPI = false, bool SP2 = false>
; __device__ __forceinline__ void gemm_phase(PG8_LAS unsigned char* lds, const Gemm g, const Sched& S, const Epi& E) {
;     ...
;             PG8_LDA(At, 1, 1); PG8_STAGE(PG8_SB(1, 0), b3, voffB); PG8_STAGE(PG8_SB(1, 1), b3 + hstep, voffB); PG8_STAGE(PG8_SA(1, 0), a3, voffA);
;             PG8_WAIT_V(8); PG8_WAIT_L(0); PG8_BAR; PG8_MMA(1, 0, At, B0); PG8_MMA(1, 1, At, B1); PG8_BAR; PG8_SCHED;
;     ...
;         if constexpr (ALIGN_EPI) { if (wr == 0) PG8_BAR; }
	s_add_i32 s24, s56, s17
	v_lshl_add_u64 v[152:153], v[152:153], 0, s[12:13]
	s_mov_b32 m0, s24
	ds_read_b128 v[184:187], v159 offset:49152
	ds_read_b128 v[188:191], v159 offset:50176
	ds_read_b128 v[192:195], v159 offset:51200
	ds_read_b128 v[196:199], v159 offset:52224
	ds_read_b128 v[200:203], v159 offset:53248
	ds_read_b128 v[204:207], v159 offset:54272
	ds_read_b128 v[208:211], v159 offset:55296
	ds_read_b128 v[212:215], v159 offset:56320
	global_load_lds_dwordx4 v[152:153], off
	s_add_i32 m0, s24, 0x2000
	s_add_u32 s0, s0, 0x40080
	v_lshl_add_u64 v[152:153], v[216:217], 0, s[12:13]
	s_addc_u32 s1, s1, 0
	s_add_i32 s24, s57, s17
	global_load_lds_dwordx4 v[152:153], off
	v_lshl_add_u64 v[152:153], s[0:1], 0, v[130:131]
	s_mov_b32 m0, s24
	s_nop 0
	global_load_lds_dwordx4 v[152:153], off
	v_lshl_add_u64 v[152:153], s[0:1], 0, v[134:135]
	s_add_i32 m0, s24, 0x2000
	s_nop 0
	global_load_lds_dwordx4 v[152:153], off
	v_lshl_add_u64 v[152:153], v[218:219], 0, s[12:13]
	s_mov_b32 m0, s40
	s_nop 0
	global_load_lds_dwordx4 v[152:153], off
	v_lshl_add_u64 v[152:153], v[220:221], 0, s[12:13]
	s_mov_b32 m0, s41
	s_nop 0
	global_load_lds_dwordx4 v[152:153], off
	s_waitcnt vmcnt(8)
	s_waitcnt lgkmcnt(0)
	s_barrier
	s_setprio 1
	v_mfma_f32_16x16x32_bf16 v[60:63], v[144:147], v[184:187], v[60:63]
	v_mfma_f32_16x16x32_bf16 v[56:59], v[160:163], v[184:187], v[56:59]
	v_mfma_f32_16x16x32_bf16 v[48:51], v[144:147], v[192:195], v[48:51]
	v_mfma_f32_16x16x32_bf16 v[40:43], v[160:163], v[192:195], v[40:43]
	v_mfma_f32_16x16x32_bf16 v[32:35], v[144:147], v[200:203], v[32:35]
	v_mfma_f32_16x16x32_bf16 v[24:27], v[160:163], v[200:203], v[24:27]
	v_mfma_f32_16x16x32_bf16 v[16:19], v[144:147], v[208:211], v[16:19]
	v_mfma_f32_16x16x32_bf16 v[8:11], v[160:163], v[208:211], v[8:11]
	v_mfma_f32_16x16x32_bf16 v[60:63], v[148:151], v[188:191], v[60:63]
	v_mfma_f32_16x16x32_bf16 v[56:59], v[164:167], v[188:191], v[56:59]
	v_mfma_f32_16x16x32_bf16 v[48:51], v[148:151], v[196:199], v[48:51]
	v_mfma_f32_16x16x32_bf16 v[40:43], v[164:167], v[196:199], v[40:43]
	v_mfma_f32_16x16x32_bf16 v[32:35], v[148:151], v[204:207], v[32:35]
	v_mfma_f32_16x16x32_bf16 v[24:27], v[164:167], v[204:207], v[24:27]
	v_mfma_f32_16x16x32_bf16 v[16:19], v[148:151], v[212:215], v[16:19]
	v_mfma_f32_16x16x32_bf16 v[8:11], v[164:167], v[212:215], v[8:11]
	s_setprio 0
	s_setprio 1
	v_mfma_f32_16x16x32_bf16 v[52:55], v[168:171], v[184:187], v[52:55]
	v_mfma_f32_16x16x32_bf16 v[44:47], v[176:179], v[184:187], v[44:47]
	v_mfma_f32_16x16x32_bf16 v[36:39], v[168:171], v[192:195], v[36:39]
	v_mfma_f32_16x16x32_bf16 v[28:31], v[176:179], v[192:195], v[28:31]
	v_mfma_f32_16x16x32_bf16 v[20:23], v[168:171], v[200:203], v[20:23]
	v_mfma_f32_16x16x32_bf16 v[12:15], v[176:179], v[200:203], v[12:15]
	v_mfma_f32_16x16x32_bf16 v[4:7], v[168:171], v[208:211], v[4:7]
	v_mfma_f32_16x16x32_bf16 v[0:3], v[176:179], v[208:211], v[0:3]
	v_mfma_f32_16x16x32_bf16 v[52:55], v[172:175], v[188:191], v[52:55]
	v_mfma_f32_16x16x32_bf16 v[44:47], v[180:183], v[188:191], v[44:47]
	v_mfma_f32_16x16x32_bf16 v[36:39], v[172:175], v[196:199], v[36:39]
	v_mfma_f32_16x16x32_bf16 v[28:31], v[180:183], v[196:199], v[28:31]
	v_mfma_f32_16x16x32_bf16 v[20:23], v[172:175], v[204:207], v[20:23]
	v_mfma_f32_16x16x32_bf16 v[12:15], v[180:183], v[204:207], v[12:15]
	v_mfma_f32_16x16x32_bf16 v[4:7], v[172:175], v[212:215], v[4:7]
	v_mfma_f32_16x16x32_bf16 v[0:3], v[180:183], v[212:215], v[0:3]
	s_setprio 0
	s_barrier
	s_add_i32 s55, s55, 2
	s_add_u32 s36, s36, 0x100
	s_addc_u32 s37, s37, 0
	s_add_u32 s53, s53, 0x100
	s_addc_u32 s54, s54, 0
	s_cmp_gt_u32 s55, 13
	s_cbranch_scc0 .LBB0_1678
	s_and_b64 vcc, exec, s[14:15]
	s_cbranch_vccz .LBB0_1681
	s_barrier

; #define PG8_STAGE(bufoff, gbase, voff) do { _Pragma("unroll") for (int _i = 0; _i < 2; ++_i) \
;         __builtin_amdgcn_global_load_lds((const unsigned*)((const char*)(gbase) + (voff)[_i]), (PG8_LAS unsigned*)(lds + (bufoff) + ldsw + _i * 8192), 16, 0, 0); } while (0)
; #define PG8_LDA(dst, b, h) do { _Pragma("unroll") for (int m = 0; m < 4; ++m) _Pragma("unroll") for (int k = 0; k < 2; ++k) dst[m][k] = *(const PG8_LAS bf16x8*)(lds + PG8_SA(b, h) + aoff + m * 2048 + k * 1024); } while (0)
; #define PG8_LDB(dst, b, h) do { _Pragma("unroll") for (int n = 0; n < 2; ++n) _Pragma("unroll") for (int k = 0; k < 2; ++k) dst[n][k] = *(const PG8_LAS bf16x8*)(lds + PG8_SB(b, h) + boff + n * 2048 + k * 1024); } while (0)
; #define PG8_MMA(ai, bj, At, Bt) do { __builtin_amdgcn_s_setprio(1); _Pragma("unroll") for (int m = 0; m < 4; ++m) _Pragma("unroll") for (int n = 0; n < 2; ++n) _Pragma("unroll") for (int k = 0; k < 2; ++k) \
;         acc[ai][bj][m][n] = __builtin_amdgcn_mfma_f32_16x16x32_bf16(Bt[n][k], At[m][k], acc[ai][bj][m][n], 0, 0, 0); __builtin_amdgcn_s_setprio(0); } while (0)
; #define PG8_WAIT_V(n) asm volatile("s_waitcnt vmcnt(" #n ")" ::: "memory")
; #define PG8_WAIT_L(n) asm volatile("s_waitcnt lgkmcnt(" #n ")" ::: "memory")
; #define PG8_BAR __builtin_amdgcn_s_barrier()
; #define PG8_SCHED __builtin_amdgcn_sched_barrier(0)
; template <class Epi, class Sched, bool ALIGN_EPI = false, bool SP2 = false>
; __device__ __forceinline__ void gemm_phase(PG8_LAS unsigned char* lds, const Gemm g, const Sched& S, const Epi& E) {
;     ...
;         for (int t = 0; t < nt; t += 2) {
;             const bool last = (t == nt - 2);
;             const char* a1 = cA + (size_t)(t + 1) * kstep;
;             const char* a2 = last ? nA : cA + (size_t)(t + 2) * kstep; const char* b2 = last ? nB : cB + (size_t)(t + 2) * kstep;
;             const char* a3 = a2 + kstep; const char* b3 = b2 + kstep;
;             if (last && has_next) S.a_ready(nxt);
;             if constexpr (SP2) {
;             PG8_LDB(B0, 0, 0); PG8_LDB(B1, 0, 1); PG8_SCHED; PG8_LDA(At, 0, 0); PG8_STAGE(PG8_SA(1, 1), a1 + hstep, voffA);
;             PG8_WAIT_V(8); PG8_WAIT_L(0); PG8_BAR; PG8_MMA(0, 0, At, B0); PG8_MMA(0, 1, At, B1); PG8_BAR; PG8_SCHED;
;             PG8_LDA(At, 0, 1); PG8_STAGE(PG8_SB(0, 0), b2, voffB); PG8_STAGE(PG8_SB(0, 1), b2 + hstep, voffB); PG8_STAGE(PG8_SA(0, 0), a2, voffA);
.LBB0_1702:
	ds_read_b128 v[128:131], v175
	ds_read_b128 v[132:135], v175 offset:1024
	ds_read_b128 v[136:139], v175 offset:2048
	ds_read_b128 v[156:159], v175 offset:3072
	ds_read_b128 v[160:163], v176
	ds_read_b128 v[164:167], v176 offset:1024
	ds_read_b128 v[168:171], v176 offset:2048
	ds_read_b128 v[178:181], v176 offset:3072
	s_add_u32 s0, s38, 0xfffc0080
	s_addc_u32 s1, s39, -1
	s_cmp_eq_u32 s57, 12
	s_cselect_b32 s25, s23, s1
	s_cselect_b32 s24, s53, s0
	s_cselect_b32 s1, s21, s56
	s_cselect_b32 s0, s54, s55
	v_lshl_add_u64 v[214:215], s[38:39], 0, v[148:149]
	s_add_i32 m0, s33, 0xc000
	ds_read_b128 v[182:185], v177
	ds_read_b128 v[186:189], v177 offset:1024
	ds_read_b128 v[190:193], v177 offset:2048
	ds_read_b128 v[194:197], v177 offset:3072
	ds_read_b128 v[198:201], v177 offset:4096
	ds_read_b128 v[202:205], v177 offset:5120
	ds_read_b128 v[206:209], v177 offset:6144
	ds_read_b128 v[210:213], v177 offset:7168
	global_load_lds_dwordx4 v[214:215], off
	v_lshl_add_u64 v[214:215], s[38:39], 0, v[150:151]
	s_add_i32 m0, s33, 0xe000
	s_nop 0
	global_load_lds_dwordx4 v[214:215], off
	s_waitcnt vmcnt(8)
	s_waitcnt lgkmcnt(0)
	s_barrier
	s_setprio 1
	v_mfma_f32_16x16x32_bf16 v[124:127], v[128:131], v[182:185], v[124:127]
	v_mfma_f32_16x16x32_bf16 v[120:123], v[136:139], v[182:185], v[120:123]
	v_mfma_f32_16x16x32_bf16 v[108:111], v[128:131], v[190:193], v[108:111]
	v_mfma_f32_16x16x32_bf16 v[104:107], v[136:139], v[190:193], v[104:107]
	v_mfma_f32_16x16x32_bf16 v[92:95], v[128:131], v[198:201], v[92:95]
	v_mfma_f32_16x16x32_bf16 v[88:91], v[136:139], v[198:201], v[88:91]
	v_mfma_f32_16x16x32_bf16 v[76:79], v[128:131], v[206:209], v[76:79]
	v_mfma_f32_16x16x32_bf16 v[72:75], v[136:139], v[206:209], v[72:75]
	v_mfma_f32_16x16x32_bf16 v[124:127], v[132:135], v[186:189], v[124:127]
	v_mfma_f32_16x16x32_bf16 v[120:123], v[156:159], v[186:189], v[120:123]
	v_mfma_f32_16x16x32_bf16 v[108:111], v[132:135], v[194:197], v[108:111]
	v_mfma_f32_16x16x32_bf16 v[104:107], v[156:159], v[194:197], v[104:107]
	v_mfma_f32_16x16x32_bf16 v[92:95], v[132:135], v[202:205], v[92:95]
	v_mfma_f32_16x16x32_bf16 v[88:91], v[156:159], v[202:205], v[88:91]
	v_mfma_f32_16x16x32_bf16 v[76:79], v[132:135], v[210:213], v[76:79]
	v_mfma_f32_16x16x32_bf16 v[72:75], v[156:159], v[210:213], v[72:75]
	s_setprio 0
	s_setprio 1
	v_mfma_f32_16x16x32_bf16 v[116:119], v[160:163], v[182:185], v[116:119]
	v_mfma_f32_16x16x32_bf16 v[112:115], v[168:171], v[182:185], v[112:115]
	v_mfma_f32_16x16x32_bf16 v[100:103], v[160:163], v[190:193], v[100:103]
	v_mfma_f32_16x16x32_bf16 v[96:99], v[168:171], v[190:193], v[96:99]
	v_mfma_f32_16x16x32_bf16 v[84:87], v[160:163], v[198:201], v[84:87]
	v_mfma_f32_16x16x32_bf16 v[80:83], v[168:171], v[198:201], v[80:83]
	v_mfma_f32_16x16x32_bf16 v[68:71], v[160:163], v[206:209], v[68:71]
	v_mfma_f32_16x16x32_bf16 v[64:67], v[168:171], v[206:209], v[64:67]
	v_mfma_f32_16x16x32_bf16 v[116:119], v[164:167], v[186:189], v[116:119]
	v_mfma_f32_16x16x32_bf16 v[112:115], v[178:181], v[186:189], v[112:115]
	v_mfma_f32_16x16x32_bf16 v[100:103], v[164:167], v[194:197], v[100:103]
	v_mfma_f32_16x16x32_bf16 v[96:99], v[178:181], v[194:197], v[96:99]
	v_mfma_f32_16x16x32_bf16 v[84:87], v[164:167], v[202:205], v[84:87]
	v_mfma_f32_16x16x32_bf16 v[80:83], v[178:181], v[202:205], v[80:83]
	v_mfma_f32_16x16x32_bf16 v[68:71], v[164:167], v[210:213], v[68:71]
	v_mfma_f32_16x16x32_bf16 v[64:67], v[178:181], v[210:213], v[64:67]
	s_setprio 0
	s_barrier
	s_add_i32 s58, s50, s19
	v_lshl_add_u64 v[214:215], s[0:1], 0, v[142:143]
	s_mov_b32 m0, s58
	ds_read_b128 v[182:185], v177 offset:16384
	ds_read_b128 v[186:189], v177 offset:17408
	ds_read_b128 v[190:193], v177 offset:18432
	ds_read_b128 v[194:197], v177 offset:19456
	ds_read_b128 v[198:201], v177 offset:20480
	ds_read_b128 v[202:205], v177 offset:21504
	ds_read_b128 v[206:209], v177 offset:22528
	ds_read_b128 v[210:213], v177 offset:23552
	global_load_lds_dwordx4 v[214:215], off
	s_add_i32 m0, s58, 0x2000
	s_add_u32 s58, s0, 0x40000
	v_lshl_add_u64 v[216:217], s[0:1], 0, v[146:147]
	s_addc_u32 s59, s1, 0
	s_add_i32 s65, s51, s19
	global_load_lds_dwordx4 v[216:217], off
	v_lshl_add_u64 v[218:219], s[58:59], 0, v[142:143]
	s_mov_b32 m0, s65
	v_lshl_add_u64 v[220:221], s[24:25], 0, v[144:145]
	global_load_lds_dwordx4 v[218:219], off
	v_lshl_add_u64 v[218:219], s[58:59], 0, v[146:147]
	s_add_i32 m0, s65, 0x2000
	s_nop 0
	global_load_lds_dwordx4 v[218:219], off
	v_lshl_add_u64 v[218:219], s[24:25], 0, v[140:141]
	s_mov_b32 m0, s33
	s_nop 0
	global_load_lds_dwordx4 v[218:219], off
	s_mov_b32 m0, s35
	s_nop 0
	global_load_lds_dwordx4 v[220:221], off
	s_waitcnt vmcnt(8)
	s_waitcnt lgkmcnt(0)
	s_barrier
; #define PG8_STAGE(bufoff, gbase, voff) do { _Pragma("unroll") for (int _i = 0; _i < 2; ++_i) \
;         __builtin_amdgcn_global_load_lds((const unsigned*)((const char*)(gbase) + (voff)[_i]), (PG8_LAS unsigned*)(lds + (bufoff) + ldsw + _i * 8192), 16, 0, 0); } while (0)
; #define PG8_LDA(dst, b, h) do { _Pragma("unroll") for (int m = 0; m < 4; ++m) _Pragma("unroll") for (int k = 0; k < 2; ++k) dst[m][k] = *(const PG8_LAS bf16x8*)(lds + PG8_SA(b, h) + aoff + m * 2048 + k * 1024); } while (0)
; #define PG8_LDB(dst, b, h) do { _Pragma("unroll") for (int n = 0; n < 2; ++n) _Pragma("unroll") for (int k = 0; k < 2; ++k) dst[n][k] = *(const PG8_LAS bf16x8*)(lds + PG8_SB(b, h) + boff + n * 2048 + k * 1024); } while (0)
; #define PG8_MMA(ai, bj, At, Bt) do { __builtin_amdgcn_s_setprio(1); _Pragma("unroll") for (int m = 0; m < 4; ++m) _Pragma("unroll") for (int n = 0; n < 2; ++n) _Pragma("unroll") for (int k = 0; k < 2; ++k) \
;         acc[ai][bj][m][n] = __builtin_amdgcn_mfma_f32_16x16x32_bf16(Bt[n][k], At[m][k], acc[ai][bj][m][n], 0, 0, 0); __builtin_amdgcn_s_setprio(0); } while (0)
; #define PG8_WAIT_V(n) asm volatile("s_waitcnt vmcnt(" #n ")" ::: "memory")
; #define PG8_WAIT_L(n) asm volatile("s_waitcnt lgkmcnt(" #n ")" ::: "memory")
; #define PG8_BAR __builtin_amdgcn_s_barrier()
; #define PG8_SCHED __builtin_amdgcn_sched_barrier(0)
; template <class Epi, class Sched, bool ALIGN_EPI = false, bool SP2 = false>
; __device__ __forceinline__ void gemm_phase(PG8_LAS unsigned char* lds, const Gemm g, const Sched& S, const Epi& E) {
;     ...
;             PG8_WAIT_V(8); PG8_WAIT_L(0); PG8_BAR; PG8_MMA(1, 0, At, B0); PG8_MMA(1, 1, At, B1); PG8_BAR; PG8_SCHED;
;             PG8_LDB(B0, 1, 0); PG8_LDB(B1, 1, 1); PG8_SCHED; PG8_LDA(At, 1, 0); PG8_STAGE(PG8_SA(0, 1), a2 + hstep, voffA);
;             PG8_WAIT_V(8); PG8_WAIT_L(0); PG8_BAR; PG8_MMA(0, 0, At, B0); PG8_MMA(0, 1, At, B1); PG8_BAR; PG8_SCHED;
	s_setprio 1
	v_mfma_f32_16x16x32_bf16 v[60:63], v[128:131], v[182:185], v[60:63]
	v_mfma_f32_16x16x32_bf16 v[56:59], v[136:139], v[182:185], v[56:59]
	v_mfma_f32_16x16x32_bf16 v[44:47], v[128:131], v[190:193], v[44:47]
	v_mfma_f32_16x16x32_bf16 v[40:43], v[136:139], v[190:193], v[40:43]
	v_mfma_f32_16x16x32_bf16 v[28:31], v[128:131], v[198:201], v[28:31]
	v_mfma_f32_16x16x32_bf16 v[24:27], v[136:139], v[198:201], v[24:27]
	v_mfma_f32_16x16x32_bf16 v[12:15], v[128:131], v[206:209], v[12:15]
	v_mfma_f32_16x16x32_bf16 v[8:11], v[136:139], v[206:209], v[8:11]
	v_mfma_f32_16x16x32_bf16 v[60:63], v[132:135], v[186:189], v[60:63]
	v_mfma_f32_16x16x32_bf16 v[56:59], v[156:159], v[186:189], v[56:59]
	v_mfma_f32_16x16x32_bf16 v[44:47], v[132:135], v[194:197], v[44:47]
	v_mfma_f32_16x16x32_bf16 v[40:43], v[156:159], v[194:197], v[40:43]
	v_mfma_f32_16x16x32_bf16 v[28:31], v[132:135], v[202:205], v[28:31]
	v_mfma_f32_16x16x32_bf16 v[24:27], v[156:159], v[202:205], v[24:27]
	v_mfma_f32_16x16x32_bf16 v[12:15], v[132:135], v[210:213], v[12:15]
	v_mfma_f32_16x16x32_bf16 v[8:11], v[156:159], v[210:213], v[8:11]
	s_setprio 0
	s_setprio 1
	v_mfma_f32_16x16x32_bf16 v[52:55], v[160:163], v[182:185], v[52:55]
	v_mfma_f32_16x16x32_bf16 v[48:51], v[168:171], v[182:185], v[48:51]
	v_mfma_f32_16x16x32_bf16 v[36:39], v[160:163], v[190:193], v[36:39]
	v_mfma_f32_16x16x32_bf16 v[32:35], v[168:171], v[190:193], v[32:35]
	v_mfma_f32_16x16x32_bf16 v[20:23], v[160:163], v[198:201], v[20:23]
	v_mfma_f32_16x16x32_bf16 v[16:19], v[168:171], v[198:201], v[16:19]
	v_mfma_f32_16x16x32_bf16 v[4:7], v[160:163], v[206:209], v[4:7]
	v_mfma_f32_16x16x32_bf16 v[0:3], v[168:171], v[206:209], v[0:3]
	v_mfma_f32_16x16x32_bf16 v[52:55], v[164:167], v[186:189], v[52:55]
	v_mfma_f32_16x16x32_bf16 v[48:51], v[178:181], v[186:189], v[48:51]
	v_mfma_f32_16x16x32_bf16 v[36:39], v[164:167], v[194:197], v[36:39]
	v_mfma_f32_16x16x32_bf16 v[32:35], v[178:181], v[194:197], v[32:35]
	v_mfma_f32_16x16x32_bf16 v[20:23], v[164:167], v[202:205], v[20:23]
	v_mfma_f32_16x16x32_bf16 v[16:19], v[178:181], v[202:205], v[16:19]
	v_mfma_f32_16x16x32_bf16 v[4:7], v[164:167], v[210:213], v[4:7]
	v_mfma_f32_16x16x32_bf16 v[0:3], v[178:181], v[210:213], v[0:3]
	s_setprio 0
	s_barrier
	s_add_i32 s58, 0, 0x18000
	s_add_i32 s59, 0, 0x1c000
	v_add_u32_e32 v156, s58, v173
	v_add_u32_e32 v178, s59, v173
	ds_read_b128 v[128:131], v156
	ds_read_b128 v[132:135], v156 offset:1024
	ds_read_b128 v[136:139], v156 offset:2048
	ds_read_b128 v[156:159], v156 offset:3072
	ds_read_b128 v[160:163], v178
	ds_read_b128 v[164:167], v178 offset:1024
	ds_read_b128 v[168:171], v178 offset:2048
	ds_read_b128 v[178:181], v178 offset:3072
	s_add_u32 s24, s24, 0x40000
	s_addc_u32 s25, s25, 0
	s_mov_b32 m0, s37
	v_lshl_add_u64 v[228:229], s[24:25], 0, v[140:141]
	ds_read_b128 v[182:185], v177 offset:32768
	ds_read_b128 v[186:189], v177 offset:33792
	ds_read_b128 v[190:193], v177 offset:34816
	ds_read_b128 v[194:197], v177 offset:35840
	ds_read_b128 v[198:201], v177 offset:36864
	ds_read_b128 v[202:205], v177 offset:37888
	ds_read_b128 v[206:209], v177 offset:38912
	ds_read_b128 v[210:213], v177 offset:39936
	global_load_lds_dwordx4 v[228:229], off
	v_lshl_add_u64 v[228:229], s[24:25], 0, v[144:145]
	s_mov_b32 m0, s40
	s_nop 0
	global_load_lds_dwordx4 v[228:229], off
	s_waitcnt vmcnt(8)
	s_waitcnt lgkmcnt(0)
	s_barrier
	s_setprio 1
	v_mfma_f32_16x16x32_bf16 v[124:127], v[128:131], v[182:185], v[124:127]
	v_mfma_f32_16x16x32_bf16 v[120:123], v[136:139], v[182:185], v[120:123]
	v_mfma_f32_16x16x32_bf16 v[108:111], v[128:131], v[190:193], v[108:111]
	v_mfma_f32_16x16x32_bf16 v[104:107], v[136:139], v[190:193], v[104:107]
	v_mfma_f32_16x16x32_bf16 v[92:95], v[128:131], v[198:201], v[92:95]
	v_mfma_f32_16x16x32_bf16 v[88:91], v[136:139], v[198:201], v[88:91]
	v_mfma_f32_16x16x32_bf16 v[76:79], v[128:131], v[206:209], v[76:79]
	v_mfma_f32_16x16x32_bf16 v[72:75], v[136:139], v[206:209], v[72:75]
	v_mfma_f32_16x16x32_bf16 v[124:127], v[132:135], v[186:189], v[124:127]
	v_mfma_f32_16x16x32_bf16 v[120:123], v[156:159], v[186:189], v[120:123]
	v_mfma_f32_16x16x32_bf16 v[108:111], v[132:135], v[194:197], v[108:111]
	v_mfma_f32_16x16x32_bf16 v[104:107], v[156:159], v[194:197], v[104:107]
	v_mfma_f32_16x16x32_bf16 v[92:95], v[132:135], v[202:205], v[92:95]
	v_mfma_f32_16x16x32_bf16 v[88:91], v[156:159], v[202:205], v[88:91]
	v_mfma_f32_16x16x32_bf16 v[76:79], v[132:135], v[210:213], v[76:79]
	v_mfma_f32_16x16x32_bf16 v[72:75], v[156:159], v[210:213], v[72:75]
	s_setprio 0
	s_setprio 1
	v_mfma_f32_16x16x32_bf16 v[116:119], v[160:163], v[182:185], v[116:119]
	v_mfma_f32_16x16x32_bf16 v[112:115], v[168:171], v[182:185], v[112:115]
	v_mfma_f32_16x16x32_bf16 v[100:103], v[160:163], v[190:193], v[100:103]
	v_mfma_f32_16x16x32_bf16 v[96:99], v[168:171], v[190:193], v[96:99]
	v_mfma_f32_16x16x32_bf16 v[84:87], v[160:163], v[198:201], v[84:87]
	v_mfma_f32_16x16x32_bf16 v[80:83], v[168:171], v[198:201], v[80:83]
	v_mfma_f32_16x16x32_bf16 v[68:71], v[160:163], v[206:209], v[68:71]
	v_mfma_f32_16x16x32_bf16 v[64:67], v[168:171], v[206:209], v[64:67]
	v_mfma_f32_16x16x32_bf16 v[116:119], v[164:167], v[186:189], v[116:119]
	v_mfma_f32_16x16x32_bf16 v[112:115], v[178:181], v[186:189], v[112:115]
	v_mfma_f32_16x16x32_bf16 v[100:103], v[164:167], v[194:197], v[100:103]
	v_mfma_f32_16x16x32_bf16 v[96:99], v[178:181], v[194:197], v[96:99]
	v_mfma_f32_16x16x32_bf16 v[84:87], v[164:167], v[202:205], v[84:87]
	v_mfma_f32_16x16x32_bf16 v[80:83], v[178:181], v[202:205], v[80:83]
	v_mfma_f32_16x16x32_bf16 v[68:71], v[164:167], v[210:213], v[68:71]
	v_mfma_f32_16x16x32_bf16 v[64:67], v[178:181], v[210:213], v[64:67]
	s_setprio 0
	s_barrier
; #define PG8_STAGE(bufoff, gbase, voff) do { _Pragma("unroll") for (int _i = 0; _i < 2; ++_i) \
;         __builtin_amdgcn_global_load_lds((const unsigned*)((const char*)(gbase) + (voff)[_i]), (PG8_LAS unsigned*)(lds + (bufoff) + ldsw + _i * 8192), 16, 0, 0); } while (0)
; #define PG8_LDA(dst, b, h) do { _Pragma("unroll") for (int m = 0; m < 4; ++m) _Pragma("unroll") for (int k = 0; k < 2; ++k) dst[m][k] = *(const PG8_LAS bf16x8*)(lds + PG8_SA(b, h) + aoff + m * 2048 + k * 1024); } while (0)
; #define PG8_MMA(ai, bj, At, Bt) do { __builtin_amdgcn_s_setprio(1); _Pragma("unroll") for (int m = 0; m < 4; ++m) _Pragma("unroll") for (int n = 0; n < 2; ++n) _Pragma("unroll") for (int k = 0; k < 2; ++k) \
;         acc[ai][bj][m][n] = __builtin_amdgcn_mfma_f32_16x16x32_bf16(Bt[n][k], At[m][k], acc[ai][bj][m][n], 0, 0, 0); __builtin_amdgcn_s_setprio(0); } while (0)
; #define PG8_WAIT_V(n) asm volatile("s_waitcnt vmcnt(" #n ")" ::: "memory")
; #define PG8_WAIT_L(n) asm volatile("s_waitcnt lgkmcnt(" #n ")" ::: "memory")
; #define PG8_BAR __builtin_amdgcn_s_barrier()
; #define PG8_SCHED __builtin_amdgcn_sched_barrier(0)
; template <class Epi, class Sched, bool ALIGN_EPI = false, bool SP2 = false>
; __device__ __forceinline__ void gemm_phase(PG8_LAS unsigned char* lds, const Gemm g, const Sched& S, const Epi& E) {
;     ...
;             PG8_LDA(At, 1, 1); PG8_STAGE(PG8_SB(1, 0), b3, voffB); PG8_STAGE(PG8_SB(1, 1), b3 + hstep, voffB); PG8_STAGE(PG8_SA(1, 0), a3, voffA);
;             PG8_WAIT_V(8); PG8_WAIT_L(0); PG8_BAR; PG8_MMA(1, 0, At, B0); PG8_MMA(1, 1, At, B1); PG8_BAR; PG8_SCHED;
;     ...
;         if constexpr (ALIGN_EPI) { if (wr == 0) PG8_BAR; }
	s_add_i32 s24, s58, s19
	v_lshl_add_u64 v[214:215], v[214:215], 0, s[14:15]
	s_mov_b32 m0, s24
	ds_read_b128 v[182:185], v177 offset:49152
	ds_read_b128 v[186:189], v177 offset:50176
	ds_read_b128 v[190:193], v177 offset:51200
	ds_read_b128 v[194:197], v177 offset:52224
	ds_read_b128 v[198:201], v177 offset:53248
	ds_read_b128 v[202:205], v177 offset:54272
	ds_read_b128 v[206:209], v177 offset:55296
	ds_read_b128 v[210:213], v177 offset:56320
	global_load_lds_dwordx4 v[214:215], off
	s_add_i32 m0, s24, 0x2000
	s_add_u32 s0, s0, 0x40080
	v_lshl_add_u64 v[214:215], v[216:217], 0, s[14:15]
	s_addc_u32 s1, s1, 0
	s_add_i32 s24, s59, s19
	global_load_lds_dwordx4 v[214:215], off
	v_lshl_add_u64 v[214:215], s[0:1], 0, v[142:143]
	s_mov_b32 m0, s24
	s_nop 0
	global_load_lds_dwordx4 v[214:215], off
	v_lshl_add_u64 v[214:215], s[0:1], 0, v[146:147]
	s_add_i32 m0, s24, 0x2000
	s_nop 0
	global_load_lds_dwordx4 v[214:215], off
	v_lshl_add_u64 v[214:215], v[218:219], 0, s[14:15]
	s_mov_b32 m0, s42
	s_nop 0
	global_load_lds_dwordx4 v[214:215], off
	v_lshl_add_u64 v[214:215], v[220:221], 0, s[14:15]
	s_mov_b32 m0, s43
	s_nop 0
	global_load_lds_dwordx4 v[214:215], off
	s_waitcnt vmcnt(8)
	s_waitcnt lgkmcnt(0)
	s_barrier
	s_setprio 1
	v_mfma_f32_16x16x32_bf16 v[60:63], v[128:131], v[182:185], v[60:63]
	v_mfma_f32_16x16x32_bf16 v[56:59], v[136:139], v[182:185], v[56:59]
	v_mfma_f32_16x16x32_bf16 v[44:47], v[128:131], v[190:193], v[44:47]
	v_mfma_f32_16x16x32_bf16 v[40:43], v[136:139], v[190:193], v[40:43]
	v_mfma_f32_16x16x32_bf16 v[28:31], v[128:131], v[198:201], v[28:31]
	v_mfma_f32_16x16x32_bf16 v[24:27], v[136:139], v[198:201], v[24:27]
	v_mfma_f32_16x16x32_bf16 v[12:15], v[128:131], v[206:209], v[12:15]
	v_mfma_f32_16x16x32_bf16 v[8:11], v[136:139], v[206:209], v[8:11]
	v_mfma_f32_16x16x32_bf16 v[60:63], v[132:135], v[186:189], v[60:63]
	v_mfma_f32_16x16x32_bf16 v[56:59], v[156:159], v[186:189], v[56:59]
	v_mfma_f32_16x16x32_bf16 v[44:47], v[132:135], v[194:197], v[44:47]
	v_mfma_f32_16x16x32_bf16 v[40:43], v[156:159], v[194:197], v[40:43]
	v_mfma_f32_16x16x32_bf16 v[28:31], v[132:135], v[202:205], v[28:31]
	v_mfma_f32_16x16x32_bf16 v[24:27], v[156:159], v[202:205], v[24:27]
	v_mfma_f32_16x16x32_bf16 v[12:15], v[132:135], v[210:213], v[12:15]
	v_mfma_f32_16x16x32_bf16 v[8:11], v[156:159], v[210:213], v[8:11]
	s_setprio 0
	s_setprio 1
	v_mfma_f32_16x16x32_bf16 v[52:55], v[160:163], v[182:185], v[52:55]
	v_mfma_f32_16x16x32_bf16 v[48:51], v[168:171], v[182:185], v[48:51]
	v_mfma_f32_16x16x32_bf16 v[36:39], v[160:163], v[190:193], v[36:39]
	v_mfma_f32_16x16x32_bf16 v[32:35], v[168:171], v[190:193], v[32:35]
	v_mfma_f32_16x16x32_bf16 v[20:23], v[160:163], v[198:201], v[20:23]
	v_mfma_f32_16x16x32_bf16 v[16:19], v[168:171], v[198:201], v[16:19]
	v_mfma_f32_16x16x32_bf16 v[4:7], v[160:163], v[206:209], v[4:7]
	v_mfma_f32_16x16x32_bf16 v[0:3], v[168:171], v[206:209], v[0:3]
	v_mfma_f32_16x16x32_bf16 v[52:55], v[164:167], v[186:189], v[52:55]
	v_mfma_f32_16x16x32_bf16 v[48:51], v[178:181], v[186:189], v[48:51]
	v_mfma_f32_16x16x32_bf16 v[36:39], v[164:167], v[194:197], v[36:39]
	v_mfma_f32_16x16x32_bf16 v[32:35], v[178:181], v[194:197], v[32:35]
	v_mfma_f32_16x16x32_bf16 v[20:23], v[164:167], v[202:205], v[20:23]
	v_mfma_f32_16x16x32_bf16 v[16:19], v[178:181], v[202:205], v[16:19]
	v_mfma_f32_16x16x32_bf16 v[4:7], v[164:167], v[210:213], v[4:7]
	v_mfma_f32_16x16x32_bf16 v[0:3], v[178:181], v[210:213], v[0:3]
	s_setprio 0
	s_barrier
	s_add_i32 s57, s57, 2
	s_add_u32 s38, s38, 0x100
	s_addc_u32 s39, s39, 0
	s_add_u32 s55, s55, 0x100
	s_addc_u32 s56, s56, 0
	s_cmp_gt_u32 s57, 13
	s_cbranch_scc0 .LBB0_1702
	s_and_b64 vcc, exec, s[16:17]
	s_cbranch_vccz .LBB0_1705
	s_barrier

; #define PG8_STAGE(bufoff, gbase, voff) do { _Pragma("unroll") for (int _i = 0; _i < 2; ++_i) \
;         __builtin_amdgcn_global_load_lds((const unsigned*)((const char*)(gbase) + (voff)[_i]), (PG8_LAS unsigned*)(lds + (bufoff) + ldsw + _i * 8192), 16, 0, 0); } while (0)
; #define PG8_LDA(dst, b, h) do { _Pragma("unroll") for (int m = 0; m < 4; ++m) _Pragma("unroll") for (int k = 0; k < 2; ++k) dst[m][k] = *(const PG8_LAS bf16x8*)(lds + PG8_SA(b, h) + aoff + m * 2048 + k * 1024); } while (0)
; #define PG8_LDB(dst, b, h) do { _Pragma("unroll") for (int n = 0; n < 2; ++n) _Pragma("unroll") for (int k = 0; k < 2; ++k) dst[n][k] = *(const PG8_LAS bf16x8*)(lds + PG8_SB(b, h) + boff + n * 2048 + k * 1024); } while (0)
; #define PG8_MMA(ai, bj, At, Bt) do { __builtin_amdgcn_s_setprio(1); _Pragma("unroll") for (int m = 0; m < 4; ++m) _Pragma("unroll") for (int n = 0; n < 2; ++n) _Pragma("unroll") for (int k = 0; k < 2; ++k) \
;         acc[ai][bj][m][n] = __builtin_amdgcn_mfma_f32_16x16x32_bf16(Bt[n][k], At[m][k], acc[ai][bj][m][n], 0, 0, 0); __builtin_amdgcn_s_setprio(0); } while (0)
; #define PG8_WAIT_V(n) asm volatile("s_waitcnt vmcnt(" #n ")" ::: "memory")
; #define PG8_WAIT_L(n) asm volatile("s_waitcnt lgkmcnt(" #n ")" ::: "memory")
; #define PG8_BAR __builtin_amdgcn_s_barrier()
; #define PG8_SCHED __builtin_amdgcn_sched_barrier(0)
; template <class Epi, class Sched, bool ALIGN_EPI = false, bool SP2 = false>
; __device__ __forceinline__ void gemm_phase(PG8_LAS unsigned char* lds, const Gemm g, const Sched& S, const Epi& E) {
;     ...
;         for (int t = 0; t < nt; t += 2) {
;             const bool last = (t == nt - 2);
;             const char* a1 = cA + (size_t)(t + 1) * kstep;
;             const char* a2 = last ? nA : cA + (size_t)(t + 2) * kstep; const char* b2 = last ? nB : cB + (size_t)(t + 2) * kstep;
;             const char* a3 = a2 + kstep; const char* b3 = b2 + kstep;
;             if (last && has_next) S.a_ready(nxt);
;             if constexpr (SP2) {
;             PG8_LDB(B0, 0, 0); PG8_LDB(B1, 0, 1); PG8_SCHED; PG8_LDA(At, 0, 0); PG8_STAGE(PG8_SA(1, 1), a1 + hstep, voffA);
;             PG8_WAIT_V(8); PG8_WAIT_L(0); PG8_BAR; PG8_MMA(0, 0, At, B0); PG8_MMA(0, 1, At, B1); PG8_BAR; PG8_SCHED;
;             PG8_LDA(At, 0, 1); PG8_STAGE(PG8_SB(0, 0), b2, voffB); PG8_STAGE(PG8_SB(0, 1), b2 + hstep, voffB); PG8_STAGE(PG8_SA(0, 0), a2, voffA);
.LBB0_1798:
	ds_read_b128 v[128:131], v209
	ds_read_b128 v[132:135], v209 offset:1024
	ds_read_b128 v[136:139], v209 offset:2048
	ds_read_b128 v[140:143], v209 offset:3072
	ds_read_b128 v[144:147], v210
	ds_read_b128 v[148:151], v210 offset:1024
	ds_read_b128 v[152:155], v210 offset:2048
	ds_read_b128 v[156:159], v210 offset:3072
	s_add_u32 s0, s40, 0xfff80080
	s_addc_u32 s1, s41, -1
	s_cmp_eq_u32 s56, 28
	s_cselect_b32 s25, s23, s1
	s_cselect_b32 s24, s52, s0
	s_cselect_b32 s1, s21, s55
	s_cselect_b32 s0, s53, s54
	v_lshl_add_u64 v[204:205], s[40:41], 0, v[180:181]
	s_add_i32 m0, s33, 0xc000
	ds_read_b128 v[160:163], v211
	ds_read_b128 v[164:167], v211 offset:1024
	ds_read_b128 v[168:171], v211 offset:2048
	ds_read_b128 v[172:175], v211 offset:3072
	ds_read_b128 v[188:191], v211 offset:4096
	ds_read_b128 v[192:195], v211 offset:5120
	ds_read_b128 v[196:199], v211 offset:6144
	ds_read_b128 v[200:203], v211 offset:7168
	global_load_lds_dwordx4 v[204:205], off
	v_lshl_add_u64 v[204:205], s[40:41], 0, v[182:183]
	s_add_i32 m0, s33, 0xe000
	s_nop 0
	global_load_lds_dwordx4 v[204:205], off
	s_waitcnt vmcnt(8)
	s_waitcnt lgkmcnt(0)
	s_barrier
	s_setprio 1
	v_mfma_f32_16x16x32_bf16 v[124:127], v[128:131], v[160:163], v[124:127]
	v_mfma_f32_16x16x32_bf16 v[120:123], v[136:139], v[160:163], v[120:123]
	v_mfma_f32_16x16x32_bf16 v[108:111], v[128:131], v[168:171], v[108:111]
	v_mfma_f32_16x16x32_bf16 v[104:107], v[136:139], v[168:171], v[104:107]
	v_mfma_f32_16x16x32_bf16 v[92:95], v[128:131], v[188:191], v[92:95]
	v_mfma_f32_16x16x32_bf16 v[88:91], v[136:139], v[188:191], v[88:91]
	v_mfma_f32_16x16x32_bf16 v[76:79], v[128:131], v[196:199], v[76:79]
	v_mfma_f32_16x16x32_bf16 v[72:75], v[136:139], v[196:199], v[72:75]
	v_mfma_f32_16x16x32_bf16 v[124:127], v[132:135], v[164:167], v[124:127]
	v_mfma_f32_16x16x32_bf16 v[120:123], v[140:143], v[164:167], v[120:123]
	v_mfma_f32_16x16x32_bf16 v[108:111], v[132:135], v[172:175], v[108:111]
	v_mfma_f32_16x16x32_bf16 v[104:107], v[140:143], v[172:175], v[104:107]
	v_mfma_f32_16x16x32_bf16 v[92:95], v[132:135], v[192:195], v[92:95]
	v_mfma_f32_16x16x32_bf16 v[88:91], v[140:143], v[192:195], v[88:91]
	v_mfma_f32_16x16x32_bf16 v[76:79], v[132:135], v[200:203], v[76:79]
	v_mfma_f32_16x16x32_bf16 v[72:75], v[140:143], v[200:203], v[72:75]
	s_setprio 0
	s_setprio 1
	v_mfma_f32_16x16x32_bf16 v[116:119], v[144:147], v[160:163], v[116:119]
	v_mfma_f32_16x16x32_bf16 v[112:115], v[152:155], v[160:163], v[112:115]
	v_mfma_f32_16x16x32_bf16 v[100:103], v[144:147], v[168:171], v[100:103]
	v_mfma_f32_16x16x32_bf16 v[96:99], v[152:155], v[168:171], v[96:99]
	v_mfma_f32_16x16x32_bf16 v[84:87], v[144:147], v[188:191], v[84:87]
	v_mfma_f32_16x16x32_bf16 v[80:83], v[152:155], v[188:191], v[80:83]
	v_mfma_f32_16x16x32_bf16 v[68:71], v[144:147], v[196:199], v[68:71]
	v_mfma_f32_16x16x32_bf16 v[64:67], v[152:155], v[196:199], v[64:67]
	v_mfma_f32_16x16x32_bf16 v[116:119], v[148:151], v[164:167], v[116:119]
	v_mfma_f32_16x16x32_bf16 v[112:115], v[156:159], v[164:167], v[112:115]
	v_mfma_f32_16x16x32_bf16 v[100:103], v[148:151], v[172:175], v[100:103]
	v_mfma_f32_16x16x32_bf16 v[96:99], v[156:159], v[172:175], v[96:99]
	v_mfma_f32_16x16x32_bf16 v[84:87], v[148:151], v[192:195], v[84:87]
	v_mfma_f32_16x16x32_bf16 v[80:83], v[156:159], v[192:195], v[80:83]
	v_mfma_f32_16x16x32_bf16 v[68:71], v[148:151], v[200:203], v[68:71]
	v_mfma_f32_16x16x32_bf16 v[64:67], v[156:159], v[200:203], v[64:67]
	s_setprio 0
	s_barrier
	s_add_i32 s57, s50, s3
	v_lshl_add_u64 v[204:205], s[0:1], 0, v[176:177]
	s_mov_b32 m0, s57
	ds_read_b128 v[160:163], v211 offset:16384
	ds_read_b128 v[164:167], v211 offset:17408
	ds_read_b128 v[168:171], v211 offset:18432
	ds_read_b128 v[172:175], v211 offset:19456
	ds_read_b128 v[188:191], v211 offset:20480
	ds_read_b128 v[192:195], v211 offset:21504
	ds_read_b128 v[196:199], v211 offset:22528
	ds_read_b128 v[200:203], v211 offset:23552
	global_load_lds_dwordx4 v[204:205], off
	s_add_i32 m0, s57, 0x2000
	s_add_u32 s58, s0, 0x80000
	v_lshl_add_u64 v[212:213], s[0:1], 0, v[178:179]
	s_addc_u32 s59, s1, 0
	s_add_i32 s57, s51, s3
	global_load_lds_dwordx4 v[212:213], off
	v_lshl_add_u64 v[214:215], s[58:59], 0, v[176:177]
	s_mov_b32 m0, s57
	v_lshl_add_u64 v[216:217], s[24:25], 0, v[178:179]
	global_load_lds_dwordx4 v[214:215], off
	v_lshl_add_u64 v[214:215], s[58:59], 0, v[178:179]
	s_add_i32 m0, s57, 0x2000
	s_nop 0
	global_load_lds_dwordx4 v[214:215], off
	v_lshl_add_u64 v[214:215], s[24:25], 0, v[176:177]
	s_mov_b32 m0, s33
	s_nop 0
	global_load_lds_dwordx4 v[214:215], off
	s_mov_b32 m0, s35
	s_nop 0
	global_load_lds_dwordx4 v[216:217], off
	s_waitcnt vmcnt(8)
	s_waitcnt lgkmcnt(0)
	s_barrier
; #define PG8_STAGE(bufoff, gbase, voff) do { _Pragma("unroll") for (int _i = 0; _i < 2; ++_i) \
;         __builtin_amdgcn_global_load_lds((const unsigned*)((const char*)(gbase) + (voff)[_i]), (PG8_LAS unsigned*)(lds + (bufoff) + ldsw + _i * 8192), 16, 0, 0); } while (0)
; #define PG8_LDA(dst, b, h) do { _Pragma("unroll") for (int m = 0; m < 4; ++m) _Pragma("unroll") for (int k = 0; k < 2; ++k) dst[m][k] = *(const PG8_LAS bf16x8*)(lds + PG8_SA(b, h) + aoff + m * 2048 + k * 1024); } while (0)
; #define PG8_LDB(dst, b, h) do { _Pragma("unroll") for (int n = 0; n < 2; ++n) _Pragma("unroll") for (int k = 0; k < 2; ++k) dst[n][k] = *(const PG8_LAS bf16x8*)(lds + PG8_SB(b, h) + boff + n * 2048 + k * 1024); } while (0)
; #define PG8_MMA(ai, bj, At, Bt) do { __builtin_amdgcn_s_setprio(1); _Pragma("unroll") for (int m = 0; m < 4; ++m) _Pragma("unroll") for (int n = 0; n < 2; ++n) _Pragma("unroll") for (int k = 0; k < 2; ++k) \
;         acc[ai][bj][m][n] = __builtin_amdgcn_mfma_f32_16x16x32_bf16(Bt[n][k], At[m][k], acc[ai][bj][m][n], 0, 0, 0); __builtin_amdgcn_s_setprio(0); } while (0)
; #define PG8_WAIT_V(n) asm volatile("s_waitcnt vmcnt(" #n ")" ::: "memory")
; #define PG8_WAIT_L(n) asm volatile("s_waitcnt lgkmcnt(" #n ")" ::: "memory")
; #define PG8_BAR __builtin_amdgcn_s_barrier()
; #define PG8_SCHED __builtin_amdgcn_sched_barrier(0)
; template <class Epi, class Sched, bool ALIGN_EPI = false, bool SP2 = false>
; __device__ __forceinline__ void gemm_phase(PG8_LAS unsigned char* lds, const Gemm g, const Sched& S, const Epi& E) {
;     ...
;             PG8_WAIT_V(8); PG8_WAIT_L(0); PG8_BAR; PG8_MMA(1, 0, At, B0); PG8_MMA(1, 1, At, B1); PG8_BAR; PG8_SCHED;
;             PG8_LDB(B0, 1, 0); PG8_LDB(B1, 1, 1); PG8_SCHED; PG8_LDA(At, 1, 0); PG8_STAGE(PG8_SA(0, 1), a2 + hstep, voffA);
;             PG8_WAIT_V(8); PG8_WAIT_L(0); PG8_BAR; PG8_MMA(0, 0, At, B0); PG8_MMA(0, 1, At, B1); PG8_BAR; PG8_SCHED;
	s_setprio 1
	v_mfma_f32_16x16x32_bf16 v[60:63], v[128:131], v[160:163], v[60:63]
	v_mfma_f32_16x16x32_bf16 v[56:59], v[136:139], v[160:163], v[56:59]
	v_mfma_f32_16x16x32_bf16 v[44:47], v[128:131], v[168:171], v[44:47]
	v_mfma_f32_16x16x32_bf16 v[40:43], v[136:139], v[168:171], v[40:43]
	v_mfma_f32_16x16x32_bf16 v[28:31], v[128:131], v[188:191], v[28:31]
	v_mfma_f32_16x16x32_bf16 v[24:27], v[136:139], v[188:191], v[24:27]
	v_mfma_f32_16x16x32_bf16 v[12:15], v[128:131], v[196:199], v[12:15]
	v_mfma_f32_16x16x32_bf16 v[8:11], v[136:139], v[196:199], v[8:11]
	v_mfma_f32_16x16x32_bf16 v[60:63], v[132:135], v[164:167], v[60:63]
	v_mfma_f32_16x16x32_bf16 v[56:59], v[140:143], v[164:167], v[56:59]
	v_mfma_f32_16x16x32_bf16 v[44:47], v[132:135], v[172:175], v[44:47]
	v_mfma_f32_16x16x32_bf16 v[40:43], v[140:143], v[172:175], v[40:43]
	v_mfma_f32_16x16x32_bf16 v[28:31], v[132:135], v[192:195], v[28:31]
	v_mfma_f32_16x16x32_bf16 v[24:27], v[140:143], v[192:195], v[24:27]
	v_mfma_f32_16x16x32_bf16 v[12:15], v[132:135], v[200:203], v[12:15]
	v_mfma_f32_16x16x32_bf16 v[8:11], v[140:143], v[200:203], v[8:11]
	s_setprio 0
	s_setprio 1
	v_mfma_f32_16x16x32_bf16 v[52:55], v[144:147], v[160:163], v[52:55]
	v_mfma_f32_16x16x32_bf16 v[48:51], v[152:155], v[160:163], v[48:51]
	v_mfma_f32_16x16x32_bf16 v[36:39], v[144:147], v[168:171], v[36:39]
	v_mfma_f32_16x16x32_bf16 v[32:35], v[152:155], v[168:171], v[32:35]
	v_mfma_f32_16x16x32_bf16 v[20:23], v[144:147], v[188:191], v[20:23]
	v_mfma_f32_16x16x32_bf16 v[16:19], v[152:155], v[188:191], v[16:19]
	v_mfma_f32_16x16x32_bf16 v[4:7], v[144:147], v[196:199], v[4:7]
	v_mfma_f32_16x16x32_bf16 v[0:3], v[152:155], v[196:199], v[0:3]
	v_mfma_f32_16x16x32_bf16 v[52:55], v[148:151], v[164:167], v[52:55]
	v_mfma_f32_16x16x32_bf16 v[48:51], v[156:159], v[164:167], v[48:51]
	v_mfma_f32_16x16x32_bf16 v[36:39], v[148:151], v[172:175], v[36:39]
	v_mfma_f32_16x16x32_bf16 v[32:35], v[156:159], v[172:175], v[32:35]
	v_mfma_f32_16x16x32_bf16 v[20:23], v[148:151], v[192:195], v[20:23]
	v_mfma_f32_16x16x32_bf16 v[16:19], v[156:159], v[192:195], v[16:19]
	v_mfma_f32_16x16x32_bf16 v[4:7], v[148:151], v[200:203], v[4:7]
	v_mfma_f32_16x16x32_bf16 v[0:3], v[156:159], v[200:203], v[0:3]
	s_setprio 0
	s_barrier
	s_add_i32 s57, 0, 0x18000
	s_add_i32 s58, 0, 0x1c000
	v_add_u32_e32 v140, s57, v207
	v_add_u32_e32 v156, s58, v207
	ds_read_b128 v[128:131], v140
	ds_read_b128 v[132:135], v140 offset:1024
	ds_read_b128 v[136:139], v140 offset:2048
	ds_read_b128 v[140:143], v140 offset:3072
	ds_read_b128 v[144:147], v156
	ds_read_b128 v[148:151], v156 offset:1024
	ds_read_b128 v[152:155], v156 offset:2048
	ds_read_b128 v[156:159], v156 offset:3072
	s_add_u32 s24, s24, 0x80000
	s_addc_u32 s25, s25, 0
	s_mov_b32 m0, s37
	v_lshl_add_u64 v[218:219], s[24:25], 0, v[176:177]
	ds_read_b128 v[160:163], v211 offset:32768
	ds_read_b128 v[164:167], v211 offset:33792
	ds_read_b128 v[168:171], v211 offset:34816
	ds_read_b128 v[172:175], v211 offset:35840
	ds_read_b128 v[188:191], v211 offset:36864
	ds_read_b128 v[192:195], v211 offset:37888
	ds_read_b128 v[196:199], v211 offset:38912
	ds_read_b128 v[200:203], v211 offset:39936
	global_load_lds_dwordx4 v[218:219], off
	v_lshl_add_u64 v[218:219], s[24:25], 0, v[178:179]
	s_mov_b32 m0, s39
	s_nop 0
	global_load_lds_dwordx4 v[218:219], off
	s_waitcnt vmcnt(8)
	s_waitcnt lgkmcnt(0)
	s_barrier
	s_setprio 1
	v_mfma_f32_16x16x32_bf16 v[124:127], v[128:131], v[160:163], v[124:127]
	v_mfma_f32_16x16x32_bf16 v[120:123], v[136:139], v[160:163], v[120:123]
	v_mfma_f32_16x16x32_bf16 v[108:111], v[128:131], v[168:171], v[108:111]
	v_mfma_f32_16x16x32_bf16 v[104:107], v[136:139], v[168:171], v[104:107]
	v_mfma_f32_16x16x32_bf16 v[92:95], v[128:131], v[188:191], v[92:95]
	v_mfma_f32_16x16x32_bf16 v[88:91], v[136:139], v[188:191], v[88:91]
	v_mfma_f32_16x16x32_bf16 v[76:79], v[128:131], v[196:199], v[76:79]
	v_mfma_f32_16x16x32_bf16 v[72:75], v[136:139], v[196:199], v[72:75]
	v_mfma_f32_16x16x32_bf16 v[124:127], v[132:135], v[164:167], v[124:127]
	v_mfma_f32_16x16x32_bf16 v[120:123], v[140:143], v[164:167], v[120:123]
	v_mfma_f32_16x16x32_bf16 v[108:111], v[132:135], v[172:175], v[108:111]
	v_mfma_f32_16x16x32_bf16 v[104:107], v[140:143], v[172:175], v[104:107]
	v_mfma_f32_16x16x32_bf16 v[92:95], v[132:135], v[192:195], v[92:95]
	v_mfma_f32_16x16x32_bf16 v[88:91], v[140:143], v[192:195], v[88:91]
	v_mfma_f32_16x16x32_bf16 v[76:79], v[132:135], v[200:203], v[76:79]
	v_mfma_f32_16x16x32_bf16 v[72:75], v[140:143], v[200:203], v[72:75]
	s_setprio 0
	s_setprio 1
	v_mfma_f32_16x16x32_bf16 v[116:119], v[144:147], v[160:163], v[116:119]
	v_mfma_f32_16x16x32_bf16 v[112:115], v[152:155], v[160:163], v[112:115]
	v_mfma_f32_16x16x32_bf16 v[100:103], v[144:147], v[168:171], v[100:103]
	v_mfma_f32_16x16x32_bf16 v[96:99], v[152:155], v[168:171], v[96:99]
	v_mfma_f32_16x16x32_bf16 v[84:87], v[144:147], v[188:191], v[84:87]
	v_mfma_f32_16x16x32_bf16 v[80:83], v[152:155], v[188:191], v[80:83]
	v_mfma_f32_16x16x32_bf16 v[68:71], v[144:147], v[196:199], v[68:71]
	v_mfma_f32_16x16x32_bf16 v[64:67], v[152:155], v[196:199], v[64:67]
	v_mfma_f32_16x16x32_bf16 v[116:119], v[148:151], v[164:167], v[116:119]
	v_mfma_f32_16x16x32_bf16 v[112:115], v[156:159], v[164:167], v[112:115]
	v_mfma_f32_16x16x32_bf16 v[100:103], v[148:151], v[172:175], v[100:103]
	v_mfma_f32_16x16x32_bf16 v[96:99], v[156:159], v[172:175], v[96:99]
	v_mfma_f32_16x16x32_bf16 v[84:87], v[148:151], v[192:195], v[84:87]
	v_mfma_f32_16x16x32_bf16 v[80:83], v[156:159], v[192:195], v[80:83]
	v_mfma_f32_16x16x32_bf16 v[68:71], v[148:151], v[200:203], v[68:71]
	v_mfma_f32_16x16x32_bf16 v[64:67], v[156:159], v[200:203], v[64:67]
	s_setprio 0
	s_barrier
; #define PG8_STAGE(bufoff, gbase, voff) do { _Pragma("unroll") for (int _i = 0; _i < 2; ++_i) \
;         __builtin_amdgcn_global_load_lds((const unsigned*)((const char*)(gbase) + (voff)[_i]), (PG8_LAS unsigned*)(lds + (bufoff) + ldsw + _i * 8192), 16, 0, 0); } while (0)
; #define PG8_LDA(dst, b, h) do { _Pragma("unroll") for (int m = 0; m < 4; ++m) _Pragma("unroll") for (int k = 0; k < 2; ++k) dst[m][k] = *(const PG8_LAS bf16x8*)(lds + PG8_SA(b, h) + aoff + m * 2048 + k * 1024); } while (0)
; #define PG8_MMA(ai, bj, At, Bt) do { __builtin_amdgcn_s_setprio(1); _Pragma("unroll") for (int m = 0; m < 4; ++m) _Pragma("unroll") for (int n = 0; n < 2; ++n) _Pragma("unroll") for (int k = 0; k < 2; ++k) \
;         acc[ai][bj][m][n] = __builtin_amdgcn_mfma_f32_16x16x32_bf16(Bt[n][k], At[m][k], acc[ai][bj][m][n], 0, 0, 0); __builtin_amdgcn_s_setprio(0); } while (0)
; #define PG8_WAIT_V(n) asm volatile("s_waitcnt vmcnt(" #n ")" ::: "memory")
; #define PG8_WAIT_L(n) asm volatile("s_waitcnt lgkmcnt(" #n ")" ::: "memory")
; #define PG8_BAR __builtin_amdgcn_s_barrier()
; #define PG8_SCHED __builtin_amdgcn_sched_barrier(0)
; template <class Epi, class Sched, bool ALIGN_EPI = false, bool SP2 = false>
; __device__ __forceinline__ void gemm_phase(PG8_LAS unsigned char* lds, const Gemm g, const Sched& S, const Epi& E) {
;     ...
;             PG8_LDA(At, 1, 1); PG8_STAGE(PG8_SB(1, 0), b3, voffB); PG8_STAGE(PG8_SB(1, 1), b3 + hstep, voffB); PG8_STAGE(PG8_SA(1, 0), a3, voffA);
;             PG8_WAIT_V(8); PG8_WAIT_L(0); PG8_BAR; PG8_MMA(1, 0, At, B0); PG8_MMA(1, 1, At, B1); PG8_BAR; PG8_SCHED;
;     ...
;         if constexpr (ALIGN_EPI) { if (wr == 0) PG8_BAR; }
	s_add_i32 s24, s57, s3
	v_lshl_add_u64 v[204:205], v[204:205], 0, s[16:17]
	s_mov_b32 m0, s24
	ds_read_b128 v[160:163], v211 offset:49152
	ds_read_b128 v[164:167], v211 offset:50176
	ds_read_b128 v[168:171], v211 offset:51200
	ds_read_b128 v[172:175], v211 offset:52224
	ds_read_b128 v[188:191], v211 offset:53248
	ds_read_b128 v[192:195], v211 offset:54272
	ds_read_b128 v[196:199], v211 offset:55296
	ds_read_b128 v[200:203], v211 offset:56320
	global_load_lds_dwordx4 v[204:205], off
	s_add_i32 m0, s24, 0x2000
	s_add_u32 s0, s0, 0x80080
	v_lshl_add_u64 v[204:205], v[212:213], 0, s[16:17]
	s_addc_u32 s1, s1, 0
	s_add_i32 s24, s58, s3
	global_load_lds_dwordx4 v[204:205], off
	v_lshl_add_u64 v[204:205], s[0:1], 0, v[176:177]
	s_mov_b32 m0, s24
	s_nop 0
	global_load_lds_dwordx4 v[204:205], off
	v_lshl_add_u64 v[204:205], s[0:1], 0, v[178:179]
	s_add_i32 m0, s24, 0x2000
	s_nop 0
	global_load_lds_dwordx4 v[204:205], off
	v_lshl_add_u64 v[204:205], v[214:215], 0, s[16:17]
	s_mov_b32 m0, s43
	s_nop 0
	global_load_lds_dwordx4 v[204:205], off
	v_lshl_add_u64 v[204:205], v[216:217], 0, s[16:17]
	s_mov_b32 m0, s44
	s_nop 0
	global_load_lds_dwordx4 v[204:205], off
	s_waitcnt vmcnt(8)
	s_waitcnt lgkmcnt(0)
	s_barrier
	s_setprio 1
	v_mfma_f32_16x16x32_bf16 v[60:63], v[128:131], v[160:163], v[60:63]
	v_mfma_f32_16x16x32_bf16 v[56:59], v[136:139], v[160:163], v[56:59]
	v_mfma_f32_16x16x32_bf16 v[44:47], v[128:131], v[168:171], v[44:47]
	v_mfma_f32_16x16x32_bf16 v[40:43], v[136:139], v[168:171], v[40:43]
	v_mfma_f32_16x16x32_bf16 v[28:31], v[128:131], v[188:191], v[28:31]
	v_mfma_f32_16x16x32_bf16 v[24:27], v[136:139], v[188:191], v[24:27]
	v_mfma_f32_16x16x32_bf16 v[12:15], v[128:131], v[196:199], v[12:15]
	v_mfma_f32_16x16x32_bf16 v[8:11], v[136:139], v[196:199], v[8:11]
	v_mfma_f32_16x16x32_bf16 v[60:63], v[132:135], v[164:167], v[60:63]
	v_mfma_f32_16x16x32_bf16 v[56:59], v[140:143], v[164:167], v[56:59]
	v_mfma_f32_16x16x32_bf16 v[44:47], v[132:135], v[172:175], v[44:47]
	v_mfma_f32_16x16x32_bf16 v[40:43], v[140:143], v[172:175], v[40:43]
	v_mfma_f32_16x16x32_bf16 v[28:31], v[132:135], v[192:195], v[28:31]
	v_mfma_f32_16x16x32_bf16 v[24:27], v[140:143], v[192:195], v[24:27]
	v_mfma_f32_16x16x32_bf16 v[12:15], v[132:135], v[200:203], v[12:15]
	v_mfma_f32_16x16x32_bf16 v[8:11], v[140:143], v[200:203], v[8:11]
	s_setprio 0
	s_setprio 1
	v_mfma_f32_16x16x32_bf16 v[52:55], v[144:147], v[160:163], v[52:55]
	v_mfma_f32_16x16x32_bf16 v[48:51], v[152:155], v[160:163], v[48:51]
	v_mfma_f32_16x16x32_bf16 v[36:39], v[144:147], v[168:171], v[36:39]
	v_mfma_f32_16x16x32_bf16 v[32:35], v[152:155], v[168:171], v[32:35]
	v_mfma_f32_16x16x32_bf16 v[20:23], v[144:147], v[188:191], v[20:23]
	v_mfma_f32_16x16x32_bf16 v[16:19], v[152:155], v[188:191], v[16:19]
	v_mfma_f32_16x16x32_bf16 v[4:7], v[144:147], v[196:199], v[4:7]
	v_mfma_f32_16x16x32_bf16 v[0:3], v[152:155], v[196:199], v[0:3]
	v_mfma_f32_16x16x32_bf16 v[52:55], v[148:151], v[164:167], v[52:55]
	v_mfma_f32_16x16x32_bf16 v[48:51], v[156:159], v[164:167], v[48:51]
	v_mfma_f32_16x16x32_bf16 v[36:39], v[148:151], v[172:175], v[36:39]
	v_mfma_f32_16x16x32_bf16 v[32:35], v[156:159], v[172:175], v[32:35]
	v_mfma_f32_16x16x32_bf16 v[20:23], v[148:151], v[192:195], v[20:23]
	v_mfma_f32_16x16x32_bf16 v[16:19], v[156:159], v[192:195], v[16:19]
	v_mfma_f32_16x16x32_bf16 v[4:7], v[148:151], v[200:203], v[4:7]
	v_mfma_f32_16x16x32_bf16 v[0:3], v[156:159], v[200:203], v[0:3]
	s_setprio 0
	s_barrier
	s_add_i32 s56, s56, 2
	s_add_u32 s40, s40, 0x100
	s_addc_u32 s41, s41, 0
	s_add_u32 s54, s54, 0x100
	s_addc_u32 s55, s55, 0
	s_cmp_gt_u32 s56, 29
	s_cbranch_scc0 .LBB0_1798
	s_and_b64 vcc, exec, s[18:19]
	s_cbranch_vccz .LBB0_1801
	s_barrier

; #define PG8_STAGE(bufoff, gbase, voff) do { _Pragma("unroll") for (int _i = 0; _i < 2; ++_i) \
;         __builtin_amdgcn_global_load_lds((const unsigned*)((const char*)(gbase) + (voff)[_i]), (PG8_LAS unsigned*)(lds + (bufoff) + ldsw + _i * 8192), 16, 0, 0); } while (0)
; #define PG8_LDA(dst, b, h) do { _Pragma("unroll") for (int m = 0; m < 4; ++m) _Pragma("unroll") for (int k = 0; k < 2; ++k) dst[m][k] = *(const PG8_LAS bf16x8*)(lds + PG8_SA(b, h) + aoff + m * 2048 + k * 1024); } while (0)
; #define PG8_LDB(dst, b, h) do { _Pragma("unroll") for (int n = 0; n < 2; ++n) _Pragma("unroll") for (int k = 0; k < 2; ++k) dst[n][k] = *(const PG8_LAS bf16x8*)(lds + PG8_SB(b, h) + boff + n * 2048 + k * 1024); } while (0)
; #define PG8_MMA(ai, bj, At, Bt) do { __builtin_amdgcn_s_setprio(1); _Pragma("unroll") for (int m = 0; m < 4; ++m) _Pragma("unroll") for (int n = 0; n < 2; ++n) _Pragma("unroll") for (int k = 0; k < 2; ++k) \
;         acc[ai][bj][m][n] = __builtin_amdgcn_mfma_f32_16x16x32_bf16(Bt[n][k], At[m][k], acc[ai][bj][m][n], 0, 0, 0); __builtin_amdgcn_s_setprio(0); } while (0)
; #define PG8_WAIT_V(n) asm volatile("s_waitcnt vmcnt(" #n ")" ::: "memory")
; #define PG8_WAIT_L(n) asm volatile("s_waitcnt lgkmcnt(" #n ")" ::: "memory")
; #define PG8_BAR __builtin_amdgcn_s_barrier()
; #define PG8_SCHED __builtin_amdgcn_sched_barrier(0)
; template <class Epi, class Sched, bool ALIGN_EPI = false, bool SP2 = false>
; __device__ __forceinline__ void gemm_phase(PG8_LAS unsigned char* lds, const Gemm g, const Sched& S, const Epi& E) {
;     ...
;         for (int t = 0; t < nt; t += 2) {
;             const bool last = (t == nt - 2);
;             const char* a1 = cA + (size_t)(t + 1) * kstep;
;             const char* a2 = last ? nA : cA + (size_t)(t + 2) * kstep; const char* b2 = last ? nB : cB + (size_t)(t + 2) * kstep;
;             const char* a3 = a2 + kstep; const char* b3 = b2 + kstep;
;             if (last && has_next) S.a_ready(nxt);
;             if constexpr (SP2) {
;             PG8_LDB(B0, 0, 0); PG8_LDB(B1, 0, 1); PG8_SCHED; PG8_LDA(At, 0, 0); PG8_STAGE(PG8_SA(1, 1), a1 + hstep, voffA);
;             PG8_WAIT_V(8); PG8_WAIT_L(0); PG8_BAR; PG8_MMA(0, 0, At, B0); PG8_MMA(0, 1, At, B1); PG8_BAR; PG8_SCHED;
;             PG8_LDA(At, 0, 1); PG8_STAGE(PG8_SB(0, 0), b2, voffB); PG8_STAGE(PG8_SB(0, 1), b2 + hstep, voffB); PG8_STAGE(PG8_SA(0, 0), a2, voffA);
.LBB0_1882:
	ds_read_b128 v[144:147], v155
	ds_read_b128 v[148:151], v155 offset:1024
	ds_read_b128 v[160:163], v155 offset:2048
	ds_read_b128 v[164:167], v155 offset:3072
	ds_read_b128 v[168:171], v156
	ds_read_b128 v[172:175], v156 offset:1024
	ds_read_b128 v[176:179], v156 offset:2048
	ds_read_b128 v[180:183], v156 offset:3072
	s_add_u32 s0, s30, 0xfff80080
	s_addc_u32 s1, s31, -1
	s_cmp_eq_u32 s55, 28
	s_cselect_b32 s25, s21, s1
	s_cselect_b32 s24, s51, s0
	s_cselect_b32 s1, s19, s54
	s_cselect_b32 s0, s52, s53
	v_lshl_add_u64 v[216:217], s[30:31], 0, v[136:137]
	s_add_i32 m0, s36, 0xc000
	ds_read_b128 v[184:187], v157
	ds_read_b128 v[188:191], v157 offset:1024
	ds_read_b128 v[192:195], v157 offset:2048
	ds_read_b128 v[196:199], v157 offset:3072
	ds_read_b128 v[200:203], v157 offset:4096
	ds_read_b128 v[204:207], v157 offset:5120
	ds_read_b128 v[208:211], v157 offset:6144
	ds_read_b128 v[212:215], v157 offset:7168
	global_load_lds_dwordx4 v[216:217], off
	v_lshl_add_u64 v[216:217], s[30:31], 0, v[138:139]
	s_add_i32 m0, s36, 0xe000
	s_nop 0
	global_load_lds_dwordx4 v[216:217], off
	s_waitcnt vmcnt(8)
	s_waitcnt lgkmcnt(0)
	s_barrier
	s_setprio 1
	v_mfma_f32_16x16x32_bf16 v[124:127], v[144:147], v[184:187], v[124:127]
	v_mfma_f32_16x16x32_bf16 v[120:123], v[160:163], v[184:187], v[120:123]
	v_mfma_f32_16x16x32_bf16 v[108:111], v[144:147], v[192:195], v[108:111]
	v_mfma_f32_16x16x32_bf16 v[104:107], v[160:163], v[192:195], v[104:107]
	v_mfma_f32_16x16x32_bf16 v[92:95], v[144:147], v[200:203], v[92:95]
	v_mfma_f32_16x16x32_bf16 v[88:91], v[160:163], v[200:203], v[88:91]
	v_mfma_f32_16x16x32_bf16 v[76:79], v[144:147], v[208:211], v[76:79]
	v_mfma_f32_16x16x32_bf16 v[72:75], v[160:163], v[208:211], v[72:75]
	v_mfma_f32_16x16x32_bf16 v[124:127], v[148:151], v[188:191], v[124:127]
	v_mfma_f32_16x16x32_bf16 v[120:123], v[164:167], v[188:191], v[120:123]
	v_mfma_f32_16x16x32_bf16 v[108:111], v[148:151], v[196:199], v[108:111]
	v_mfma_f32_16x16x32_bf16 v[104:107], v[164:167], v[196:199], v[104:107]
	v_mfma_f32_16x16x32_bf16 v[92:95], v[148:151], v[204:207], v[92:95]
	v_mfma_f32_16x16x32_bf16 v[88:91], v[164:167], v[204:207], v[88:91]
	v_mfma_f32_16x16x32_bf16 v[76:79], v[148:151], v[212:215], v[76:79]
	v_mfma_f32_16x16x32_bf16 v[72:75], v[164:167], v[212:215], v[72:75]
	s_setprio 0
	s_setprio 1
	v_mfma_f32_16x16x32_bf16 v[116:119], v[168:171], v[184:187], v[116:119]
	v_mfma_f32_16x16x32_bf16 v[112:115], v[176:179], v[184:187], v[112:115]
	v_mfma_f32_16x16x32_bf16 v[100:103], v[168:171], v[192:195], v[100:103]
	v_mfma_f32_16x16x32_bf16 v[96:99], v[176:179], v[192:195], v[96:99]
	v_mfma_f32_16x16x32_bf16 v[84:87], v[168:171], v[200:203], v[84:87]
	v_mfma_f32_16x16x32_bf16 v[80:83], v[176:179], v[200:203], v[80:83]
	v_mfma_f32_16x16x32_bf16 v[68:71], v[168:171], v[208:211], v[68:71]
	v_mfma_f32_16x16x32_bf16 v[64:67], v[176:179], v[208:211], v[64:67]
	v_mfma_f32_16x16x32_bf16 v[116:119], v[172:175], v[188:191], v[116:119]
	v_mfma_f32_16x16x32_bf16 v[112:115], v[180:183], v[188:191], v[112:115]
	v_mfma_f32_16x16x32_bf16 v[100:103], v[172:175], v[196:199], v[100:103]
	v_mfma_f32_16x16x32_bf16 v[96:99], v[180:183], v[196:199], v[96:99]
	v_mfma_f32_16x16x32_bf16 v[84:87], v[172:175], v[204:207], v[84:87]
	v_mfma_f32_16x16x32_bf16 v[80:83], v[180:183], v[204:207], v[80:83]
	v_mfma_f32_16x16x32_bf16 v[68:71], v[172:175], v[212:215], v[68:71]
	v_mfma_f32_16x16x32_bf16 v[64:67], v[180:183], v[212:215], v[64:67]
	s_setprio 0
	s_barrier
	s_add_i32 s56, s45, s3
	v_lshl_add_u64 v[216:217], s[0:1], 0, v[132:133]
	s_mov_b32 m0, s56
	ds_read_b128 v[184:187], v157 offset:16384
	ds_read_b128 v[188:191], v157 offset:17408
	ds_read_b128 v[192:195], v157 offset:18432
	ds_read_b128 v[196:199], v157 offset:19456
	ds_read_b128 v[200:203], v157 offset:20480
	ds_read_b128 v[204:207], v157 offset:21504
	ds_read_b128 v[208:211], v157 offset:22528
	ds_read_b128 v[212:215], v157 offset:23552
	global_load_lds_dwordx4 v[216:217], off
	s_add_i32 m0, s56, 0x2000
	s_add_u32 s56, s0, 0x80000
	v_lshl_add_u64 v[218:219], s[0:1], 0, v[128:129]
	s_addc_u32 s57, s1, 0
	s_add_i32 s58, s46, s3
	global_load_lds_dwordx4 v[218:219], off
	v_lshl_add_u64 v[220:221], s[56:57], 0, v[132:133]
	s_mov_b32 m0, s58
	v_lshl_add_u64 v[224:225], s[24:25], 0, v[130:131]
	global_load_lds_dwordx4 v[220:221], off
	v_lshl_add_u64 v[220:221], s[56:57], 0, v[128:129]
	s_add_i32 m0, s58, 0x2000
	s_nop 0
	global_load_lds_dwordx4 v[220:221], off
	v_lshl_add_u64 v[220:221], s[24:25], 0, v[134:135]
	s_mov_b32 m0, s36
	s_nop 0
	global_load_lds_dwordx4 v[220:221], off
	s_mov_b32 m0, s37
	s_nop 0
	global_load_lds_dwordx4 v[224:225], off
	s_waitcnt vmcnt(8)
	s_waitcnt lgkmcnt(0)
	s_barrier
; #define PG8_STAGE(bufoff, gbase, voff) do { _Pragma("unroll") for (int _i = 0; _i < 2; ++_i) \
;         __builtin_amdgcn_global_load_lds((const unsigned*)((const char*)(gbase) + (voff)[_i]), (PG8_LAS unsigned*)(lds + (bufoff) + ldsw + _i * 8192), 16, 0, 0); } while (0)
; #define PG8_LDA(dst, b, h) do { _Pragma("unroll") for (int m = 0; m < 4; ++m) _Pragma("unroll") for (int k = 0; k < 2; ++k) dst[m][k] = *(const PG8_LAS bf16x8*)(lds + PG8_SA(b, h) + aoff + m * 2048 + k * 1024); } while (0)
; #define PG8_LDB(dst, b, h) do { _Pragma("unroll") for (int n = 0; n < 2; ++n) _Pragma("unroll") for (int k = 0; k < 2; ++k) dst[n][k] = *(const PG8_LAS bf16x8*)(lds + PG8_SB(b, h) + boff + n * 2048 + k * 1024); } while (0)
; #define PG8_MMA(ai, bj, At, Bt) do { __builtin_amdgcn_s_setprio(1); _Pragma("unroll") for (int m = 0; m < 4; ++m) _Pragma("unroll") for (int n = 0; n < 2; ++n) _Pragma("unroll") for (int k = 0; k < 2; ++k) \
;         acc[ai][bj][m][n] = __builtin_amdgcn_mfma_f32_16x16x32_bf16(Bt[n][k], At[m][k], acc[ai][bj][m][n], 0, 0, 0); __builtin_amdgcn_s_setprio(0); } while (0)
; #define PG8_WAIT_V(n) asm volatile("s_waitcnt vmcnt(" #n ")" ::: "memory")
; #define PG8_WAIT_L(n) asm volatile("s_waitcnt lgkmcnt(" #n ")" ::: "memory")
; #define PG8_BAR __builtin_amdgcn_s_barrier()
; #define PG8_SCHED __builtin_amdgcn_sched_barrier(0)
; template <class Epi, class Sched, bool ALIGN_EPI = false, bool SP2 = false>
; __device__ __forceinline__ void gemm_phase(PG8_LAS unsigned char* lds, const Gemm g, const Sched& S, const Epi& E) {
;     ...
;             PG8_WAIT_V(8); PG8_WAIT_L(0); PG8_BAR; PG8_MMA(1, 0, At, B0); PG8_MMA(1, 1, At, B1); PG8_BAR; PG8_SCHED;
;             PG8_LDB(B0, 1, 0); PG8_LDB(B1, 1, 1); PG8_SCHED; PG8_LDA(At, 1, 0); PG8_STAGE(PG8_SA(0, 1), a2 + hstep, voffA);
;             PG8_WAIT_V(8); PG8_WAIT_L(0); PG8_BAR; PG8_MMA(0, 0, At, B0); PG8_MMA(0, 1, At, B1); PG8_BAR; PG8_SCHED;
	s_setprio 1
	v_mfma_f32_16x16x32_bf16 v[60:63], v[144:147], v[184:187], v[60:63]
	v_mfma_f32_16x16x32_bf16 v[56:59], v[160:163], v[184:187], v[56:59]
	v_mfma_f32_16x16x32_bf16 v[44:47], v[144:147], v[192:195], v[44:47]
	v_mfma_f32_16x16x32_bf16 v[40:43], v[160:163], v[192:195], v[40:43]
	v_mfma_f32_16x16x32_bf16 v[28:31], v[144:147], v[200:203], v[28:31]
	v_mfma_f32_16x16x32_bf16 v[24:27], v[160:163], v[200:203], v[24:27]
	v_mfma_f32_16x16x32_bf16 v[12:15], v[144:147], v[208:211], v[12:15]
	v_mfma_f32_16x16x32_bf16 v[8:11], v[160:163], v[208:211], v[8:11]
	v_mfma_f32_16x16x32_bf16 v[60:63], v[148:151], v[188:191], v[60:63]
	v_mfma_f32_16x16x32_bf16 v[56:59], v[164:167], v[188:191], v[56:59]
	v_mfma_f32_16x16x32_bf16 v[44:47], v[148:151], v[196:199], v[44:47]
	v_mfma_f32_16x16x32_bf16 v[40:43], v[164:167], v[196:199], v[40:43]
	v_mfma_f32_16x16x32_bf16 v[28:31], v[148:151], v[204:207], v[28:31]
	v_mfma_f32_16x16x32_bf16 v[24:27], v[164:167], v[204:207], v[24:27]
	v_mfma_f32_16x16x32_bf16 v[12:15], v[148:151], v[212:215], v[12:15]
	v_mfma_f32_16x16x32_bf16 v[8:11], v[164:167], v[212:215], v[8:11]
	s_setprio 0
	s_setprio 1
	v_mfma_f32_16x16x32_bf16 v[52:55], v[168:171], v[184:187], v[52:55]
	v_mfma_f32_16x16x32_bf16 v[48:51], v[176:179], v[184:187], v[48:51]
	v_mfma_f32_16x16x32_bf16 v[36:39], v[168:171], v[192:195], v[36:39]
	v_mfma_f32_16x16x32_bf16 v[32:35], v[176:179], v[192:195], v[32:35]
	v_mfma_f32_16x16x32_bf16 v[20:23], v[168:171], v[200:203], v[20:23]
	v_mfma_f32_16x16x32_bf16 v[16:19], v[176:179], v[200:203], v[16:19]
	v_mfma_f32_16x16x32_bf16 v[4:7], v[168:171], v[208:211], v[4:7]
	v_mfma_f32_16x16x32_bf16 v[0:3], v[176:179], v[208:211], v[0:3]
	v_mfma_f32_16x16x32_bf16 v[52:55], v[172:175], v[188:191], v[52:55]
	v_mfma_f32_16x16x32_bf16 v[48:51], v[180:183], v[188:191], v[48:51]
	v_mfma_f32_16x16x32_bf16 v[36:39], v[172:175], v[196:199], v[36:39]
	v_mfma_f32_16x16x32_bf16 v[32:35], v[180:183], v[196:199], v[32:35]
	v_mfma_f32_16x16x32_bf16 v[20:23], v[172:175], v[204:207], v[20:23]
	v_mfma_f32_16x16x32_bf16 v[16:19], v[180:183], v[204:207], v[16:19]
	v_mfma_f32_16x16x32_bf16 v[4:7], v[172:175], v[212:215], v[4:7]
	v_mfma_f32_16x16x32_bf16 v[0:3], v[180:183], v[212:215], v[0:3]
	s_setprio 0
	s_barrier
	s_add_i32 s56, 0, 0x18000
	s_add_i32 s57, 0, 0x1c000
	v_add_u32_e32 v164, s56, v153
	v_add_u32_e32 v180, s57, v153
	ds_read_b128 v[144:147], v164
	ds_read_b128 v[148:151], v164 offset:1024
	ds_read_b128 v[160:163], v164 offset:2048
	ds_read_b128 v[164:167], v164 offset:3072
	ds_read_b128 v[168:171], v180
	ds_read_b128 v[172:175], v180 offset:1024
	ds_read_b128 v[176:179], v180 offset:2048
	ds_read_b128 v[180:183], v180 offset:3072
	s_add_u32 s24, s24, 0x80000
	s_addc_u32 s25, s25, 0
	s_mov_b32 m0, s38
	v_lshl_add_u64 v[228:229], s[24:25], 0, v[134:135]
	ds_read_b128 v[184:187], v157 offset:32768
	ds_read_b128 v[188:191], v157 offset:33792
	ds_read_b128 v[192:195], v157 offset:34816
	ds_read_b128 v[196:199], v157 offset:35840
	ds_read_b128 v[200:203], v157 offset:36864
	ds_read_b128 v[204:207], v157 offset:37888
	ds_read_b128 v[208:211], v157 offset:38912
	ds_read_b128 v[212:215], v157 offset:39936
	global_load_lds_dwordx4 v[228:229], off
	v_lshl_add_u64 v[228:229], s[24:25], 0, v[130:131]
	s_mov_b32 m0, s39
	s_nop 0
	global_load_lds_dwordx4 v[228:229], off
	s_waitcnt vmcnt(8)
	s_waitcnt lgkmcnt(0)
	s_barrier
	s_setprio 1
	v_mfma_f32_16x16x32_bf16 v[124:127], v[144:147], v[184:187], v[124:127]
	v_mfma_f32_16x16x32_bf16 v[120:123], v[160:163], v[184:187], v[120:123]
	v_mfma_f32_16x16x32_bf16 v[108:111], v[144:147], v[192:195], v[108:111]
	v_mfma_f32_16x16x32_bf16 v[104:107], v[160:163], v[192:195], v[104:107]
	v_mfma_f32_16x16x32_bf16 v[92:95], v[144:147], v[200:203], v[92:95]
	v_mfma_f32_16x16x32_bf16 v[88:91], v[160:163], v[200:203], v[88:91]
	v_mfma_f32_16x16x32_bf16 v[76:79], v[144:147], v[208:211], v[76:79]
	v_mfma_f32_16x16x32_bf16 v[72:75], v[160:163], v[208:211], v[72:75]
	v_mfma_f32_16x16x32_bf16 v[124:127], v[148:151], v[188:191], v[124:127]
	v_mfma_f32_16x16x32_bf16 v[120:123], v[164:167], v[188:191], v[120:123]
	v_mfma_f32_16x16x32_bf16 v[108:111], v[148:151], v[196:199], v[108:111]
	v_mfma_f32_16x16x32_bf16 v[104:107], v[164:167], v[196:199], v[104:107]
	v_mfma_f32_16x16x32_bf16 v[92:95], v[148:151], v[204:207], v[92:95]
	v_mfma_f32_16x16x32_bf16 v[88:91], v[164:167], v[204:207], v[88:91]
	v_mfma_f32_16x16x32_bf16 v[76:79], v[148:151], v[212:215], v[76:79]
	v_mfma_f32_16x16x32_bf16 v[72:75], v[164:167], v[212:215], v[72:75]
	s_setprio 0
	s_setprio 1
	v_mfma_f32_16x16x32_bf16 v[116:119], v[168:171], v[184:187], v[116:119]
	v_mfma_f32_16x16x32_bf16 v[112:115], v[176:179], v[184:187], v[112:115]
	v_mfma_f32_16x16x32_bf16 v[100:103], v[168:171], v[192:195], v[100:103]
	v_mfma_f32_16x16x32_bf16 v[96:99], v[176:179], v[192:195], v[96:99]
	v_mfma_f32_16x16x32_bf16 v[84:87], v[168:171], v[200:203], v[84:87]
	v_mfma_f32_16x16x32_bf16 v[80:83], v[176:179], v[200:203], v[80:83]
	v_mfma_f32_16x16x32_bf16 v[68:71], v[168:171], v[208:211], v[68:71]
	v_mfma_f32_16x16x32_bf16 v[64:67], v[176:179], v[208:211], v[64:67]
	v_mfma_f32_16x16x32_bf16 v[116:119], v[172:175], v[188:191], v[116:119]
	v_mfma_f32_16x16x32_bf16 v[112:115], v[180:183], v[188:191], v[112:115]
	v_mfma_f32_16x16x32_bf16 v[100:103], v[172:175], v[196:199], v[100:103]
	v_mfma_f32_16x16x32_bf16 v[96:99], v[180:183], v[196:199], v[96:99]
	v_mfma_f32_16x16x32_bf16 v[84:87], v[172:175], v[204:207], v[84:87]
	v_mfma_f32_16x16x32_bf16 v[80:83], v[180:183], v[204:207], v[80:83]
	v_mfma_f32_16x16x32_bf16 v[68:71], v[172:175], v[212:215], v[68:71]
	v_mfma_f32_16x16x32_bf16 v[64:67], v[180:183], v[212:215], v[64:67]
	s_setprio 0
	s_barrier
; #define PG8_STAGE(bufoff, gbase, voff) do { _Pragma("unroll") for (int _i = 0; _i < 2; ++_i) \
;         __builtin_amdgcn_global_load_lds((const unsigned*)((const char*)(gbase) + (voff)[_i]), (PG8_LAS unsigned*)(lds + (bufoff) + ldsw + _i * 8192), 16, 0, 0); } while (0)
; #define PG8_LDA(dst, b, h) do { _Pragma("unroll") for (int m = 0; m < 4; ++m) _Pragma("unroll") for (int k = 0; k < 2; ++k) dst[m][k] = *(const PG8_LAS bf16x8*)(lds + PG8_SA(b, h) + aoff + m * 2048 + k * 1024); } while (0)
; #define PG8_MMA(ai, bj, At, Bt) do { __builtin_amdgcn_s_setprio(1); _Pragma("unroll") for (int m = 0; m < 4; ++m) _Pragma("unroll") for (int n = 0; n < 2; ++n) _Pragma("unroll") for (int k = 0; k < 2; ++k) \
;         acc[ai][bj][m][n] = __builtin_amdgcn_mfma_f32_16x16x32_bf16(Bt[n][k], At[m][k], acc[ai][bj][m][n], 0, 0, 0); __builtin_amdgcn_s_setprio(0); } while (0)
; #define PG8_WAIT_V(n) asm volatile("s_waitcnt vmcnt(" #n ")" ::: "memory")
; #define PG8_WAIT_L(n) asm volatile("s_waitcnt lgkmcnt(" #n ")" ::: "memory")
; #define PG8_BAR __builtin_amdgcn_s_barrier()
; #define PG8_SCHED __builtin_amdgcn_sched_barrier(0)
; template <class Epi, class Sched, bool ALIGN_EPI = false, bool SP2 = false>
; __device__ __forceinline__ void gemm_phase(PG8_LAS unsigned char* lds, const Gemm g, const Sched& S, const Epi& E) {
;     ...
;             PG8_LDA(At, 1, 1); PG8_STAGE(PG8_SB(1, 0), b3, voffB); PG8_STAGE(PG8_SB(1, 1), b3 + hstep, voffB); PG8_STAGE(PG8_SA(1, 0), a3, voffA);
;             PG8_WAIT_V(8); PG8_WAIT_L(0); PG8_BAR; PG8_MMA(1, 0, At, B0); PG8_MMA(1, 1, At, B1); PG8_BAR; PG8_SCHED;
;     ...
;         if constexpr (ALIGN_EPI) { if (wr == 0) PG8_BAR; }
	s_add_i32 s24, s56, s3
	v_lshl_add_u64 v[216:217], v[216:217], 0, s[14:15]
	s_mov_b32 m0, s24
	ds_read_b128 v[184:187], v157 offset:49152
	ds_read_b128 v[188:191], v157 offset:50176
	ds_read_b128 v[192:195], v157 offset:51200
	ds_read_b128 v[196:199], v157 offset:52224
	ds_read_b128 v[200:203], v157 offset:53248
	ds_read_b128 v[204:207], v157 offset:54272
	ds_read_b128 v[208:211], v157 offset:55296
	ds_read_b128 v[212:215], v157 offset:56320
	global_load_lds_dwordx4 v[216:217], off
	s_add_i32 m0, s24, 0x2000
	s_add_u32 s0, s0, 0x80080
	v_lshl_add_u64 v[216:217], v[218:219], 0, s[14:15]
	s_addc_u32 s1, s1, 0
	s_add_i32 s24, s57, s3
	global_load_lds_dwordx4 v[216:217], off
	v_lshl_add_u64 v[216:217], s[0:1], 0, v[132:133]
	s_mov_b32 m0, s24
	s_nop 0
	global_load_lds_dwordx4 v[216:217], off
	v_lshl_add_u64 v[216:217], s[0:1], 0, v[128:129]
	s_add_i32 m0, s24, 0x2000
	s_nop 0
	global_load_lds_dwordx4 v[216:217], off
	v_lshl_add_u64 v[216:217], v[220:221], 0, s[14:15]
	s_mov_b32 m0, s41
	s_nop 0
	global_load_lds_dwordx4 v[216:217], off
	v_lshl_add_u64 v[216:217], v[224:225], 0, s[14:15]
	s_mov_b32 m0, s42
	s_nop 0
	global_load_lds_dwordx4 v[216:217], off
	s_waitcnt vmcnt(8)
	s_waitcnt lgkmcnt(0)
	s_barrier
	s_setprio 1
	v_mfma_f32_16x16x32_bf16 v[60:63], v[144:147], v[184:187], v[60:63]
	v_mfma_f32_16x16x32_bf16 v[56:59], v[160:163], v[184:187], v[56:59]
	v_mfma_f32_16x16x32_bf16 v[44:47], v[144:147], v[192:195], v[44:47]
	v_mfma_f32_16x16x32_bf16 v[40:43], v[160:163], v[192:195], v[40:43]
	v_mfma_f32_16x16x32_bf16 v[28:31], v[144:147], v[200:203], v[28:31]
	v_mfma_f32_16x16x32_bf16 v[24:27], v[160:163], v[200:203], v[24:27]
	v_mfma_f32_16x16x32_bf16 v[12:15], v[144:147], v[208:211], v[12:15]
	v_mfma_f32_16x16x32_bf16 v[8:11], v[160:163], v[208:211], v[8:11]
	v_mfma_f32_16x16x32_bf16 v[60:63], v[148:151], v[188:191], v[60:63]
	v_mfma_f32_16x16x32_bf16 v[56:59], v[164:167], v[188:191], v[56:59]
	v_mfma_f32_16x16x32_bf16 v[44:47], v[148:151], v[196:199], v[44:47]
	v_mfma_f32_16x16x32_bf16 v[40:43], v[164:167], v[196:199], v[40:43]
	v_mfma_f32_16x16x32_bf16 v[28:31], v[148:151], v[204:207], v[28:31]
	v_mfma_f32_16x16x32_bf16 v[24:27], v[164:167], v[204:207], v[24:27]
	v_mfma_f32_16x16x32_bf16 v[12:15], v[148:151], v[212:215], v[12:15]
	v_mfma_f32_16x16x32_bf16 v[8:11], v[164:167], v[212:215], v[8:11]
	s_setprio 0
	s_setprio 1
	v_mfma_f32_16x16x32_bf16 v[52:55], v[168:171], v[184:187], v[52:55]
	v_mfma_f32_16x16x32_bf16 v[48:51], v[176:179], v[184:187], v[48:51]
	v_mfma_f32_16x16x32_bf16 v[36:39], v[168:171], v[192:195], v[36:39]
	v_mfma_f32_16x16x32_bf16 v[32:35], v[176:179], v[192:195], v[32:35]
	v_mfma_f32_16x16x32_bf16 v[20:23], v[168:171], v[200:203], v[20:23]
	v_mfma_f32_16x16x32_bf16 v[16:19], v[176:179], v[200:203], v[16:19]
	v_mfma_f32_16x16x32_bf16 v[4:7], v[168:171], v[208:211], v[4:7]
	v_mfma_f32_16x16x32_bf16 v[0:3], v[176:179], v[208:211], v[0:3]
	v_mfma_f32_16x16x32_bf16 v[52:55], v[172:175], v[188:191], v[52:55]
	v_mfma_f32_16x16x32_bf16 v[48:51], v[180:183], v[188:191], v[48:51]
	v_mfma_f32_16x16x32_bf16 v[36:39], v[172:175], v[196:199], v[36:39]
	v_mfma_f32_16x16x32_bf16 v[32:35], v[180:183], v[196:199], v[32:35]
	v_mfma_f32_16x16x32_bf16 v[20:23], v[172:175], v[204:207], v[20:23]
	v_mfma_f32_16x16x32_bf16 v[16:19], v[180:183], v[204:207], v[16:19]
	v_mfma_f32_16x16x32_bf16 v[4:7], v[172:175], v[212:215], v[4:7]
	v_mfma_f32_16x16x32_bf16 v[0:3], v[180:183], v[212:215], v[0:3]
	s_setprio 0
	s_barrier
	s_add_i32 s55, s55, 2
	s_add_u32 s30, s30, 0x100
	s_addc_u32 s31, s31, 0
	s_add_u32 s53, s53, 0x100
	s_addc_u32 s54, s54, 0
	s_cmp_gt_u32 s55, 29
	s_cbranch_scc0 .LBB0_1882
	s_and_b64 vcc, exec, s[16:17]
	s_cbranch_vccz .LBB0_1885
	s_barrier

; #define PG8_STAGE(bufoff, gbase, voff) do { _Pragma("unroll") for (int _i = 0; _i < 2; ++_i) \
;         __builtin_amdgcn_global_load_lds((const unsigned*)((const char*)(gbase) + (voff)[_i]), (PG8_LAS unsigned*)(lds + (bufoff) + ldsw + _i * 8192), 16, 0, 0); } while (0)
; #define PG8_LDA(dst, b, h) do { _Pragma("unroll") for (int m = 0; m < 4; ++m) _Pragma("unroll") for (int k = 0; k < 2; ++k) dst[m][k] = *(const PG8_LAS bf16x8*)(lds + PG8_SA(b, h) + aoff + m * 2048 + k * 1024); } while (0)
; #define PG8_LDB(dst, b, h) do { _Pragma("unroll") for (int n = 0; n < 2; ++n) _Pragma("unroll") for (int k = 0; k < 2; ++k) dst[n][k] = *(const PG8_LAS bf16x8*)(lds + PG8_SB(b, h) + boff + n * 2048 + k * 1024); } while (0)
; #define PG8_MMA(ai, bj, At, Bt) do { __builtin_amdgcn_s_setprio(1); _Pragma("unroll") for (int m = 0; m < 4; ++m) _Pragma("unroll") for (int n = 0; n < 2; ++n) _Pragma("unroll") for (int k = 0; k < 2; ++k) \
;         acc[ai][bj][m][n] = __builtin_amdgcn_mfma_f32_16x16x32_bf16(Bt[n][k], At[m][k], acc[ai][bj][m][n], 0, 0, 0); __builtin_amdgcn_s_setprio(0); } while (0)
; #define PG8_WAIT_V(n) asm volatile("s_waitcnt vmcnt(" #n ")" ::: "memory")
; #define PG8_WAIT_L(n) asm volatile("s_waitcnt lgkmcnt(" #n ")" ::: "memory")
; #define PG8_BAR __builtin_amdgcn_s_barrier()
; #define PG8_SCHED __builtin_amdgcn_sched_barrier(0)
; template <class Epi, class Sched, bool ALIGN_EPI = false, bool SP2 = false>
; __device__ __forceinline__ void gemm_phase(PG8_LAS unsigned char* lds, const Gemm g, const Sched& S, const Epi& E) {
;     ...
;         for (int t = 0; t < nt; t += 2) {
;             const bool last = (t == nt - 2);
;             const char* a1 = cA + (size_t)(t + 1) * kstep;
;             const char* a2 = last ? nA : cA + (size_t)(t + 2) * kstep; const char* b2 = last ? nB : cB + (size_t)(t + 2) * kstep;
;             const char* a3 = a2 + kstep; const char* b3 = b2 + kstep;
;             if (last && has_next) S.a_ready(nxt);
;             if constexpr (SP2) {
;             PG8_LDB(B0, 0, 0); PG8_LDB(B1, 0, 1); PG8_SCHED; PG8_LDA(At, 0, 0); PG8_STAGE(PG8_SA(1, 1), a1 + hstep, voffA);
;             PG8_WAIT_V(8); PG8_WAIT_L(0); PG8_BAR; PG8_MMA(0, 0, At, B0); PG8_MMA(0, 1, At, B1); PG8_BAR; PG8_SCHED;
;             PG8_LDA(At, 0, 1); PG8_STAGE(PG8_SB(0, 0), b2, voffB); PG8_STAGE(PG8_SB(0, 1), b2 + hstep, voffB); PG8_STAGE(PG8_SA(0, 0), a2, voffA);
.LBB0_1965:
	ds_read_b128 v[128:131], v209
	ds_read_b128 v[132:135], v209 offset:1024
	ds_read_b128 v[136:139], v209 offset:2048
	ds_read_b128 v[140:143], v209 offset:3072
	ds_read_b128 v[144:147], v210
	ds_read_b128 v[148:151], v210 offset:1024
	ds_read_b128 v[152:155], v210 offset:2048
	ds_read_b128 v[156:159], v210 offset:3072
	s_add_u32 s0, s22, 0x100
	s_addc_u32 s1, s23, 0
	s_cmpk_eq_i32 s50, 0x54
	s_cselect_b32 s29, s7, s1
	s_cselect_b32 s28, s6, s0
	s_cselect_b32 s25, s21, s49
	s_cselect_b32 s24, s20, s48
	v_lshl_add_u64 v[204:205], s[22:23], 0, v[180:181]
	s_add_i32 m0, s30, 0xc000
	ds_read_b128 v[160:163], v211
	ds_read_b128 v[164:167], v211 offset:1024
	ds_read_b128 v[168:171], v211 offset:2048
	ds_read_b128 v[172:175], v211 offset:3072
	ds_read_b128 v[188:191], v211 offset:4096
	ds_read_b128 v[192:195], v211 offset:5120
	ds_read_b128 v[196:199], v211 offset:6144
	ds_read_b128 v[200:203], v211 offset:7168
	global_load_lds_dwordx4 v[204:205], off
	v_lshl_add_u64 v[204:205], s[22:23], 0, v[182:183]
	s_add_i32 m0, s30, 0xe000
	s_nop 0
	global_load_lds_dwordx4 v[204:205], off
	s_waitcnt vmcnt(8)
	s_waitcnt lgkmcnt(0)
	s_barrier
	s_setprio 1
	v_mfma_f32_16x16x32_bf16 v[124:127], v[128:131], v[160:163], v[124:127]
	v_mfma_f32_16x16x32_bf16 v[120:123], v[136:139], v[160:163], v[120:123]
	v_mfma_f32_16x16x32_bf16 v[108:111], v[128:131], v[168:171], v[108:111]
	v_mfma_f32_16x16x32_bf16 v[104:107], v[136:139], v[168:171], v[104:107]
	v_mfma_f32_16x16x32_bf16 v[92:95], v[128:131], v[188:191], v[92:95]
	v_mfma_f32_16x16x32_bf16 v[88:91], v[136:139], v[188:191], v[88:91]
	v_mfma_f32_16x16x32_bf16 v[76:79], v[128:131], v[196:199], v[76:79]
	v_mfma_f32_16x16x32_bf16 v[72:75], v[136:139], v[196:199], v[72:75]
	v_mfma_f32_16x16x32_bf16 v[124:127], v[132:135], v[164:167], v[124:127]
	v_mfma_f32_16x16x32_bf16 v[120:123], v[140:143], v[164:167], v[120:123]
	v_mfma_f32_16x16x32_bf16 v[108:111], v[132:135], v[172:175], v[108:111]
	v_mfma_f32_16x16x32_bf16 v[104:107], v[140:143], v[172:175], v[104:107]
	v_mfma_f32_16x16x32_bf16 v[92:95], v[132:135], v[192:195], v[92:95]
	v_mfma_f32_16x16x32_bf16 v[88:91], v[140:143], v[192:195], v[88:91]
	v_mfma_f32_16x16x32_bf16 v[76:79], v[132:135], v[200:203], v[76:79]
	v_mfma_f32_16x16x32_bf16 v[72:75], v[140:143], v[200:203], v[72:75]
	s_setprio 0
	s_setprio 1
	v_mfma_f32_16x16x32_bf16 v[116:119], v[144:147], v[160:163], v[116:119]
	v_mfma_f32_16x16x32_bf16 v[112:115], v[152:155], v[160:163], v[112:115]
	v_mfma_f32_16x16x32_bf16 v[100:103], v[144:147], v[168:171], v[100:103]
	v_mfma_f32_16x16x32_bf16 v[96:99], v[152:155], v[168:171], v[96:99]
	v_mfma_f32_16x16x32_bf16 v[84:87], v[144:147], v[188:191], v[84:87]
	v_mfma_f32_16x16x32_bf16 v[80:83], v[152:155], v[188:191], v[80:83]
	v_mfma_f32_16x16x32_bf16 v[68:71], v[144:147], v[196:199], v[68:71]
	v_mfma_f32_16x16x32_bf16 v[64:67], v[152:155], v[196:199], v[64:67]
	v_mfma_f32_16x16x32_bf16 v[116:119], v[148:151], v[164:167], v[116:119]
	v_mfma_f32_16x16x32_bf16 v[112:115], v[156:159], v[164:167], v[112:115]
	v_mfma_f32_16x16x32_bf16 v[100:103], v[148:151], v[172:175], v[100:103]
	v_mfma_f32_16x16x32_bf16 v[96:99], v[156:159], v[172:175], v[96:99]
	v_mfma_f32_16x16x32_bf16 v[84:87], v[148:151], v[192:195], v[84:87]
	v_mfma_f32_16x16x32_bf16 v[80:83], v[156:159], v[192:195], v[80:83]
	v_mfma_f32_16x16x32_bf16 v[68:71], v[148:151], v[200:203], v[68:71]
	v_mfma_f32_16x16x32_bf16 v[64:67], v[156:159], v[200:203], v[64:67]
	s_setprio 0
	s_barrier
	s_add_i32 s22, s42, s3
	v_lshl_add_u64 v[204:205], s[24:25], 0, v[176:177]
	s_mov_b32 m0, s22
	ds_read_b128 v[160:163], v211 offset:16384
	ds_read_b128 v[164:167], v211 offset:17408
	ds_read_b128 v[168:171], v211 offset:18432
	ds_read_b128 v[172:175], v211 offset:19456
	ds_read_b128 v[188:191], v211 offset:20480
	ds_read_b128 v[192:195], v211 offset:21504
	ds_read_b128 v[196:199], v211 offset:22528
	ds_read_b128 v[200:203], v211 offset:23552
	global_load_lds_dwordx4 v[204:205], off
	s_add_i32 m0, s22, 0x2000
	s_add_u32 s22, s24, 0x160000
	v_lshl_add_u64 v[212:213], s[24:25], 0, v[178:179]
	s_addc_u32 s23, s25, 0
	s_add_i32 s51, s43, s3
	global_load_lds_dwordx4 v[212:213], off
	v_lshl_add_u64 v[214:215], s[22:23], 0, v[176:177]
	s_mov_b32 m0, s51
	v_lshl_add_u64 v[216:217], s[28:29], 0, v[178:179]
	global_load_lds_dwordx4 v[214:215], off
	v_lshl_add_u64 v[214:215], s[22:23], 0, v[178:179]
	s_add_i32 m0, s51, 0x2000
	s_nop 0
	global_load_lds_dwordx4 v[214:215], off
	v_lshl_add_u64 v[214:215], s[28:29], 0, v[176:177]
	s_mov_b32 m0, s30
	s_nop 0
	global_load_lds_dwordx4 v[214:215], off
	s_mov_b32 m0, s31
	s_nop 0
	global_load_lds_dwordx4 v[216:217], off
	s_waitcnt vmcnt(8)
	s_waitcnt lgkmcnt(0)
	s_barrier
; #define PG8_STAGE(bufoff, gbase, voff) do { _Pragma("unroll") for (int _i = 0; _i < 2; ++_i) \
;         __builtin_amdgcn_global_load_lds((const unsigned*)((const char*)(gbase) + (voff)[_i]), (PG8_LAS unsigned*)(lds + (bufoff) + ldsw + _i * 8192), 16, 0, 0); } while (0)
; #define PG8_LDA(dst, b, h) do { _Pragma("unroll") for (int m = 0; m < 4; ++m) _Pragma("unroll") for (int k = 0; k < 2; ++k) dst[m][k] = *(const PG8_LAS bf16x8*)(lds + PG8_SA(b, h) + aoff + m * 2048 + k * 1024); } while (0)
; #define PG8_LDB(dst, b, h) do { _Pragma("unroll") for (int n = 0; n < 2; ++n) _Pragma("unroll") for (int k = 0; k < 2; ++k) dst[n][k] = *(const PG8_LAS bf16x8*)(lds + PG8_SB(b, h) + boff + n * 2048 + k * 1024); } while (0)
; #define PG8_MMA(ai, bj, At, Bt) do { __builtin_amdgcn_s_setprio(1); _Pragma("unroll") for (int m = 0; m < 4; ++m) _Pragma("unroll") for (int n = 0; n < 2; ++n) _Pragma("unroll") for (int k = 0; k < 2; ++k) \
;         acc[ai][bj][m][n] = __builtin_amdgcn_mfma_f32_16x16x32_bf16(Bt[n][k], At[m][k], acc[ai][bj][m][n], 0, 0, 0); __builtin_amdgcn_s_setprio(0); } while (0)
; #define PG8_WAIT_V(n) asm volatile("s_waitcnt vmcnt(" #n ")" ::: "memory")
; #define PG8_WAIT_L(n) asm volatile("s_waitcnt lgkmcnt(" #n ")" ::: "memory")
; #define PG8_BAR __builtin_amdgcn_s_barrier()
; #define PG8_SCHED __builtin_amdgcn_sched_barrier(0)
; template <class Epi, class Sched, bool ALIGN_EPI = false, bool SP2 = false>
; __device__ __forceinline__ void gemm_phase(PG8_LAS unsigned char* lds, const Gemm g, const Sched& S, const Epi& E) {
;     ...
;             PG8_WAIT_V(8); PG8_WAIT_L(0); PG8_BAR; PG8_MMA(1, 0, At, B0); PG8_MMA(1, 1, At, B1); PG8_BAR; PG8_SCHED;
;             PG8_LDB(B0, 1, 0); PG8_LDB(B1, 1, 1); PG8_SCHED; PG8_LDA(At, 1, 0); PG8_STAGE(PG8_SA(0, 1), a2 + hstep, voffA);
;             PG8_WAIT_V(8); PG8_WAIT_L(0); PG8_BAR; PG8_MMA(0, 0, At, B0); PG8_MMA(0, 1, At, B1); PG8_BAR; PG8_SCHED;
	s_setprio 1
	v_mfma_f32_16x16x32_bf16 v[60:63], v[128:131], v[160:163], v[60:63]
	v_mfma_f32_16x16x32_bf16 v[56:59], v[136:139], v[160:163], v[56:59]
	v_mfma_f32_16x16x32_bf16 v[44:47], v[128:131], v[168:171], v[44:47]
	v_mfma_f32_16x16x32_bf16 v[40:43], v[136:139], v[168:171], v[40:43]
	v_mfma_f32_16x16x32_bf16 v[28:31], v[128:131], v[188:191], v[28:31]
	v_mfma_f32_16x16x32_bf16 v[24:27], v[136:139], v[188:191], v[24:27]
	v_mfma_f32_16x16x32_bf16 v[12:15], v[128:131], v[196:199], v[12:15]
	v_mfma_f32_16x16x32_bf16 v[8:11], v[136:139], v[196:199], v[8:11]
	v_mfma_f32_16x16x32_bf16 v[60:63], v[132:135], v[164:167], v[60:63]
	v_mfma_f32_16x16x32_bf16 v[56:59], v[140:143], v[164:167], v[56:59]
	v_mfma_f32_16x16x32_bf16 v[44:47], v[132:135], v[172:175], v[44:47]
	v_mfma_f32_16x16x32_bf16 v[40:43], v[140:143], v[172:175], v[40:43]
	v_mfma_f32_16x16x32_bf16 v[28:31], v[132:135], v[192:195], v[28:31]
	v_mfma_f32_16x16x32_bf16 v[24:27], v[140:143], v[192:195], v[24:27]
	v_mfma_f32_16x16x32_bf16 v[12:15], v[132:135], v[200:203], v[12:15]
	v_mfma_f32_16x16x32_bf16 v[8:11], v[140:143], v[200:203], v[8:11]
	s_setprio 0
	s_setprio 1
	v_mfma_f32_16x16x32_bf16 v[52:55], v[144:147], v[160:163], v[52:55]
	v_mfma_f32_16x16x32_bf16 v[48:51], v[152:155], v[160:163], v[48:51]
	v_mfma_f32_16x16x32_bf16 v[36:39], v[144:147], v[168:171], v[36:39]
	v_mfma_f32_16x16x32_bf16 v[32:35], v[152:155], v[168:171], v[32:35]
	v_mfma_f32_16x16x32_bf16 v[20:23], v[144:147], v[188:191], v[20:23]
	v_mfma_f32_16x16x32_bf16 v[16:19], v[152:155], v[188:191], v[16:19]
	v_mfma_f32_16x16x32_bf16 v[4:7], v[144:147], v[196:199], v[4:7]
	v_mfma_f32_16x16x32_bf16 v[0:3], v[152:155], v[196:199], v[0:3]
	v_mfma_f32_16x16x32_bf16 v[52:55], v[148:151], v[164:167], v[52:55]
	v_mfma_f32_16x16x32_bf16 v[48:51], v[156:159], v[164:167], v[48:51]
	v_mfma_f32_16x16x32_bf16 v[36:39], v[148:151], v[172:175], v[36:39]
	v_mfma_f32_16x16x32_bf16 v[32:35], v[156:159], v[172:175], v[32:35]
	v_mfma_f32_16x16x32_bf16 v[20:23], v[148:151], v[192:195], v[20:23]
	v_mfma_f32_16x16x32_bf16 v[16:19], v[156:159], v[192:195], v[16:19]
	v_mfma_f32_16x16x32_bf16 v[4:7], v[148:151], v[200:203], v[4:7]
	v_mfma_f32_16x16x32_bf16 v[0:3], v[156:159], v[200:203], v[0:3]
	s_setprio 0
	s_barrier
	s_add_i32 s51, 0, 0x18000
	s_add_i32 s52, 0, 0x1c000
	v_add_u32_e32 v140, s51, v207
	v_add_u32_e32 v156, s52, v207
	ds_read_b128 v[128:131], v140
	ds_read_b128 v[132:135], v140 offset:1024
	ds_read_b128 v[136:139], v140 offset:2048
	ds_read_b128 v[140:143], v140 offset:3072
	ds_read_b128 v[144:147], v156
	ds_read_b128 v[148:151], v156 offset:1024
	ds_read_b128 v[152:155], v156 offset:2048
	ds_read_b128 v[156:159], v156 offset:3072
	s_add_u32 s22, s28, 0x160000
	s_addc_u32 s23, s29, 0
	s_mov_b32 m0, s33
	v_lshl_add_u64 v[218:219], s[22:23], 0, v[176:177]
	ds_read_b128 v[160:163], v211 offset:32768
	ds_read_b128 v[164:167], v211 offset:33792
	ds_read_b128 v[168:171], v211 offset:34816
	ds_read_b128 v[172:175], v211 offset:35840
	ds_read_b128 v[188:191], v211 offset:36864
	ds_read_b128 v[192:195], v211 offset:37888
	ds_read_b128 v[196:199], v211 offset:38912
	ds_read_b128 v[200:203], v211 offset:39936
	global_load_lds_dwordx4 v[218:219], off
	v_lshl_add_u64 v[218:219], s[22:23], 0, v[178:179]
	s_mov_b32 m0, s35
	s_nop 0
	global_load_lds_dwordx4 v[218:219], off
	s_waitcnt vmcnt(8)
	s_waitcnt lgkmcnt(0)
	s_barrier
	s_setprio 1
	v_mfma_f32_16x16x32_bf16 v[124:127], v[128:131], v[160:163], v[124:127]
	v_mfma_f32_16x16x32_bf16 v[120:123], v[136:139], v[160:163], v[120:123]
	v_mfma_f32_16x16x32_bf16 v[108:111], v[128:131], v[168:171], v[108:111]
	v_mfma_f32_16x16x32_bf16 v[104:107], v[136:139], v[168:171], v[104:107]
	v_mfma_f32_16x16x32_bf16 v[92:95], v[128:131], v[188:191], v[92:95]
	v_mfma_f32_16x16x32_bf16 v[88:91], v[136:139], v[188:191], v[88:91]
	v_mfma_f32_16x16x32_bf16 v[76:79], v[128:131], v[196:199], v[76:79]
	v_mfma_f32_16x16x32_bf16 v[72:75], v[136:139], v[196:199], v[72:75]
	v_mfma_f32_16x16x32_bf16 v[124:127], v[132:135], v[164:167], v[124:127]
	v_mfma_f32_16x16x32_bf16 v[120:123], v[140:143], v[164:167], v[120:123]
	v_mfma_f32_16x16x32_bf16 v[108:111], v[132:135], v[172:175], v[108:111]
	v_mfma_f32_16x16x32_bf16 v[104:107], v[140:143], v[172:175], v[104:107]
	v_mfma_f32_16x16x32_bf16 v[92:95], v[132:135], v[192:195], v[92:95]
	v_mfma_f32_16x16x32_bf16 v[88:91], v[140:143], v[192:195], v[88:91]
	v_mfma_f32_16x16x32_bf16 v[76:79], v[132:135], v[200:203], v[76:79]
	v_mfma_f32_16x16x32_bf16 v[72:75], v[140:143], v[200:203], v[72:75]
	s_setprio 0
	s_setprio 1
	v_mfma_f32_16x16x32_bf16 v[116:119], v[144:147], v[160:163], v[116:119]
	v_mfma_f32_16x16x32_bf16 v[112:115], v[152:155], v[160:163], v[112:115]
	v_mfma_f32_16x16x32_bf16 v[100:103], v[144:147], v[168:171], v[100:103]
	v_mfma_f32_16x16x32_bf16 v[96:99], v[152:155], v[168:171], v[96:99]
	v_mfma_f32_16x16x32_bf16 v[84:87], v[144:147], v[188:191], v[84:87]
	v_mfma_f32_16x16x32_bf16 v[80:83], v[152:155], v[188:191], v[80:83]
	v_mfma_f32_16x16x32_bf16 v[68:71], v[144:147], v[196:199], v[68:71]
	v_mfma_f32_16x16x32_bf16 v[64:67], v[152:155], v[196:199], v[64:67]
	v_mfma_f32_16x16x32_bf16 v[116:119], v[148:151], v[164:167], v[116:119]
	v_mfma_f32_16x16x32_bf16 v[112:115], v[156:159], v[164:167], v[112:115]
	v_mfma_f32_16x16x32_bf16 v[100:103], v[148:151], v[172:175], v[100:103]
	v_mfma_f32_16x16x32_bf16 v[96:99], v[156:159], v[172:175], v[96:99]
	v_mfma_f32_16x16x32_bf16 v[84:87], v[148:151], v[192:195], v[84:87]
	v_mfma_f32_16x16x32_bf16 v[80:83], v[156:159], v[192:195], v[80:83]
	v_mfma_f32_16x16x32_bf16 v[68:71], v[148:151], v[200:203], v[68:71]
	v_mfma_f32_16x16x32_bf16 v[64:67], v[156:159], v[200:203], v[64:67]
	s_setprio 0
	s_barrier
; #define PG8_STAGE(bufoff, gbase, voff) do { _Pragma("unroll") for (int _i = 0; _i < 2; ++_i) \
;         __builtin_amdgcn_global_load_lds((const unsigned*)((const char*)(gbase) + (voff)[_i]), (PG8_LAS unsigned*)(lds + (bufoff) + ldsw + _i * 8192), 16, 0, 0); } while (0)
; #define PG8_LDA(dst, b, h) do { _Pragma("unroll") for (int m = 0; m < 4; ++m) _Pragma("unroll") for (int k = 0; k < 2; ++k) dst[m][k] = *(const PG8_LAS bf16x8*)(lds + PG8_SA(b, h) + aoff + m * 2048 + k * 1024); } while (0)
; #define PG8_MMA(ai, bj, At, Bt) do { __builtin_amdgcn_s_setprio(1); _Pragma("unroll") for (int m = 0; m < 4; ++m) _Pragma("unroll") for (int n = 0; n < 2; ++n) _Pragma("unroll") for (int k = 0; k < 2; ++k) \
;         acc[ai][bj][m][n] = __builtin_amdgcn_mfma_f32_16x16x32_bf16(Bt[n][k], At[m][k], acc[ai][bj][m][n], 0, 0, 0); __builtin_amdgcn_s_setprio(0); } while (0)
; #define PG8_WAIT_V(n) asm volatile("s_waitcnt vmcnt(" #n ")" ::: "memory")
; #define PG8_WAIT_L(n) asm volatile("s_waitcnt lgkmcnt(" #n ")" ::: "memory")
; #define PG8_BAR __builtin_amdgcn_s_barrier()
; #define PG8_SCHED __builtin_amdgcn_sched_barrier(0)
; template <class Epi, class Sched, bool ALIGN_EPI = false, bool SP2 = false>
; __device__ __forceinline__ void gemm_phase(PG8_LAS unsigned char* lds, const Gemm g, const Sched& S, const Epi& E) {
;     ...
;             PG8_LDA(At, 1, 1); PG8_STAGE(PG8_SB(1, 0), b3, voffB); PG8_STAGE(PG8_SB(1, 1), b3 + hstep, voffB); PG8_STAGE(PG8_SA(1, 0), a3, voffA);
;             PG8_WAIT_V(8); PG8_WAIT_L(0); PG8_BAR; PG8_MMA(1, 0, At, B0); PG8_MMA(1, 1, At, B1); PG8_BAR; PG8_SCHED;
;     ...
;         if constexpr (ALIGN_EPI) { if (wr == 0) PG8_BAR; }
	s_add_i32 s22, s51, s3
	v_lshl_add_u64 v[204:205], v[204:205], 0, s[16:17]
	s_mov_b32 m0, s22
	ds_read_b128 v[160:163], v211 offset:49152
	ds_read_b128 v[164:167], v211 offset:50176
	ds_read_b128 v[168:171], v211 offset:51200
	ds_read_b128 v[172:175], v211 offset:52224
	ds_read_b128 v[188:191], v211 offset:53248
	ds_read_b128 v[192:195], v211 offset:54272
	ds_read_b128 v[196:199], v211 offset:55296
	ds_read_b128 v[200:203], v211 offset:56320
	global_load_lds_dwordx4 v[204:205], off
	s_add_i32 m0, s22, 0x2000
	s_add_u32 s22, s24, 0x160080
	v_lshl_add_u64 v[204:205], v[212:213], 0, s[16:17]
	s_addc_u32 s23, s25, 0
	s_add_i32 s24, s52, s3
	global_load_lds_dwordx4 v[204:205], off
	v_lshl_add_u64 v[204:205], s[22:23], 0, v[176:177]
	s_mov_b32 m0, s24
	s_nop 0
	global_load_lds_dwordx4 v[204:205], off
	v_lshl_add_u64 v[204:205], s[22:23], 0, v[178:179]
	s_add_i32 m0, s24, 0x2000
	s_nop 0
	global_load_lds_dwordx4 v[204:205], off
	v_lshl_add_u64 v[204:205], v[214:215], 0, s[16:17]
	s_mov_b32 m0, s37
	s_nop 0
	global_load_lds_dwordx4 v[204:205], off
	v_lshl_add_u64 v[204:205], v[216:217], 0, s[16:17]
	s_mov_b32 m0, s38
	s_nop 0
	global_load_lds_dwordx4 v[204:205], off
	s_waitcnt vmcnt(8)
	s_waitcnt lgkmcnt(0)
	s_barrier
	s_setprio 1
	v_mfma_f32_16x16x32_bf16 v[60:63], v[128:131], v[160:163], v[60:63]
	v_mfma_f32_16x16x32_bf16 v[56:59], v[136:139], v[160:163], v[56:59]
	v_mfma_f32_16x16x32_bf16 v[44:47], v[128:131], v[168:171], v[44:47]
	v_mfma_f32_16x16x32_bf16 v[40:43], v[136:139], v[168:171], v[40:43]
	v_mfma_f32_16x16x32_bf16 v[28:31], v[128:131], v[188:191], v[28:31]
	v_mfma_f32_16x16x32_bf16 v[24:27], v[136:139], v[188:191], v[24:27]
	v_mfma_f32_16x16x32_bf16 v[12:15], v[128:131], v[196:199], v[12:15]
	v_mfma_f32_16x16x32_bf16 v[8:11], v[136:139], v[196:199], v[8:11]
	v_mfma_f32_16x16x32_bf16 v[60:63], v[132:135], v[164:167], v[60:63]
	v_mfma_f32_16x16x32_bf16 v[56:59], v[140:143], v[164:167], v[56:59]
	v_mfma_f32_16x16x32_bf16 v[44:47], v[132:135], v[172:175], v[44:47]
	v_mfma_f32_16x16x32_bf16 v[40:43], v[140:143], v[172:175], v[40:43]
	v_mfma_f32_16x16x32_bf16 v[28:31], v[132:135], v[192:195], v[28:31]
	v_mfma_f32_16x16x32_bf16 v[24:27], v[140:143], v[192:195], v[24:27]
	v_mfma_f32_16x16x32_bf16 v[12:15], v[132:135], v[200:203], v[12:15]
	v_mfma_f32_16x16x32_bf16 v[8:11], v[140:143], v[200:203], v[8:11]
	s_setprio 0
	s_setprio 1
	v_mfma_f32_16x16x32_bf16 v[52:55], v[144:147], v[160:163], v[52:55]
	v_mfma_f32_16x16x32_bf16 v[48:51], v[152:155], v[160:163], v[48:51]
	v_mfma_f32_16x16x32_bf16 v[36:39], v[144:147], v[168:171], v[36:39]
	v_mfma_f32_16x16x32_bf16 v[32:35], v[152:155], v[168:171], v[32:35]
	v_mfma_f32_16x16x32_bf16 v[20:23], v[144:147], v[188:191], v[20:23]
	v_mfma_f32_16x16x32_bf16 v[16:19], v[152:155], v[188:191], v[16:19]
	v_mfma_f32_16x16x32_bf16 v[4:7], v[144:147], v[196:199], v[4:7]
	v_mfma_f32_16x16x32_bf16 v[0:3], v[152:155], v[196:199], v[0:3]
	v_mfma_f32_16x16x32_bf16 v[52:55], v[148:151], v[164:167], v[52:55]
	v_mfma_f32_16x16x32_bf16 v[48:51], v[156:159], v[164:167], v[48:51]
	v_mfma_f32_16x16x32_bf16 v[36:39], v[148:151], v[172:175], v[36:39]
	v_mfma_f32_16x16x32_bf16 v[32:35], v[156:159], v[172:175], v[32:35]
	v_mfma_f32_16x16x32_bf16 v[20:23], v[148:151], v[192:195], v[20:23]
	v_mfma_f32_16x16x32_bf16 v[16:19], v[156:159], v[192:195], v[16:19]
	v_mfma_f32_16x16x32_bf16 v[4:7], v[148:151], v[200:203], v[4:7]
	v_mfma_f32_16x16x32_bf16 v[0:3], v[156:159], v[200:203], v[0:3]
	s_setprio 0
	s_barrier
	s_add_i32 s50, s50, 2
	s_add_u32 s48, s48, 0x100
	s_addc_u32 s49, s49, 0
	s_cmpk_gt_u32 s50, 0x55
	s_mov_b64 s[22:23], s[0:1]
	s_cbranch_scc0 .LBB0_1965
	s_and_b64 vcc, exec, s[18:19]
	s_cbranch_vccz .LBB0_1968
	s_barrier

; #define PG8_STAGE(bufoff, gbase, voff) do { _Pragma("unroll") for (int _i = 0; _i < 2; ++_i) \
;         __builtin_amdgcn_global_load_lds((const unsigned*)((const char*)(gbase) + (voff)[_i]), (PG8_LAS unsigned*)(lds + (bufoff) + ldsw + _i * 8192), 16, 0, 0); } while (0)
; #define PG8_LDA(dst, b, h) do { _Pragma("unroll") for (int m = 0; m < 4; ++m) _Pragma("unroll") for (int k = 0; k < 2; ++k) dst[m][k] = *(const PG8_LAS bf16x8*)(lds + PG8_SA(b, h) + aoff + m * 2048 + k * 1024); } while (0)
; #define PG8_LDB(dst, b, h) do { _Pragma("unroll") for (int n = 0; n < 2; ++n) _Pragma("unroll") for (int k = 0; k < 2; ++k) dst[n][k] = *(const PG8_LAS bf16x8*)(lds + PG8_SB(b, h) + boff + n * 2048 + k * 1024); } while (0)
; #define PG8_MMA(ai, bj, At, Bt) do { __builtin_amdgcn_s_setprio(1); _Pragma("unroll") for (int m = 0; m < 4; ++m) _Pragma("unroll") for (int n = 0; n < 2; ++n) _Pragma("unroll") for (int k = 0; k < 2; ++k) \
;         acc[ai][bj][m][n] = __builtin_amdgcn_mfma_f32_16x16x32_bf16(Bt[n][k], At[m][k], acc[ai][bj][m][n], 0, 0, 0); __builtin_amdgcn_s_setprio(0); } while (0)
; #define PG8_WAIT_V(n) asm volatile("s_waitcnt vmcnt(" #n ")" ::: "memory")
; #define PG8_WAIT_L(n) asm volatile("s_waitcnt lgkmcnt(" #n ")" ::: "memory")
; #define PG8_BAR __builtin_amdgcn_s_barrier()
; #define PG8_SCHED __builtin_amdgcn_sched_barrier(0)
; template <class Epi, class Sched, bool ALIGN_EPI = false, bool SP2 = false>
; __device__ __forceinline__ void gemm_phase(PG8_LAS unsigned char* lds, const Gemm g, const Sched& S, const Epi& E) {
;     ...
;         for (int t = 0; t < nt; t += 2) {
;             const bool last = (t == nt - 2);
;             const char* a1 = cA + (size_t)(t + 1) * kstep;
;             const char* a2 = last ? nA : cA + (size_t)(t + 2) * kstep; const char* b2 = last ? nB : cB + (size_t)(t + 2) * kstep;
;             const char* a3 = a2 + kstep; const char* b3 = b2 + kstep;
;             if (last && has_next) S.a_ready(nxt);
;             if constexpr (SP2) {
;             PG8_LDB(B0, 0, 0); PG8_LDB(B1, 0, 1); PG8_SCHED; PG8_LDA(At, 0, 0); PG8_STAGE(PG8_SA(1, 1), a1 + hstep, voffA);
;             PG8_WAIT_V(8); PG8_WAIT_L(0); PG8_BAR; PG8_MMA(0, 0, At, B0); PG8_MMA(0, 1, At, B1); PG8_BAR; PG8_SCHED;
;             PG8_LDA(At, 0, 1); PG8_STAGE(PG8_SB(0, 0), b2, voffB); PG8_STAGE(PG8_SB(0, 1), b2 + hstep, voffB); PG8_STAGE(PG8_SA(0, 0), a2, voffA);
.LBB0_2053:
	ds_read_b128 v[128:131], v225
	ds_read_b128 v[132:135], v225 offset:1024
	ds_read_b128 v[136:139], v225 offset:2048
	ds_read_b128 v[140:143], v225 offset:3072
	ds_read_b128 v[144:147], v228
	ds_read_b128 v[148:151], v228 offset:1024
	ds_read_b128 v[152:155], v228 offset:2048
	ds_read_b128 v[156:159], v228 offset:3072
	s_add_u32 s24, s22, 0x100
	s_addc_u32 s25, s23, 0
	s_cmpk_eq_i32 s55, 0x54
	s_cselect_b32 s31, s21, s25
	s_cselect_b32 s30, s20, s24
	s_cselect_b32 s29, s9, s7
	s_cselect_b32 s28, s8, s6
	s_mov_b32 m0, s43
	v_lshl_add_u64 v[204:205], s[22:23], 0, v[184:185]
	ds_read_b128 v[160:163], v229
	ds_read_b128 v[164:167], v229 offset:1024
	ds_read_b128 v[168:171], v229 offset:2048
	ds_read_b128 v[172:175], v229 offset:3072
	ds_read_b128 v[188:191], v229 offset:4096
	ds_read_b128 v[192:195], v229 offset:5120
	ds_read_b128 v[196:199], v229 offset:6144
	ds_read_b128 v[200:203], v229 offset:7168
	global_load_lds_dwordx4 v[204:205], off
	v_lshl_add_u64 v[204:205], s[22:23], 0, v[186:187]
	s_mov_b32 m0, s44
	s_nop 0
	global_load_lds_dwordx4 v[204:205], off
	s_waitcnt vmcnt(8)
	s_waitcnt lgkmcnt(0)
	s_barrier
	s_setprio 1
	v_mfma_f32_16x16x32_bf16 v[124:127], v[128:131], v[160:163], v[124:127]
	v_mfma_f32_16x16x32_bf16 v[120:123], v[136:139], v[160:163], v[120:123]
	v_mfma_f32_16x16x32_bf16 v[108:111], v[128:131], v[168:171], v[108:111]
	v_mfma_f32_16x16x32_bf16 v[104:107], v[136:139], v[168:171], v[104:107]
	v_mfma_f32_16x16x32_bf16 v[96:99], v[128:131], v[188:191], v[96:99]
	v_mfma_f32_16x16x32_bf16 v[88:91], v[136:139], v[188:191], v[88:91]
	v_mfma_f32_16x16x32_bf16 v[80:83], v[128:131], v[196:199], v[80:83]
	v_mfma_f32_16x16x32_bf16 v[72:75], v[136:139], v[196:199], v[72:75]
	v_mfma_f32_16x16x32_bf16 v[124:127], v[132:135], v[164:167], v[124:127]
	v_mfma_f32_16x16x32_bf16 v[120:123], v[140:143], v[164:167], v[120:123]
	v_mfma_f32_16x16x32_bf16 v[108:111], v[132:135], v[172:175], v[108:111]
	v_mfma_f32_16x16x32_bf16 v[104:107], v[140:143], v[172:175], v[104:107]
	v_mfma_f32_16x16x32_bf16 v[96:99], v[132:135], v[192:195], v[96:99]
	v_mfma_f32_16x16x32_bf16 v[88:91], v[140:143], v[192:195], v[88:91]
	v_mfma_f32_16x16x32_bf16 v[80:83], v[132:135], v[200:203], v[80:83]
	v_mfma_f32_16x16x32_bf16 v[72:75], v[140:143], v[200:203], v[72:75]
	s_setprio 0
	s_setprio 1
	v_mfma_f32_16x16x32_bf16 v[116:119], v[144:147], v[160:163], v[116:119]
	v_mfma_f32_16x16x32_bf16 v[112:115], v[152:155], v[160:163], v[112:115]
	v_mfma_f32_16x16x32_bf16 v[100:103], v[144:147], v[168:171], v[100:103]
	v_mfma_f32_16x16x32_bf16 v[92:95], v[152:155], v[168:171], v[92:95]
	v_mfma_f32_16x16x32_bf16 v[84:87], v[144:147], v[188:191], v[84:87]
	v_mfma_f32_16x16x32_bf16 v[76:79], v[152:155], v[188:191], v[76:79]
	v_mfma_f32_16x16x32_bf16 v[68:71], v[144:147], v[196:199], v[68:71]
	v_mfma_f32_16x16x32_bf16 v[64:67], v[152:155], v[196:199], v[64:67]
	v_mfma_f32_16x16x32_bf16 v[116:119], v[148:151], v[164:167], v[116:119]
	v_mfma_f32_16x16x32_bf16 v[112:115], v[156:159], v[164:167], v[112:115]
	v_mfma_f32_16x16x32_bf16 v[100:103], v[148:151], v[172:175], v[100:103]
	v_mfma_f32_16x16x32_bf16 v[92:95], v[156:159], v[172:175], v[92:95]
	v_mfma_f32_16x16x32_bf16 v[84:87], v[148:151], v[192:195], v[84:87]
	v_mfma_f32_16x16x32_bf16 v[76:79], v[156:159], v[192:195], v[76:79]
	v_mfma_f32_16x16x32_bf16 v[68:71], v[148:151], v[200:203], v[68:71]
	v_mfma_f32_16x16x32_bf16 v[64:67], v[156:159], v[200:203], v[64:67]
	s_setprio 0
	s_barrier
	s_mov_b32 m0, s45
	v_lshl_add_u64 v[204:205], s[28:29], 0, v[176:177]
	s_add_u32 s22, s28, 0x160000
	ds_read_b128 v[160:163], v229 offset:16384
	ds_read_b128 v[164:167], v229 offset:17408
	ds_read_b128 v[168:171], v229 offset:18432
	ds_read_b128 v[172:175], v229 offset:19456
	ds_read_b128 v[188:191], v229 offset:20480
	ds_read_b128 v[192:195], v229 offset:21504
	ds_read_b128 v[196:199], v229 offset:22528
	ds_read_b128 v[200:203], v229 offset:23552
	global_load_lds_dwordx4 v[204:205], off
	v_lshl_add_u64 v[206:207], s[28:29], 0, v[178:179]
	s_mov_b32 m0, s46
	s_addc_u32 s23, s29, 0
	global_load_lds_dwordx4 v[206:207], off
	v_lshl_add_u64 v[208:209], s[22:23], 0, v[176:177]
	s_mov_b32 m0, s47
	v_lshl_add_u64 v[210:211], s[30:31], 0, v[178:179]
	global_load_lds_dwordx4 v[208:209], off
	v_lshl_add_u64 v[208:209], s[22:23], 0, v[178:179]
	s_mov_b32 m0, s48
	s_nop 0
	global_load_lds_dwordx4 v[208:209], off
	v_lshl_add_u64 v[208:209], s[30:31], 0, v[176:177]
	s_mov_b32 m0, s34
	s_nop 0
	global_load_lds_dwordx4 v[208:209], off
	s_mov_b32 m0, s35
	s_nop 0
	global_load_lds_dwordx4 v[210:211], off
	s_waitcnt vmcnt(8)
	s_waitcnt lgkmcnt(0)
	s_barrier
; #define PG8_STAGE(bufoff, gbase, voff) do { _Pragma("unroll") for (int _i = 0; _i < 2; ++_i) \
;         __builtin_amdgcn_global_load_lds((const unsigned*)((const char*)(gbase) + (voff)[_i]), (PG8_LAS unsigned*)(lds + (bufoff) + ldsw + _i * 8192), 16, 0, 0); } while (0)
; #define PG8_LDA(dst, b, h) do { _Pragma("unroll") for (int m = 0; m < 4; ++m) _Pragma("unroll") for (int k = 0; k < 2; ++k) dst[m][k] = *(const PG8_LAS bf16x8*)(lds + PG8_SA(b, h) + aoff + m * 2048 + k * 1024); } while (0)
; #define PG8_LDB(dst, b, h) do { _Pragma("unroll") for (int n = 0; n < 2; ++n) _Pragma("unroll") for (int k = 0; k < 2; ++k) dst[n][k] = *(const PG8_LAS bf16x8*)(lds + PG8_SB(b, h) + boff + n * 2048 + k * 1024); } while (0)
; #define PG8_MMA(ai, bj, At, Bt) do { __builtin_amdgcn_s_setprio(1); _Pragma("unroll") for (int m = 0; m < 4; ++m) _Pragma("unroll") for (int n = 0; n < 2; ++n) _Pragma("unroll") for (int k = 0; k < 2; ++k) \
;         acc[ai][bj][m][n] = __builtin_amdgcn_mfma_f32_16x16x32_bf16(Bt[n][k], At[m][k], acc[ai][bj][m][n], 0, 0, 0); __builtin_amdgcn_s_setprio(0); } while (0)
; #define PG8_WAIT_V(n) asm volatile("s_waitcnt vmcnt(" #n ")" ::: "memory")
; #define PG8_WAIT_L(n) asm volatile("s_waitcnt lgkmcnt(" #n ")" ::: "memory")
; #define PG8_BAR __builtin_amdgcn_s_barrier()
; #define PG8_SCHED __builtin_amdgcn_sched_barrier(0)
; template <class Epi, class Sched, bool ALIGN_EPI = false, bool SP2 = false>
; __device__ __forceinline__ void gemm_phase(PG8_LAS unsigned char* lds, const Gemm g, const Sched& S, const Epi& E) {
;     ...
;             PG8_WAIT_V(8); PG8_WAIT_L(0); PG8_BAR; PG8_MMA(1, 0, At, B0); PG8_MMA(1, 1, At, B1); PG8_BAR; PG8_SCHED;
;             PG8_LDB(B0, 1, 0); PG8_LDB(B1, 1, 1); PG8_SCHED; PG8_LDA(At, 1, 0); PG8_STAGE(PG8_SA(0, 1), a2 + hstep, voffA);
;             PG8_WAIT_V(8); PG8_WAIT_L(0); PG8_BAR; PG8_MMA(0, 0, At, B0); PG8_MMA(0, 1, At, B1); PG8_BAR; PG8_SCHED;
	s_setprio 1
	v_mfma_f32_16x16x32_bf16 v[60:63], v[128:131], v[160:163], v[60:63]
	v_mfma_f32_16x16x32_bf16 v[56:59], v[136:139], v[160:163], v[56:59]
	v_mfma_f32_16x16x32_bf16 v[44:47], v[128:131], v[168:171], v[44:47]
	v_mfma_f32_16x16x32_bf16 v[40:43], v[136:139], v[168:171], v[40:43]
	v_mfma_f32_16x16x32_bf16 v[32:35], v[128:131], v[188:191], v[32:35]
	v_mfma_f32_16x16x32_bf16 v[24:27], v[136:139], v[188:191], v[24:27]
	v_mfma_f32_16x16x32_bf16 v[16:19], v[128:131], v[196:199], v[16:19]
	v_mfma_f32_16x16x32_bf16 v[8:11], v[136:139], v[196:199], v[8:11]
	v_mfma_f32_16x16x32_bf16 v[60:63], v[132:135], v[164:167], v[60:63]
	v_mfma_f32_16x16x32_bf16 v[56:59], v[140:143], v[164:167], v[56:59]
	v_mfma_f32_16x16x32_bf16 v[44:47], v[132:135], v[172:175], v[44:47]
	v_mfma_f32_16x16x32_bf16 v[40:43], v[140:143], v[172:175], v[40:43]
	v_mfma_f32_16x16x32_bf16 v[32:35], v[132:135], v[192:195], v[32:35]
	v_mfma_f32_16x16x32_bf16 v[24:27], v[140:143], v[192:195], v[24:27]
	v_mfma_f32_16x16x32_bf16 v[16:19], v[132:135], v[200:203], v[16:19]
	v_mfma_f32_16x16x32_bf16 v[8:11], v[140:143], v[200:203], v[8:11]
	s_setprio 0
	s_setprio 1
	v_mfma_f32_16x16x32_bf16 v[52:55], v[144:147], v[160:163], v[52:55]
	v_mfma_f32_16x16x32_bf16 v[48:51], v[152:155], v[160:163], v[48:51]
	v_mfma_f32_16x16x32_bf16 v[36:39], v[144:147], v[168:171], v[36:39]
	v_mfma_f32_16x16x32_bf16 v[28:31], v[152:155], v[168:171], v[28:31]
	v_mfma_f32_16x16x32_bf16 v[20:23], v[144:147], v[188:191], v[20:23]
	v_mfma_f32_16x16x32_bf16 v[12:15], v[152:155], v[188:191], v[12:15]
	v_mfma_f32_16x16x32_bf16 v[4:7], v[144:147], v[196:199], v[4:7]
	v_mfma_f32_16x16x32_bf16 v[0:3], v[152:155], v[196:199], v[0:3]
	v_mfma_f32_16x16x32_bf16 v[52:55], v[148:151], v[164:167], v[52:55]
	v_mfma_f32_16x16x32_bf16 v[48:51], v[156:159], v[164:167], v[48:51]
	v_mfma_f32_16x16x32_bf16 v[36:39], v[148:151], v[172:175], v[36:39]
	v_mfma_f32_16x16x32_bf16 v[28:31], v[156:159], v[172:175], v[28:31]
	v_mfma_f32_16x16x32_bf16 v[20:23], v[148:151], v[192:195], v[20:23]
	v_mfma_f32_16x16x32_bf16 v[12:15], v[156:159], v[192:195], v[12:15]
	v_mfma_f32_16x16x32_bf16 v[4:7], v[148:151], v[200:203], v[4:7]
	v_mfma_f32_16x16x32_bf16 v[0:3], v[156:159], v[200:203], v[0:3]
	s_setprio 0
	s_barrier
	ds_read_b128 v[128:131], v232
	ds_read_b128 v[132:135], v232 offset:1024
	ds_read_b128 v[136:139], v232 offset:2048
	ds_read_b128 v[140:143], v232 offset:3072
	ds_read_b128 v[144:147], v233
	ds_read_b128 v[148:151], v233 offset:1024
	ds_read_b128 v[152:155], v233 offset:2048
	ds_read_b128 v[156:159], v233 offset:3072
	s_add_u32 s22, s30, 0x160000
	s_addc_u32 s23, s31, 0
	s_mov_b32 m0, s36
	v_lshl_add_u64 v[212:213], s[22:23], 0, v[176:177]
	ds_read_b128 v[160:163], v229 offset:32768
	ds_read_b128 v[164:167], v229 offset:33792
	ds_read_b128 v[168:171], v229 offset:34816
	ds_read_b128 v[172:175], v229 offset:35840
	ds_read_b128 v[188:191], v229 offset:36864
	ds_read_b128 v[192:195], v229 offset:37888
	ds_read_b128 v[196:199], v229 offset:38912
	ds_read_b128 v[200:203], v229 offset:39936
	global_load_lds_dwordx4 v[212:213], off
	v_lshl_add_u64 v[212:213], s[22:23], 0, v[178:179]
	s_mov_b32 m0, s37
	s_nop 0
	global_load_lds_dwordx4 v[212:213], off
	s_waitcnt vmcnt(8)
	s_waitcnt lgkmcnt(0)
	s_barrier
	s_setprio 1
	v_mfma_f32_16x16x32_bf16 v[124:127], v[128:131], v[160:163], v[124:127]
	v_mfma_f32_16x16x32_bf16 v[120:123], v[136:139], v[160:163], v[120:123]
	v_mfma_f32_16x16x32_bf16 v[108:111], v[128:131], v[168:171], v[108:111]
	v_mfma_f32_16x16x32_bf16 v[104:107], v[136:139], v[168:171], v[104:107]
	v_mfma_f32_16x16x32_bf16 v[96:99], v[128:131], v[188:191], v[96:99]
	v_mfma_f32_16x16x32_bf16 v[88:91], v[136:139], v[188:191], v[88:91]
	v_mfma_f32_16x16x32_bf16 v[80:83], v[128:131], v[196:199], v[80:83]
	v_mfma_f32_16x16x32_bf16 v[72:75], v[136:139], v[196:199], v[72:75]
	v_mfma_f32_16x16x32_bf16 v[124:127], v[132:135], v[164:167], v[124:127]
	v_mfma_f32_16x16x32_bf16 v[120:123], v[140:143], v[164:167], v[120:123]
	v_mfma_f32_16x16x32_bf16 v[108:111], v[132:135], v[172:175], v[108:111]
	v_mfma_f32_16x16x32_bf16 v[104:107], v[140:143], v[172:175], v[104:107]
	v_mfma_f32_16x16x32_bf16 v[96:99], v[132:135], v[192:195], v[96:99]
	v_mfma_f32_16x16x32_bf16 v[88:91], v[140:143], v[192:195], v[88:91]
	v_mfma_f32_16x16x32_bf16 v[80:83], v[132:135], v[200:203], v[80:83]
	v_mfma_f32_16x16x32_bf16 v[72:75], v[140:143], v[200:203], v[72:75]
	s_setprio 0
	s_setprio 1
	v_mfma_f32_16x16x32_bf16 v[116:119], v[144:147], v[160:163], v[116:119]
	v_mfma_f32_16x16x32_bf16 v[112:115], v[152:155], v[160:163], v[112:115]
	v_mfma_f32_16x16x32_bf16 v[100:103], v[144:147], v[168:171], v[100:103]
	v_mfma_f32_16x16x32_bf16 v[92:95], v[152:155], v[168:171], v[92:95]
	v_mfma_f32_16x16x32_bf16 v[84:87], v[144:147], v[188:191], v[84:87]
	v_mfma_f32_16x16x32_bf16 v[76:79], v[152:155], v[188:191], v[76:79]
	v_mfma_f32_16x16x32_bf16 v[68:71], v[144:147], v[196:199], v[68:71]
	v_mfma_f32_16x16x32_bf16 v[64:67], v[152:155], v[196:199], v[64:67]
	v_mfma_f32_16x16x32_bf16 v[116:119], v[148:151], v[164:167], v[116:119]
	v_mfma_f32_16x16x32_bf16 v[112:115], v[156:159], v[164:167], v[112:115]
	v_mfma_f32_16x16x32_bf16 v[100:103], v[148:151], v[172:175], v[100:103]
	v_mfma_f32_16x16x32_bf16 v[92:95], v[156:159], v[172:175], v[92:95]
	v_mfma_f32_16x16x32_bf16 v[84:87], v[148:151], v[192:195], v[84:87]
	v_mfma_f32_16x16x32_bf16 v[76:79], v[156:159], v[192:195], v[76:79]
	v_mfma_f32_16x16x32_bf16 v[68:71], v[148:151], v[200:203], v[68:71]
	v_mfma_f32_16x16x32_bf16 v[64:67], v[156:159], v[200:203], v[64:67]
	s_setprio 0
	s_barrier
; #define PG8_STAGE(bufoff, gbase, voff) do { _Pragma("unroll") for (int _i = 0; _i < 2; ++_i) \
;         __builtin_amdgcn_global_load_lds((const unsigned*)((const char*)(gbase) + (voff)[_i]), (PG8_LAS unsigned*)(lds + (bufoff) + ldsw + _i * 8192), 16, 0, 0); } while (0)
; #define PG8_LDA(dst, b, h) do { _Pragma("unroll") for (int m = 0; m < 4; ++m) _Pragma("unroll") for (int k = 0; k < 2; ++k) dst[m][k] = *(const PG8_LAS bf16x8*)(lds + PG8_SA(b, h) + aoff + m * 2048 + k * 1024); } while (0)
; #define PG8_MMA(ai, bj, At, Bt) do { __builtin_amdgcn_s_setprio(1); _Pragma("unroll") for (int m = 0; m < 4; ++m) _Pragma("unroll") for (int n = 0; n < 2; ++n) _Pragma("unroll") for (int k = 0; k < 2; ++k) \
;         acc[ai][bj][m][n] = __builtin_amdgcn_mfma_f32_16x16x32_bf16(Bt[n][k], At[m][k], acc[ai][bj][m][n], 0, 0, 0); __builtin_amdgcn_s_setprio(0); } while (0)
; #define PG8_WAIT_V(n) asm volatile("s_waitcnt vmcnt(" #n ")" ::: "memory")
; #define PG8_WAIT_L(n) asm volatile("s_waitcnt lgkmcnt(" #n ")" ::: "memory")
; #define PG8_BAR __builtin_amdgcn_s_barrier()
; #define PG8_SCHED __builtin_amdgcn_sched_barrier(0)
; template <class Epi, class Sched, bool ALIGN_EPI = false, bool SP2 = false>
; __device__ __forceinline__ void gemm_phase(PG8_LAS unsigned char* lds, const Gemm g, const Sched& S, const Epi& E) {
;     ...
;         for (int t = 0; t < nt; t += 2) {
;             const bool last = (t == nt - 2);
;             const char* a1 = cA + (size_t)(t + 1) * kstep;
;             const char* a2 = last ? nA : cA + (size_t)(t + 2) * kstep; const char* b2 = last ? nB : cB + (size_t)(t + 2) * kstep;
;     ...
;             PG8_LDA(At, 1, 1); PG8_STAGE(PG8_SB(1, 0), b3, voffB); PG8_STAGE(PG8_SB(1, 1), b3 + hstep, voffB); PG8_STAGE(PG8_SA(1, 0), a3, voffA);
;             PG8_WAIT_V(8); PG8_WAIT_L(0); PG8_BAR; PG8_MMA(1, 0, At, B0); PG8_MMA(1, 1, At, B1); PG8_BAR; PG8_SCHED;
	s_mov_b32 m0, s49
	v_lshl_add_u64 v[204:205], v[204:205], 0, s[14:15]
	s_add_u32 s22, s28, 0x160080
	ds_read_b128 v[160:163], v229 offset:49152
	ds_read_b128 v[164:167], v229 offset:50176
	ds_read_b128 v[168:171], v229 offset:51200
	ds_read_b128 v[172:175], v229 offset:52224
	ds_read_b128 v[188:191], v229 offset:53248
	ds_read_b128 v[192:195], v229 offset:54272
	ds_read_b128 v[196:199], v229 offset:55296
	ds_read_b128 v[200:203], v229 offset:56320
	global_load_lds_dwordx4 v[204:205], off
	v_lshl_add_u64 v[204:205], v[206:207], 0, s[14:15]
	s_mov_b32 m0, s50
	s_addc_u32 s23, s29, 0
	global_load_lds_dwordx4 v[204:205], off
	v_lshl_add_u64 v[204:205], s[22:23], 0, v[176:177]
	s_mov_b32 m0, s51
	s_nop 0
	global_load_lds_dwordx4 v[204:205], off
	v_lshl_add_u64 v[204:205], s[22:23], 0, v[178:179]
	s_mov_b32 m0, s52
	s_nop 0
	global_load_lds_dwordx4 v[204:205], off
	v_lshl_add_u64 v[204:205], v[208:209], 0, s[14:15]
	s_mov_b32 m0, s38
	s_nop 0
	global_load_lds_dwordx4 v[204:205], off
	v_lshl_add_u64 v[204:205], v[210:211], 0, s[14:15]
	s_mov_b32 m0, s39
	s_nop 0
	global_load_lds_dwordx4 v[204:205], off
	s_waitcnt vmcnt(8)
	s_waitcnt lgkmcnt(0)
	s_barrier
	s_setprio 1
	v_mfma_f32_16x16x32_bf16 v[60:63], v[128:131], v[160:163], v[60:63]
	v_mfma_f32_16x16x32_bf16 v[56:59], v[136:139], v[160:163], v[56:59]
	v_mfma_f32_16x16x32_bf16 v[44:47], v[128:131], v[168:171], v[44:47]
	v_mfma_f32_16x16x32_bf16 v[40:43], v[136:139], v[168:171], v[40:43]
	v_mfma_f32_16x16x32_bf16 v[32:35], v[128:131], v[188:191], v[32:35]
	v_mfma_f32_16x16x32_bf16 v[24:27], v[136:139], v[188:191], v[24:27]
	v_mfma_f32_16x16x32_bf16 v[16:19], v[128:131], v[196:199], v[16:19]
	v_mfma_f32_16x16x32_bf16 v[8:11], v[136:139], v[196:199], v[8:11]
	v_mfma_f32_16x16x32_bf16 v[60:63], v[132:135], v[164:167], v[60:63]
	v_mfma_f32_16x16x32_bf16 v[56:59], v[140:143], v[164:167], v[56:59]
	v_mfma_f32_16x16x32_bf16 v[44:47], v[132:135], v[172:175], v[44:47]
	v_mfma_f32_16x16x32_bf16 v[40:43], v[140:143], v[172:175], v[40:43]
	v_mfma_f32_16x16x32_bf16 v[32:35], v[132:135], v[192:195], v[32:35]
	v_mfma_f32_16x16x32_bf16 v[24:27], v[140:143], v[192:195], v[24:27]
	v_mfma_f32_16x16x32_bf16 v[16:19], v[132:135], v[200:203], v[16:19]
	v_mfma_f32_16x16x32_bf16 v[8:11], v[140:143], v[200:203], v[8:11]
	s_setprio 0
	s_setprio 1
	v_mfma_f32_16x16x32_bf16 v[52:55], v[144:147], v[160:163], v[52:55]
	v_mfma_f32_16x16x32_bf16 v[48:51], v[152:155], v[160:163], v[48:51]
	v_mfma_f32_16x16x32_bf16 v[36:39], v[144:147], v[168:171], v[36:39]
	v_mfma_f32_16x16x32_bf16 v[28:31], v[152:155], v[168:171], v[28:31]
	v_mfma_f32_16x16x32_bf16 v[20:23], v[144:147], v[188:191], v[20:23]
	v_mfma_f32_16x16x32_bf16 v[12:15], v[152:155], v[188:191], v[12:15]
	v_mfma_f32_16x16x32_bf16 v[4:7], v[144:147], v[196:199], v[4:7]
	v_mfma_f32_16x16x32_bf16 v[0:3], v[152:155], v[196:199], v[0:3]
	v_mfma_f32_16x16x32_bf16 v[52:55], v[148:151], v[164:167], v[52:55]
	v_mfma_f32_16x16x32_bf16 v[48:51], v[156:159], v[164:167], v[48:51]
	v_mfma_f32_16x16x32_bf16 v[36:39], v[148:151], v[172:175], v[36:39]
	v_mfma_f32_16x16x32_bf16 v[28:31], v[156:159], v[172:175], v[28:31]
	v_mfma_f32_16x16x32_bf16 v[20:23], v[148:151], v[192:195], v[20:23]
	v_mfma_f32_16x16x32_bf16 v[12:15], v[156:159], v[192:195], v[12:15]
	v_mfma_f32_16x16x32_bf16 v[4:7], v[148:151], v[200:203], v[4:7]
	v_mfma_f32_16x16x32_bf16 v[0:3], v[156:159], v[200:203], v[0:3]
	s_setprio 0
	s_barrier
	s_add_i32 s55, s55, 2
	s_add_u32 s6, s6, 0x100
	s_addc_u32 s7, s7, 0
	s_cmpk_gt_u32 s55, 0x55
	s_mov_b64 s[22:23], s[24:25]
	s_cbranch_scc0 .LBB0_2053
	s_and_b64 vcc, exec, s[16:17]
	s_cbranch_vccz .LBB0_2056
	s_barrier
